# speedup vs baseline: 1.0100x; 1.0100x over previous
; template <int WM, int WN> ...
;   static_assert(WM == 4 && WN == 4, "128x128 block tile");
;   constexpr int APAN = 128 * 64 + PPAD, BPAN = 128 * 64 + PPAD;
;   bf16x8 fa0[4], fb0[4], fa1[4], fb1[4];
; #pragma unroll
;   for (int n = 0; n < 4; ++n) fb0[n] = LDSF(cur + boff + n * 1024);
; #pragma unroll
;   for (int m = 0; m < 4; ++m) fa0[m] = LDSF(cur + aoff + m * 1024);
;   acc[3][0] = MFMA16(pa, pb0, acc[3][0]);
;   acc[3][1] = MFMA16(pa, pb1, acc[3][1]);
;   acc[3][2] = MFMA16(pa, pb2, acc[3][2]);
;   acc[3][3] = MFMA16(pa, pb3, acc[3][3]);
; #pragma unroll
;   for (int n = 0; n < 4; ++n) acc[0][n] = MFMA16(fa0[0], fb0[n], acc[0][n]);
; #pragma unroll
;   for (int m = 0; m < 4; ++m) fa1[m] = LDSF(cur + aoff + APAN + m * 1024);
; #pragma unroll
;   for (int n = 0; n < 4; ++n) acc[1][n] = MFMA16(fa0[1], fb0[n], acc[1][n]);
; #pragma unroll
;   for (int n = 0; n < 4; ++n) fb1[n] = LDSF(cur + boff + BPAN + n * 1024);
; #pragma unroll
;   for (int n = 0; n < 4; ++n) acc[2][n] = MFMA16(fa0[2], fb0[n], acc[2][n]);
;   *reinterpret_cast<uint4*>(nxt + wao) = a0;
;   *reinterpret_cast<uint4*>(nxt + wao + 32 * 64) = a1;
; #pragma unroll
;   for (int n = 0; n < 4; ++n) acc[3][n] = MFMA16(fa0[3], fb0[n], acc[3][n]);
;   *reinterpret_cast<uint4*>(nxt + wao + 64 * 64) = a2;
;   *reinterpret_cast<uint4*>(nxt + wao + 96 * 64) = a3;
; #pragma unroll
;   for (int n = 0; n < 4; ++n) acc[0][n] = MFMA16(fa1[0], fb1[n], acc[0][n]);
;   *reinterpret_cast<uint4*>(nxt + wbo) = b0;
; template <int WM, int WN, typename SrcF, typename PostF>
; __device__ __forceinline__ void gemm_stream(const int nsteps, SrcF src, PostF post, f32x4 (&acc)[WM][WN], char* smem) {
;     ...
;   for (int kt = 0; kt < nsteps; kt += 2) {
;     {
;       TileSrc s = src(min(kt + 2, nsteps - 1));
;       GLOAD_TILE(xa, s.a, s.lda, ACH);
;       GLOAD_TILE(xb, s.b, s.ldb, BCH);
;     }
;     step_compute<WM, WN>(smem, smem + STAGE, acc, aoff, boff, wao, wbo, ya0, ya1, ya2, ya3, yb0, yb1, yb2, yb3, pa, pb0, pb1, pb2, pb3);
;     SB_;
;     post(kt);
;     __syncthreads();
;     {
;       TileSrc s = src(min(kt + 3, nsteps - 1));
;       GLOAD_TILE(ya, s.a, s.lda, ACH);
;       GLOAD_TILE(yb, s.b, s.ldb, BCH);
;     }
;     step_compute<WM, WN>(smem + STAGE, smem, acc, aoff, boff, wao, wbo, xa0, xa1, xa2, xa3, xb0, xb1, xb2, xb3, pa, pb0, pb1, pb2, pb3);
;     SB_;
;     post(kt + 1);
;     __syncthreads();
;   }
.LBB0_104:
	s_add_i32 s11, s6, 2
	s_add_i32 s6, s6, 4
	s_min_u32 s6, s6, 15
	s_lshl_b32 s6, s6, 7
	s_add_u32 s92, s14, s6
	s_addc_u32 s93, s15, 0
	s_add_u32 s94, s20, s6
	s_addc_u32 s95, s21, 0
	ds_read_b128 v[148:151], v119
	ds_read_b128 v[132:135], v130 offset:16512
	ds_read_b128 v[136:139], v130 offset:17536
	ds_read_b128 v[140:143], v130 offset:18560
	ds_read_b128 v[144:147], v130 offset:19584
	v_mfma_f32_16x16x32_bf16 v[84:87], v[80:83], v[84:87], v[100:103]
	v_mfma_f32_16x16x32_bf16 v[96:99], v[80:83], v[104:107], v[96:99]
	s_waitcnt vmcnt(7)
	ds_write_b128 v131, v[76:79] offset:33024
	global_load_dwordx4 v[76:79], v116, s[92:93]
	s_add_u32 s52, s14, s6
	s_addc_u32 s53, s15, 0
	v_mfma_f32_16x16x32_bf16 v[92:95], v[80:83], v[108:111], v[92:95]
	v_mfma_f32_16x16x32_bf16 v[80:83], v[80:83], v[112:115], v[88:91]
	s_waitcnt lgkmcnt(4)
	v_mfma_f32_16x16x32_bf16 v[44:47], v[148:151], v[132:135], v[44:47]
	s_nop 0
	ds_read_b128 v[88:91], v119 offset:1024
	s_waitcnt lgkmcnt(4)
	v_mfma_f32_16x16x32_bf16 v[40:43], v[148:151], v[136:139], v[40:43]
	s_waitcnt vmcnt(7)
	ds_write_b128 v131, v[68:71] offset:35072
	global_load_dwordx4 v[68:71], v120, s[92:93]
	ds_read_b128 v[100:103], v119 offset:2048
	s_waitcnt lgkmcnt(5)
	v_mfma_f32_16x16x32_bf16 v[36:39], v[148:151], v[140:143], v[36:39]
	ds_read_b128 v[104:107], v119 offset:3072
	s_waitcnt lgkmcnt(5)
	v_mfma_f32_16x16x32_bf16 v[32:35], v[148:151], v[144:147], v[32:35]
	ds_read_b128 v[108:111], v119 offset:8256
	s_waitcnt lgkmcnt(4)
	v_mfma_f32_16x16x32_bf16 v[28:31], v[88:91], v[132:135], v[28:31]
	ds_read_b128 v[112:115], v119 offset:9280
	v_mfma_f32_16x16x32_bf16 v[24:27], v[88:91], v[136:139], v[24:27]
	ds_read_b128 v[148:151], v119 offset:10304
	v_mfma_f32_16x16x32_bf16 v[20:23], v[88:91], v[140:143], v[20:23]
	s_waitcnt vmcnt(7)
	ds_write_b128 v131, v[64:67] offset:37120
	global_load_dwordx4 v[64:67], v122, s[92:93]
	ds_read_b128 v[152:155], v119 offset:11328
	v_mfma_f32_16x16x32_bf16 v[16:19], v[88:91], v[144:147], v[16:19]
	ds_read_b128 v[88:91], v130 offset:24768
	s_waitcnt lgkmcnt(7)
	v_mfma_f32_16x16x32_bf16 v[12:15], v[100:103], v[132:135], v[12:15]
	ds_read_b128 v[156:159], v130 offset:25792
	v_mfma_f32_16x16x32_bf16 v[8:11], v[100:103], v[136:139], v[8:11]
	ds_read_b128 v[160:163], v130 offset:26816
	v_mfma_f32_16x16x32_bf16 v[4:7], v[100:103], v[140:143], v[4:7]
	s_waitcnt vmcnt(7)
	ds_write_b128 v131, v[72:75] offset:39168
	global_load_dwordx4 v[72:75], v124, s[92:93]
	ds_read_b128 v[164:167], v130 offset:27840
	v_mfma_f32_16x16x32_bf16 v[0:3], v[100:103], v[144:147], v[0:3]
	s_waitcnt lgkmcnt(10)
	v_mfma_f32_16x16x32_bf16 v[84:87], v[104:107], v[132:135], v[84:87]
	v_mfma_f32_16x16x32_bf16 v[96:99], v[104:107], v[136:139], v[96:99]
	v_mfma_f32_16x16x32_bf16 v[92:95], v[104:107], v[140:143], v[92:95]
	v_mfma_f32_16x16x32_bf16 v[80:83], v[104:107], v[144:147], v[80:83]
	s_waitcnt vmcnt(7)
	ds_write_b128 v131, v[60:63] offset:49536
	global_load_dwordx4 v[60:63], v116, s[94:95]
	s_waitcnt lgkmcnt(5)
	v_mfma_f32_16x16x32_bf16 v[44:47], v[108:111], v[88:91], v[44:47]
	s_add_u32 s52, s20, s6
	s_addc_u32 s53, s21, 0
	s_waitcnt lgkmcnt(4)
	v_mfma_f32_16x16x32_bf16 v[40:43], v[108:111], v[156:159], v[40:43]
	s_min_u32 s6, s11, 12
	s_lshl_b32 s6, s6, 7
	s_waitcnt lgkmcnt(3)
	v_mfma_f32_16x16x32_bf16 v[36:39], v[108:111], v[160:163], v[36:39]
	s_waitcnt lgkmcnt(1)
	v_mfma_f32_16x16x32_bf16 v[32:35], v[108:111], v[164:167], v[32:35]
	s_waitcnt vmcnt(7)
	ds_write_b128 v131, v[56:59] offset:51584
	global_load_dwordx4 v[56:59], v120, s[94:95]
	v_mfma_f32_16x16x32_bf16 v[28:31], v[112:115], v[88:91], v[28:31]
	v_mfma_f32_16x16x32_bf16 v[24:27], v[112:115], v[156:159], v[24:27]
	v_mfma_f32_16x16x32_bf16 v[20:23], v[112:115], v[160:163], v[20:23]
	v_mfma_f32_16x16x32_bf16 v[16:19], v[112:115], v[164:167], v[16:19]
	v_mfma_f32_16x16x32_bf16 v[12:15], v[148:151], v[88:91], v[12:15]
	s_waitcnt vmcnt(7)
	ds_write_b128 v131, v[52:55] offset:53632
	global_load_dwordx4 v[52:55], v122, s[94:95]
	v_mfma_f32_16x16x32_bf16 v[8:11], v[148:151], v[156:159], v[8:11]
	s_add_u32 s52, s14, s6
	s_addc_u32 s53, s15, 0
	s_add_u32 s54, s20, s6
	v_mfma_f32_16x16x32_bf16 v[4:7], v[148:151], v[160:163], v[4:7]
	s_addc_u32 s55, s21, 0
	v_mfma_f32_16x16x32_bf16 v[0:3], v[148:151], v[164:167], v[0:3]
	v_mfma_f32_16x16x32_bf16 v[88:91], v[152:155], v[88:91], v[84:87]
	s_waitcnt vmcnt(7)
	ds_write_b128 v131, v[48:51] offset:55680
	global_load_dwordx4 v[48:51], v124, s[94:95]
	v_mfma_f32_16x16x32_bf16 v[96:99], v[152:155], v[156:159], v[96:99]
	v_mfma_f32_16x16x32_bf16 v[92:95], v[152:155], v[160:163], v[92:95]
	v_mfma_f32_16x16x32_bf16 v[132:135], v[152:155], v[164:167], v[80:83]
	s_waitcnt lgkmcnt(0)
	s_barrier
; template <int WM, int WN> ...
;   static_assert(WM == 4 && WN == 4, "128x128 block tile");
;   constexpr int APAN = 128 * 64 + PPAD, BPAN = 128 * 64 + PPAD;
;   bf16x8 fa0[4], fb0[4], fa1[4], fb1[4];
; #pragma unroll
;   for (int n = 0; n < 4; ++n) fb0[n] = LDSF(cur + boff + n * 1024);
; #pragma unroll
;   for (int m = 0; m < 4; ++m) fa0[m] = LDSF(cur + aoff + m * 1024);
;   acc[3][0] = MFMA16(pa, pb0, acc[3][0]);
;   acc[3][1] = MFMA16(pa, pb1, acc[3][1]);
;   acc[3][2] = MFMA16(pa, pb2, acc[3][2]);
;   acc[3][3] = MFMA16(pa, pb3, acc[3][3]);
; #pragma unroll
;   for (int n = 0; n < 4; ++n) acc[0][n] = MFMA16(fa0[0], fb0[n], acc[0][n]);
; #pragma unroll
;   for (int m = 0; m < 4; ++m) fa1[m] = LDSF(cur + aoff + APAN + m * 1024);
; #pragma unroll
;   for (int n = 0; n < 4; ++n) acc[1][n] = MFMA16(fa0[1], fb0[n], acc[1][n]);
; #pragma unroll
;   for (int n = 0; n < 4; ++n) fb1[n] = LDSF(cur + boff + BPAN + n * 1024);
; #pragma unroll
;   for (int n = 0; n < 4; ++n) acc[2][n] = MFMA16(fa0[2], fb0[n], acc[2][n]);
;   *reinterpret_cast<uint4*>(nxt + wao) = a0;
;   *reinterpret_cast<uint4*>(nxt + wao + 32 * 64) = a1;
; #pragma unroll
;   for (int n = 0; n < 4; ++n) acc[3][n] = MFMA16(fa0[3], fb0[n], acc[3][n]);
;   *reinterpret_cast<uint4*>(nxt + wao + 64 * 64) = a2;
;   *reinterpret_cast<uint4*>(nxt + wao + 96 * 64) = a3;
; #pragma unroll
;   for (int n = 0; n < 4; ++n) acc[0][n] = MFMA16(fa1[0], fb1[n], acc[0][n]);
;   *reinterpret_cast<uint4*>(nxt + wbo) = b0;
; template <int WM, int WN, typename SrcF, typename PostF>
; __device__ __forceinline__ void gemm_stream(const int nsteps, SrcF src, PostF post, f32x4 (&acc)[WM][WN], char* smem) {
;     ...
;   for (int kt = 0; kt < nsteps; kt += 2) {
;     {
;       TileSrc s = src(min(kt + 2, nsteps - 1));
;       GLOAD_TILE(xa, s.a, s.lda, ACH);
;       GLOAD_TILE(xb, s.b, s.ldb, BCH);
;     }
;     step_compute<WM, WN>(smem, smem + STAGE, acc, aoff, boff, wao, wbo, ya0, ya1, ya2, ya3, yb0, yb1, yb2, yb3, pa, pb0, pb1, pb2, pb3);
;     SB_;
;     post(kt);
;     __syncthreads();
;     {
;       TileSrc s = src(min(kt + 3, nsteps - 1));
;       GLOAD_TILE(ya, s.a, s.lda, ACH);
;       GLOAD_TILE(yb, s.b, s.ldb, BCH);
;     }
;     step_compute<WM, WN>(smem + STAGE, smem, acc, aoff, boff, wao, wbo, xa0, xa1, xa2, xa3, xb0, xb1, xb2, xb3, pa, pb0, pb1, pb2, pb3);
;     SB_;
;     post(kt + 1);
;     __syncthreads();
;   }
	s_nop 0
	ds_read_b128 v[80:83], v119 offset:33024
	ds_read_b128 v[100:103], v130 offset:49536
	ds_read_b128 v[112:115], v130 offset:50560
	ds_read_b128 v[136:139], v130 offset:51584
	ds_read_b128 v[140:143], v130 offset:52608
	s_waitcnt lgkmcnt(3)
	v_mfma_f32_16x16x32_bf16 v[44:47], v[80:83], v[100:103], v[44:47]
	s_waitcnt lgkmcnt(2)
	v_mfma_f32_16x16x32_bf16 v[40:43], v[80:83], v[112:115], v[40:43]
	s_waitcnt vmcnt(7)
	ds_write_b128 v131, v[76:79]
	global_load_dwordx4 v[76:79], v116, s[52:53] offset:384
	s_waitcnt lgkmcnt(2)
	v_mfma_f32_16x16x32_bf16 v[36:39], v[80:83], v[136:139], v[36:39]
	s_waitcnt lgkmcnt(0)
	v_mfma_f32_16x16x32_bf16 v[32:35], v[80:83], v[140:143], v[32:35]
	ds_read_b128 v[80:83], v119 offset:34048
	s_waitcnt lgkmcnt(0)
	v_mfma_f32_16x16x32_bf16 v[28:31], v[80:83], v[100:103], v[28:31]
	s_waitcnt vmcnt(7)
	ds_write_b128 v131, v[68:71] offset:2048
	global_load_dwordx4 v[68:71], v120, s[52:53] offset:384
	ds_read_b128 v[104:107], v119 offset:35072
	v_mfma_f32_16x16x32_bf16 v[24:27], v[80:83], v[112:115], v[24:27]
	ds_read_b128 v[144:147], v119 offset:36096
	v_mfma_f32_16x16x32_bf16 v[20:23], v[80:83], v[136:139], v[20:23]
	ds_read_b128 v[148:151], v119 offset:41280
	v_mfma_f32_16x16x32_bf16 v[16:19], v[80:83], v[140:143], v[16:19]
	ds_read_b128 v[152:155], v119 offset:42304
	s_waitcnt lgkmcnt(3)
	v_mfma_f32_16x16x32_bf16 v[12:15], v[104:107], v[100:103], v[12:15]
	s_waitcnt vmcnt(7)
	ds_write_b128 v131, v[64:67] offset:4096
	global_load_dwordx4 v[64:67], v122, s[52:53] offset:384
	ds_read_b128 v[156:159], v119 offset:43328
	v_mfma_f32_16x16x32_bf16 v[8:11], v[104:107], v[112:115], v[8:11]
	ds_read_b128 v[80:83], v119 offset:44352
	v_mfma_f32_16x16x32_bf16 v[4:7], v[104:107], v[136:139], v[4:7]
	ds_read_b128 v[84:87], v130 offset:57792
	v_mfma_f32_16x16x32_bf16 v[0:3], v[104:107], v[140:143], v[0:3]
	s_waitcnt vmcnt(7)
	ds_write_b128 v131, v[72:75] offset:6144
	global_load_dwordx4 v[72:75], v124, s[52:53] offset:384
	ds_read_b128 v[104:107], v130 offset:58816
	s_waitcnt lgkmcnt(8)
	v_mfma_f32_16x16x32_bf16 v[100:103], v[144:147], v[100:103], v[88:91]
	ds_read_b128 v[108:111], v130 offset:59840
	v_mfma_f32_16x16x32_bf16 v[96:99], v[144:147], v[112:115], v[96:99]
	ds_read_b128 v[112:115], v130 offset:60864
	v_mfma_f32_16x16x32_bf16 v[92:95], v[144:147], v[136:139], v[92:95]
	v_mfma_f32_16x16x32_bf16 v[88:91], v[144:147], v[140:143], v[132:135]
	s_waitcnt vmcnt(7)
	ds_write_b128 v131, v[60:63] offset:16512
	global_load_dwordx4 v[60:63], v116, s[54:55] offset:384
	s_waitcnt lgkmcnt(5)
	v_mfma_f32_16x16x32_bf16 v[44:47], v[148:151], v[84:87], v[44:47]
	s_waitcnt lgkmcnt(3)
	v_mfma_f32_16x16x32_bf16 v[40:43], v[148:151], v[104:107], v[40:43]
	s_waitcnt lgkmcnt(2)
	v_mfma_f32_16x16x32_bf16 v[36:39], v[148:151], v[108:111], v[36:39]
	s_waitcnt vmcnt(7)
	ds_write_b128 v131, v[56:59] offset:18560
	global_load_dwordx4 v[56:59], v120, s[54:55] offset:384
	s_waitcnt lgkmcnt(2)
	v_mfma_f32_16x16x32_bf16 v[32:35], v[148:151], v[112:115], v[32:35]
	v_mfma_f32_16x16x32_bf16 v[28:31], v[152:155], v[84:87], v[28:31]
	v_mfma_f32_16x16x32_bf16 v[24:27], v[152:155], v[104:107], v[24:27]
	v_mfma_f32_16x16x32_bf16 v[20:23], v[152:155], v[108:111], v[20:23]
	s_waitcnt vmcnt(7)
	ds_write_b128 v131, v[52:55] offset:20608
	global_load_dwordx4 v[52:55], v122, s[54:55] offset:384
	v_mfma_f32_16x16x32_bf16 v[16:19], v[152:155], v[112:115], v[16:19]
	v_mfma_f32_16x16x32_bf16 v[12:15], v[156:159], v[84:87], v[12:15]
	v_mfma_f32_16x16x32_bf16 v[8:11], v[156:159], v[104:107], v[8:11]
	s_waitcnt vmcnt(7)
	ds_write_b128 v131, v[48:51] offset:22656
	global_load_dwordx4 v[48:51], v124, s[54:55] offset:384
	v_mfma_f32_16x16x32_bf16 v[4:7], v[156:159], v[108:111], v[4:7]
	v_mfma_f32_16x16x32_bf16 v[0:3], v[156:159], v[112:115], v[0:3]
	s_cmp_lt_u32 s11, 12
	s_mov_b32 s6, s11
	s_waitcnt lgkmcnt(0)
	s_barrier
	s_cbranch_scc1 .LBB0_104
	ds_read_b128 v[148:151], v119
	ds_read_b128 v[132:135], v130 offset:16512
	ds_read_b128 v[136:139], v130 offset:17536
	ds_read_b128 v[140:143], v130 offset:18560
	ds_read_b128 v[144:147], v130 offset:19584
	v_mfma_f32_16x16x32_bf16 v[84:87], v[80:83], v[84:87], v[100:103]
	s_add_i32 s11, s6, 2
	s_add_i32 s6, s6, 4
	s_min_u32 s6, s6, 15
	v_mfma_f32_16x16x32_bf16 v[96:99], v[80:83], v[104:107], v[96:99]
	s_lshl_b32 s6, s6, 7
	s_add_u32 s52, s14, s6
	s_addc_u32 s53, s15, 0
	v_mfma_f32_16x16x32_bf16 v[92:95], v[80:83], v[108:111], v[92:95]
	v_mfma_f32_16x16x32_bf16 v[80:83], v[80:83], v[112:115], v[88:91]
	s_waitcnt lgkmcnt(3)
	v_mfma_f32_16x16x32_bf16 v[44:47], v[148:151], v[132:135], v[44:47]
	s_nop 0
	ds_read_b128 v[88:91], v119 offset:1024
	s_waitcnt lgkmcnt(3)
	v_mfma_f32_16x16x32_bf16 v[40:43], v[148:151], v[136:139], v[40:43]
	ds_read_b128 v[100:103], v119 offset:2048
	s_waitcnt lgkmcnt(3)
	v_mfma_f32_16x16x32_bf16 v[36:39], v[148:151], v[140:143], v[36:39]
	ds_read_b128 v[104:107], v119 offset:3072
	s_waitcnt lgkmcnt(3)
	v_mfma_f32_16x16x32_bf16 v[32:35], v[148:151], v[144:147], v[32:35]
	ds_read_b128 v[108:111], v119 offset:8256
	s_waitcnt lgkmcnt(3)
	v_mfma_f32_16x16x32_bf16 v[28:31], v[88:91], v[132:135], v[28:31]
	ds_read_b128 v[112:115], v119 offset:9280
	v_mfma_f32_16x16x32_bf16 v[24:27], v[88:91], v[136:139], v[24:27]
	ds_read_b128 v[148:151], v119 offset:10304
	v_mfma_f32_16x16x32_bf16 v[20:23], v[88:91], v[140:143], v[20:23]
	ds_read_b128 v[152:155], v119 offset:11328
	v_mfma_f32_16x16x32_bf16 v[16:19], v[88:91], v[144:147], v[16:19]
	ds_read_b128 v[88:91], v130 offset:24768
	s_waitcnt lgkmcnt(6)
; #define MFMA16(a, b, c) __builtin_amdgcn_mfma_f32_16x16x32_bf16(a, b, c, 0, 0, 0)
; #define SGB_(mask_, n_) __builtin_amdgcn_sched_group_barrier(mask_, n_, 0)
; template <int WM, int WN> ...
;   static_assert(WM == 4 && WN == 4, "128x128 block tile");
;   constexpr int APAN = 128 * 64 + PPAD, BPAN = 128 * 64 + PPAD;
;   bf16x8 fa0[4], fb0[4], fa1[4], fb1[4];
; #pragma unroll
;   for (int n = 0; n < 4; ++n) fb0[n] = LDSF(cur + boff + n * 1024);
; #pragma unroll
;   for (int m = 0; m < 4; ++m) fa0[m] = LDSF(cur + aoff + m * 1024);
;   acc[3][0] = MFMA16(pa, pb0, acc[3][0]);
;   acc[3][1] = MFMA16(pa, pb1, acc[3][1]);
;   acc[3][2] = MFMA16(pa, pb2, acc[3][2]);
;   acc[3][3] = MFMA16(pa, pb3, acc[3][3]);
; #pragma unroll
;   for (int n = 0; n < 4; ++n) acc[0][n] = MFMA16(fa0[0], fb0[n], acc[0][n]);
; #pragma unroll
;   for (int m = 0; m < 4; ++m) fa1[m] = LDSF(cur + aoff + APAN + m * 1024);
; #pragma unroll
;   for (int n = 0; n < 4; ++n) acc[1][n] = MFMA16(fa0[1], fb0[n], acc[1][n]);
; #pragma unroll
;   for (int n = 0; n < 4; ++n) fb1[n] = LDSF(cur + boff + BPAN + n * 1024);
; #pragma unroll
;   for (int n = 0; n < 4; ++n) acc[2][n] = MFMA16(fa0[2], fb0[n], acc[2][n]);
;   *reinterpret_cast<uint4*>(nxt + wao) = a0;
;   *reinterpret_cast<uint4*>(nxt + wao + 32 * 64) = a1;
; #pragma unroll
;   for (int n = 0; n < 4; ++n) acc[3][n] = MFMA16(fa0[3], fb0[n], acc[3][n]);
;   *reinterpret_cast<uint4*>(nxt + wao + 64 * 64) = a2;
;   *reinterpret_cast<uint4*>(nxt + wao + 96 * 64) = a3;
; #pragma unroll
;   for (int n = 0; n < 4; ++n) acc[0][n] = MFMA16(fa1[0], fb1[n], acc[0][n]);
;   *reinterpret_cast<uint4*>(nxt + wbo) = b0;
;   *reinterpret_cast<uint4*>(nxt + wbo + 32 * 64) = b1;
; #pragma unroll
;   for (int n = 0; n < 4; ++n) acc[1][n] = MFMA16(fa1[1], fb1[n], acc[1][n]);
;   *reinterpret_cast<uint4*>(nxt + wbo + 64 * 64) = b2;
;   *reinterpret_cast<uint4*>(nxt + wbo + 96 * 64) = b3;
; #pragma unroll
;   for (int n = 0; n < 4; ++n) acc[2][n] = MFMA16(fa1[2], fb1[n], acc[2][n]);
;   pa = fa1[3];
;   pb0 = fb1[0]; pb1 = fb1[1]; pb2 = fb1[2]; pb3 = fb1[3];
;   SGB_(0x100, 5);
;   SGB_(0x008, 4);
; #pragma unroll
;   for (int i_ = 0; i_ < 11; ++i_) { SGB_(0x008, 1); SGB_(0x100, 1); }
; #pragma unroll
;   for (int i_ = 0; i_ < 8; ++i_) { SGB_(0x008, 2); SGB_(0x200, 1); SGB_(0x020, 1); }
;   SGB_(0x008, 1);
; }
	v_mfma_f32_16x16x32_bf16 v[12:15], v[100:103], v[132:135], v[12:15]
	ds_read_b128 v[156:159], v130 offset:25792
	v_mfma_f32_16x16x32_bf16 v[8:11], v[100:103], v[136:139], v[8:11]
	ds_read_b128 v[160:163], v130 offset:26816
	v_mfma_f32_16x16x32_bf16 v[4:7], v[100:103], v[140:143], v[4:7]
	ds_read_b128 v[164:167], v130 offset:27840
	v_mfma_f32_16x16x32_bf16 v[0:3], v[100:103], v[144:147], v[0:3]
	s_waitcnt lgkmcnt(8)
	v_mfma_f32_16x16x32_bf16 v[84:87], v[104:107], v[132:135], v[84:87]
	s_waitcnt vmcnt(7)
	ds_write_b128 v131, v[76:79] offset:33024
	v_mfma_f32_16x16x32_bf16 v[96:99], v[104:107], v[136:139], v[96:99]
	v_mfma_f32_16x16x32_bf16 v[92:95], v[104:107], v[140:143], v[92:95]
	s_waitcnt vmcnt(6)
	ds_write_b128 v131, v[68:71] offset:35072
	v_mfma_f32_16x16x32_bf16 v[80:83], v[104:107], v[144:147], v[80:83]
	s_waitcnt lgkmcnt(5)
	v_mfma_f32_16x16x32_bf16 v[44:47], v[108:111], v[88:91], v[44:47]
	s_waitcnt vmcnt(5)
	ds_write_b128 v131, v[64:67] offset:37120
	s_add_u32 s52, s20, s6
	s_addc_u32 s53, s21, 0
	s_waitcnt lgkmcnt(5)
	v_mfma_f32_16x16x32_bf16 v[40:43], v[108:111], v[156:159], v[40:43]
	s_min_u32 s6, s11, 12
	s_lshl_b32 s6, s6, 7
	s_waitcnt lgkmcnt(4)
	v_mfma_f32_16x16x32_bf16 v[36:39], v[108:111], v[160:163], v[36:39]
	s_waitcnt vmcnt(4)
	ds_write_b128 v131, v[72:75] offset:39168
	s_waitcnt lgkmcnt(4)
	v_mfma_f32_16x16x32_bf16 v[32:35], v[108:111], v[164:167], v[32:35]
	v_mfma_f32_16x16x32_bf16 v[28:31], v[112:115], v[88:91], v[28:31]
	s_waitcnt vmcnt(3)
	ds_write_b128 v131, v[60:63] offset:49536
	v_mfma_f32_16x16x32_bf16 v[24:27], v[112:115], v[156:159], v[24:27]
	v_mfma_f32_16x16x32_bf16 v[20:23], v[112:115], v[160:163], v[20:23]
	s_waitcnt vmcnt(2)
	ds_write_b128 v131, v[56:59] offset:51584
	v_mfma_f32_16x16x32_bf16 v[16:19], v[112:115], v[164:167], v[16:19]
	v_mfma_f32_16x16x32_bf16 v[12:15], v[148:151], v[88:91], v[12:15]
	s_waitcnt vmcnt(1)
	ds_write_b128 v131, v[52:55] offset:53632
	v_mfma_f32_16x16x32_bf16 v[8:11], v[148:151], v[156:159], v[8:11]
	s_add_u32 s52, s14, s6
	s_addc_u32 s53, s15, 0
	s_add_u32 s54, s20, s6
	v_mfma_f32_16x16x32_bf16 v[4:7], v[148:151], v[160:163], v[4:7]
	s_waitcnt vmcnt(0)
	ds_write_b128 v131, v[48:51] offset:55680
	s_addc_u32 s55, s21, 0
	v_mfma_f32_16x16x32_bf16 v[0:3], v[148:151], v[164:167], v[0:3]
	v_mfma_f32_16x16x32_bf16 v[88:91], v[152:155], v[88:91], v[84:87]
	v_mfma_f32_16x16x32_bf16 v[96:99], v[152:155], v[156:159], v[96:99]
	v_mfma_f32_16x16x32_bf16 v[92:95], v[152:155], v[160:163], v[92:95]
	v_mfma_f32_16x16x32_bf16 v[132:135], v[152:155], v[164:167], v[80:83]
	s_waitcnt lgkmcnt(0)
	s_barrier
	s_nop 0
	ds_read_b128 v[80:83], v119 offset:33024
	ds_read_b128 v[100:103], v130 offset:49536
	ds_read_b128 v[112:115], v130 offset:50560
	ds_read_b128 v[136:139], v130 offset:51584
	ds_read_b128 v[140:143], v130 offset:52608
	s_waitcnt lgkmcnt(3)
	v_mfma_f32_16x16x32_bf16 v[44:47], v[80:83], v[100:103], v[44:47]
	s_waitcnt lgkmcnt(2)
	v_mfma_f32_16x16x32_bf16 v[40:43], v[80:83], v[112:115], v[40:43]
	s_waitcnt lgkmcnt(1)
	v_mfma_f32_16x16x32_bf16 v[36:39], v[80:83], v[136:139], v[36:39]
	s_waitcnt lgkmcnt(0)
	v_mfma_f32_16x16x32_bf16 v[32:35], v[80:83], v[140:143], v[32:35]
	ds_read_b128 v[80:83], v119 offset:34048
	s_waitcnt lgkmcnt(0)
	v_mfma_f32_16x16x32_bf16 v[28:31], v[80:83], v[100:103], v[28:31]
	ds_read_b128 v[104:107], v119 offset:35072
	v_mfma_f32_16x16x32_bf16 v[24:27], v[80:83], v[112:115], v[24:27]
	ds_read_b128 v[144:147], v119 offset:36096
	v_mfma_f32_16x16x32_bf16 v[20:23], v[80:83], v[136:139], v[20:23]
	ds_read_b128 v[148:151], v119 offset:41280
	v_mfma_f32_16x16x32_bf16 v[16:19], v[80:83], v[140:143], v[16:19]
	ds_read_b128 v[152:155], v119 offset:42304
	s_waitcnt lgkmcnt(3)
	v_mfma_f32_16x16x32_bf16 v[12:15], v[104:107], v[100:103], v[12:15]
	ds_read_b128 v[156:159], v119 offset:43328
	v_mfma_f32_16x16x32_bf16 v[8:11], v[104:107], v[112:115], v[8:11]
	ds_read_b128 v[80:83], v119 offset:44352
	v_mfma_f32_16x16x32_bf16 v[4:7], v[104:107], v[136:139], v[4:7]
	ds_read_b128 v[84:87], v130 offset:57792
	v_mfma_f32_16x16x32_bf16 v[0:3], v[104:107], v[140:143], v[0:3]
	ds_read_b128 v[104:107], v130 offset:58816
	s_waitcnt lgkmcnt(6)
	v_mfma_f32_16x16x32_bf16 v[100:103], v[144:147], v[100:103], v[88:91]
	ds_read_b128 v[108:111], v130 offset:59840
	v_mfma_f32_16x16x32_bf16 v[96:99], v[144:147], v[112:115], v[96:99]
	ds_read_b128 v[112:115], v130 offset:60864
	v_mfma_f32_16x16x32_bf16 v[92:95], v[144:147], v[136:139], v[92:95]
	v_mfma_f32_16x16x32_bf16 v[88:91], v[144:147], v[140:143], v[132:135]
	s_waitcnt lgkmcnt(3)
	v_mfma_f32_16x16x32_bf16 v[44:47], v[148:151], v[84:87], v[44:47]
	s_waitcnt lgkmcnt(2)
	v_mfma_f32_16x16x32_bf16 v[40:43], v[148:151], v[104:107], v[40:43]
	s_waitcnt lgkmcnt(1)
	v_mfma_f32_16x16x32_bf16 v[36:39], v[148:151], v[108:111], v[36:39]
	s_waitcnt lgkmcnt(0)
	v_mfma_f32_16x16x32_bf16 v[32:35], v[148:151], v[112:115], v[32:35]
	v_mfma_f32_16x16x32_bf16 v[28:31], v[152:155], v[84:87], v[28:31]
	v_mfma_f32_16x16x32_bf16 v[24:27], v[152:155], v[104:107], v[24:27]
	v_mfma_f32_16x16x32_bf16 v[20:23], v[152:155], v[108:111], v[20:23]
	v_mfma_f32_16x16x32_bf16 v[16:19], v[152:155], v[112:115], v[16:19]
	v_mfma_f32_16x16x32_bf16 v[12:15], v[156:159], v[84:87], v[12:15]
	v_mfma_f32_16x16x32_bf16 v[8:11], v[156:159], v[104:107], v[8:11]
	v_mfma_f32_16x16x32_bf16 v[4:7], v[156:159], v[108:111], v[4:7]
	v_mfma_f32_16x16x32_bf16 v[0:3], v[156:159], v[112:115], v[0:3]
	s_cmp_lt_u32 s11, 14
	s_mov_b32 s6, s11
	s_waitcnt lgkmcnt(0)
	s_barrier
; #define MFMA16(a, b, c) __builtin_amdgcn_mfma_f32_16x16x32_bf16(a, b, c, 0, 0, 0)
; template <int WM, int WN, typename SrcF, typename PostF>
; __device__ __forceinline__ void gemm_stream(const int nsteps, SrcF src, PostF post, f32x4 (&acc)[WM][WN], char* smem) {
;     ...
;   acc[3][0] = MFMA16(pa, pb0, acc[3][0]);
;   acc[3][1] = MFMA16(pa, pb1, acc[3][1]);
;   acc[3][2] = MFMA16(pa, pb2, acc[3][2]);
;   acc[3][3] = MFMA16(pa, pb3, acc[3][3]);
; __device__ void phase_inproj(const Params& p, int layer, char* smem) {
;     ...
;     const int row0 = rb * 128 + wr * 64, col0 = cb * 128 + wc * 64;
;     if (cb >= 12 && cb <= 16) {
; #pragma unroll
;       for (int m = 0; m < 4; ++m)
; #pragma unroll
;         for (int j = 0; j < 4; ++j) {
;           int row = row0 + m * 16 + fq * 4 + j;
;           int pos = row & (SEQ - 1);
; #pragma unroll
;           for (int n = 0; n < 2; ++n) {
;             float2 cs2 = RT[pos * 32 + n * 16 + fr];
;             float c = cs2.x, s = cs2.y;
;             float x1 = acc[m][n][j], x2 = acc[m][n + 2][j];
;             acc[m][n][j] = x1 * c - x2 * s;
;             acc[m][n + 2][j] = x2 * c + x1 * s;
;           }
;         }
	s_waitcnt vmcnt(3)
	v_mfma_f32_16x16x32_bf16 v[60:63], v[80:83], v[84:87], v[100:103]
	s_add_i32 s6, s12, -12
	s_cmp_gt_u32 s6, 4
	s_waitcnt vmcnt(2)
	v_mfma_f32_16x16x32_bf16 v[56:59], v[80:83], v[104:107], v[96:99]
	s_waitcnt vmcnt(1)
	v_mfma_f32_16x16x32_bf16 v[52:55], v[80:83], v[108:111], v[92:95]
	s_waitcnt vmcnt(0)
	v_mfma_f32_16x16x32_bf16 v[48:51], v[80:83], v[112:115], v[88:91]
	s_cbranch_scc1 .LBB0_107
	v_lshl_add_u32 v64, s10, 7, v126
	v_and_or_b32 v64, v64, s40, v127
	v_lshl_or_b32 v116, v64, 8, v128
	v_lshl_add_u64 v[92:93], s[8:9], 0, v[116:117]
	v_add_co_u32_e32 v94, vcc, s44, v92
	global_load_dwordx2 v[68:69], v116, s[8:9]
	global_load_dwordx2 v[64:65], v116, s[8:9] offset:256
	global_load_dwordx2 v[66:67], v116, s[8:9] offset:384
	global_load_dwordx2 v[72:73], v116, s[8:9] offset:512
	global_load_dwordx2 v[76:77], v116, s[8:9] offset:128
	global_load_dwordx2 v[74:75], v116, s[8:9] offset:640
	global_load_dwordx2 v[70:71], v116, s[8:9] offset:768
	global_load_dwordx2 v[78:79], v116, s[8:9] offset:896
	v_addc_co_u32_e32 v95, vcc, 0, v93, vcc
	v_add_co_u32_e32 v96, vcc, s45, v92
	s_waitcnt vmcnt(7)
	v_mov_b32_e32 v124, v68
	v_addc_co_u32_e32 v97, vcc, 0, v93, vcc
	global_load_dwordx2 v[82:83], v[96:97], off offset:-4096
	global_load_dwordx2 v[80:81], v[94:95], off offset:256
	global_load_dwordx2 v[84:85], v[94:95], off offset:384
	global_load_dwordx2 v[88:89], v[94:95], off offset:512
	global_load_dwordx2 v[98:99], v[94:95], off offset:128
	global_load_dwordx2 v[90:91], v[94:95], off offset:640
	global_load_dwordx2 v[86:87], v[94:95], off offset:768
	s_waitcnt vmcnt(13)
	v_mov_b32_e32 v125, v64
	v_mov_b32_e32 v64, v69
	s_waitcnt vmcnt(10)
	v_mov_b32_e32 v68, v76
	v_mul_f32_e32 v76, v46, v72
	v_mul_f32_e32 v130, v38, v73
	v_mul_f32_e32 v72, v38, v72
	v_mul_f32_e32 v132, v46, v73
	s_waitcnt vmcnt(9)
	v_mul_f32_e32 v134, v42, v74
	v_mul_f32_e32 v138, v42, v75
	v_mov_b32_e32 v38, v47
	v_mov_b32_e32 v46, v39
	v_mov_b32_e32 v42, v35
	v_add_co_u32_e32 v92, vcc, s46, v92
	v_mov_b32_e32 v69, v66
	v_mov_b32_e32 v66, v77
	v_mul_f32_e32 v136, v34, v75
	v_mul_f32_e32 v74, v34, v74
	v_mov_b32_e32 v34, v43
	v_pk_mul_f32 v[140:141], v[44:45], v[64:65]
	v_pk_mul_f32 v[64:65], v[36:37], v[64:65]
	s_waitcnt vmcnt(8)
	v_pk_mul_f32 v[38:39], v[38:39], v[70:71]
	v_pk_mul_f32 v[46:47], v[46:47], v[70:71]
	s_waitcnt vmcnt(7)
	v_pk_mul_f32 v[42:43], v[42:43], v[78:79]
	v_addc_co_u32_e32 v93, vcc, 0, v93, vcc
	v_pk_mul_f32 v[142:143], v[40:41], v[66:67]
	v_pk_mul_f32 v[66:67], v[32:33], v[66:67]
	v_pk_mul_f32 v[34:35], v[34:35], v[78:79]
	v_mov_b32_e32 v77, v38
	v_mov_b32_e32 v131, v39
	v_pk_fma_f32 v[44:45], v[44:45], v[124:125], v[64:65] neg_lo:[0,0,1] neg_hi:[0,0,1]
	v_mov_b32_e32 v73, v46
	v_mov_b32_e32 v133, v47
	v_mov_b32_e32 v75, v42
	v_mov_b32_e32 v139, v43
	global_load_dwordx2 v[94:95], v[94:95], off offset:896
	s_nop 0
	global_load_dwordx2 v[100:101], v[96:97], off
	global_load_dwordx2 v[102:103], v[96:97], off offset:256
	global_load_dwordx2 v[104:105], v[96:97], off offset:384
	global_load_dwordx2 v[106:107], v[96:97], off offset:128
	global_load_dwordx2 v[108:109], v[96:97], off offset:512
	global_load_dwordx2 v[110:111], v[96:97], off offset:640
	global_load_dwordx2 v[112:113], v[96:97], off offset:768
	s_nop 0
	global_load_dwordx2 v[96:97], v[96:97], off offset:896
	s_nop 0
	global_load_dwordx2 v[114:115], v[92:93], off offset:640
	global_load_dwordx2 v[120:121], v[92:93], off offset:768
	global_load_dwordx2 v[122:123], v[92:93], off offset:896
	v_mov_b32_e32 v135, v34
	v_mov_b32_e32 v137, v35
	v_pk_fma_f32 v[40:41], v[40:41], v[68:69], v[66:67] neg_lo:[0,0,1] neg_hi:[0,0,1]
	v_pk_fma_f32 v[32:33], v[32:33], v[68:69], v[142:143]
	v_pk_add_f32 v[46:47], v[76:77], v[130:131] neg_lo:[0,1] neg_hi:[0,1]
	v_pk_add_f32 v[38:39], v[72:73], v[132:133]
	v_pk_add_f32 v[34:35], v[74:75], v[138:139]
	global_load_dwordx2 v[74:75], v[92:93], off
	global_load_dwordx2 v[76:77], v[92:93], off offset:256
	v_pk_fma_f32 v[36:37], v[36:37], v[124:125], v[140:141]
	v_pk_add_f32 v[42:43], v[134:135], v[136:137] neg_lo:[0,1] neg_hi:[0,1]
	s_waitcnt vmcnt(20)
	v_mov_b32_e32 v64, v82
	s_waitcnt vmcnt(19)
	v_mov_b32_e32 v65, v80
	v_mov_b32_e32 v80, v83
	s_waitcnt vmcnt(18)
	v_mov_b32_e32 v71, v84
	s_waitcnt vmcnt(16)
	v_mov_b32_e32 v84, v99
	v_pk_mul_f32 v[66:67], v[28:29], v[80:81]
	v_pk_mul_f32 v[68:69], v[20:21], v[80:81]
	v_pk_mul_f32 v[72:73], v[24:25], v[84:85]
	v_pk_mul_f32 v[78:79], v[16:17], v[84:85]
	global_load_dwordx2 v[80:81], v[92:93], off offset:384
	global_load_dwordx2 v[82:83], v[92:93], off offset:512
	global_load_dwordx2 v[84:85], v[92:93], off offset:128
	v_mov_b32_e32 v70, v98
	v_mul_f32_e32 v92, v30, v88
	v_mul_f32_e32 v98, v22, v89
	v_mul_f32_e32 v88, v22, v88
	v_mul_f32_e32 v124, v30, v89
	s_waitcnt vmcnt(18)
; __device__ void phase_inproj(const Params& p, int layer, char* smem) {
;     ...
;     if (cb >= 12 && cb <= 16) {
; #pragma unroll
;       for (int m = 0; m < 4; ++m)
; #pragma unroll
;         for (int j = 0; j < 4; ++j) {
;           int row = row0 + m * 16 + fq * 4 + j;
;           int pos = row & (SEQ - 1);
; #pragma unroll
;           for (int n = 0; n < 2; ++n) {
;             float2 cs2 = RT[pos * 32 + n * 16 + fr];
;             float c = cs2.x, s = cs2.y;
;             float x1 = acc[m][n][j], x2 = acc[m][n + 2][j];
;             acc[m][n][j] = x1 * c - x2 * s;
;             acc[m][n + 2][j] = x2 * c + x1 * s;
;           }
;         }
	v_mul_f32_e32 v130, v26, v90
	v_mul_f32_e32 v132, v18, v91
	v_mul_f32_e32 v90, v18, v90
	v_mul_f32_e32 v134, v26, v91
	v_mov_b32_e32 v22, v31
	v_mov_b32_e32 v30, v23
	v_mov_b32_e32 v18, v27
	v_mov_b32_e32 v26, v19
	s_waitcnt vmcnt(17)
	v_pk_mul_f32 v[136:137], v[22:23], v[86:87]
	v_pk_mul_f32 v[22:23], v[30:31], v[86:87]
	v_mov_b32_e32 v93, v136
	v_mov_b32_e32 v89, v22
	v_mov_b32_e32 v125, v23
	v_mov_b32_e32 v99, v137
	v_pk_add_f32 v[22:23], v[88:89], v[124:125]
	v_pk_fma_f32 v[24:25], v[24:25], v[70:71], v[78:79] neg_lo:[0,0,1] neg_hi:[0,0,1]
	v_pk_fma_f32 v[16:17], v[16:17], v[70:71], v[72:73]
	s_waitcnt vmcnt(16)
	v_pk_mul_f32 v[30:31], v[18:19], v[94:95]
	v_pk_mul_f32 v[18:19], v[26:27], v[94:95]
	s_waitcnt vmcnt(14)
	v_mov_b32_e32 v27, v102
	v_mov_b32_e32 v91, v18
	v_mov_b32_e32 v135, v19
	v_pk_add_f32 v[18:19], v[90:91], v[134:135]
	v_mov_b32_e32 v102, v101
	s_waitcnt vmcnt(13)
	v_mov_b32_e32 v71, v104
	s_waitcnt vmcnt(12)
	v_mov_b32_e32 v104, v107
	s_waitcnt vmcnt(11)
	v_mul_f32_e32 v88, v6, v109
	v_mul_f32_e32 v90, v6, v108
	v_mov_b32_e32 v6, v15
	v_pk_fma_f32 v[28:29], v[28:29], v[64:65], v[68:69] neg_lo:[0,0,1] neg_hi:[0,0,1]
	v_pk_add_f32 v[68:69], v[92:93], v[98:99] neg_lo:[0,1] neg_hi:[0,1]
	v_pk_fma_f32 v[20:21], v[20:21], v[64:65], v[66:67]
	v_mov_b32_e32 v26, v100
	v_pk_mul_f32 v[64:65], v[12:13], v[102:103]
	v_pk_mul_f32 v[66:67], v[4:5], v[102:103]
	v_mov_b32_e32 v70, v106
	v_pk_mul_f32 v[72:73], v[8:9], v[104:105]
	v_pk_mul_f32 v[78:79], v[0:1], v[104:105]
	v_mul_f32_e32 v86, v14, v108
	v_mul_f32_e32 v92, v14, v109
	s_waitcnt vmcnt(10)
	v_mul_f32_e32 v94, v10, v110
	v_mul_f32_e32 v98, v2, v111
	v_mul_f32_e32 v100, v2, v110
	v_mul_f32_e32 v102, v10, v111
	s_waitcnt vmcnt(9)
	v_pk_mul_f32 v[104:105], v[6:7], v[112:113]
	v_mov_b32_e32 v14, v7
	v_mov_b32_e32 v2, v11
	v_mov_b32_e32 v10, v3
	v_mov_b32_e32 v87, v104
	v_mov_b32_e32 v89, v105
	v_pk_mul_f32 v[6:7], v[14:15], v[112:113]
	s_waitcnt vmcnt(8)
	v_pk_mul_f32 v[14:15], v[2:3], v[96:97]
	v_pk_fma_f32 v[8:9], v[8:9], v[70:71], v[78:79] neg_lo:[0,0,1] neg_hi:[0,0,1]
	v_pk_mul_f32 v[2:3], v[10:11], v[96:97]
	v_pk_fma_f32 v[0:1], v[0:1], v[70:71], v[72:73]
	s_waitcnt vmcnt(3)
	v_mov_b32_e32 v11, v76
	v_mov_b32_e32 v76, v75
	v_pk_fma_f32 v[12:13], v[12:13], v[26:27], v[66:67] neg_lo:[0,0,1] neg_hi:[0,0,1]
	v_pk_add_f32 v[66:67], v[86:87], v[88:89] neg_lo:[0,1] neg_hi:[0,1]
	v_mov_b32_e32 v91, v6
	v_mov_b32_e32 v93, v7
	v_pk_fma_f32 v[4:5], v[4:5], v[26:27], v[64:65]
	v_mov_b32_e32 v10, v74
	v_pk_mul_f32 v[26:27], v[60:61], v[76:77]
	v_pk_mul_f32 v[64:65], v[52:53], v[76:77]
	v_mul_f32_e32 v86, v50, v115
	v_mul_f32_e32 v88, v50, v114
	v_mov_b32_e32 v50, v59
	v_pk_add_f32 v[6:7], v[90:91], v[92:93]
	v_mul_f32_e32 v90, v58, v115
	v_pk_fma_f32 v[60:61], v[60:61], v[10:11], v[64:65] neg_lo:[0,0,1] neg_hi:[0,0,1]
	v_pk_fma_f32 v[52:53], v[52:53], v[10:11], v[26:27]
	s_waitcnt vmcnt(2)
	v_mov_b32_e32 v71, v80
	s_waitcnt vmcnt(1)
	v_mul_f32_e32 v78, v54, v83
	s_waitcnt vmcnt(0)
	v_mov_b32_e32 v80, v85
	v_pk_mul_f32 v[72:73], v[56:57], v[80:81]
	v_pk_mul_f32 v[74:75], v[48:49], v[80:81]
	v_mul_f32_e32 v80, v54, v82
	v_mov_b32_e32 v54, v63
	v_mov_b32_e32 v70, v84
	v_mul_f32_e32 v76, v62, v82
	v_mul_f32_e32 v82, v62, v83
	v_mul_f32_e32 v84, v58, v114
	v_pk_mul_f32 v[92:93], v[54:55], v[120:121]
	v_mov_b32_e32 v62, v55
	v_pk_mul_f32 v[10:11], v[50:51], v[122:123]
	v_mov_b32_e32 v58, v51
	v_mov_b32_e32 v131, v30
	v_mov_b32_e32 v133, v31
	v_mov_b32_e32 v95, v14
	v_mov_b32_e32 v99, v15
	v_mov_b32_e32 v77, v92
	v_mov_b32_e32 v79, v93
	v_pk_mul_f32 v[54:55], v[62:63], v[120:121]
	v_mov_b32_e32 v85, v10
	v_mov_b32_e32 v87, v11
	v_pk_mul_f32 v[26:27], v[58:59], v[122:123]
	v_pk_add_f32 v[30:31], v[130:131], v[132:133] neg_lo:[0,1] neg_hi:[0,1]
	v_pk_add_f32 v[14:15], v[94:95], v[98:99] neg_lo:[0,1] neg_hi:[0,1]
	v_mov_b32_e32 v101, v2
	v_mov_b32_e32 v103, v3
	v_pk_add_f32 v[64:65], v[76:77], v[78:79] neg_lo:[0,1] neg_hi:[0,1]
	v_mov_b32_e32 v81, v54
	v_mov_b32_e32 v83, v55
	v_pk_add_f32 v[10:11], v[84:85], v[86:87] neg_lo:[0,1] neg_hi:[0,1]
	v_mov_b32_e32 v89, v26
	v_mov_b32_e32 v91, v27
	v_pk_add_f32 v[2:3], v[100:101], v[102:103]
	v_pk_add_f32 v[54:55], v[80:81], v[82:83]
	v_pk_fma_f32 v[56:57], v[56:57], v[70:71], v[74:75] neg_lo:[0,0,1] neg_hi:[0,0,1]
	v_pk_fma_f32 v[48:49], v[48:49], v[70:71], v[72:73]
	v_pk_add_f32 v[50:51], v[88:89], v[90:91]
	v_mov_b32_e32 v58, v10
	v_mov_b32_e32 v59, v11
	v_mov_b32_e32 v62, v64
	v_mov_b32_e32 v63, v65
	v_mov_b32_e32 v10, v14
	v_mov_b32_e32 v11, v15
	v_mov_b32_e32 v14, v66
	v_mov_b32_e32 v15, v67
	v_mov_b32_e32 v26, v30
	v_mov_b32_e32 v27, v31
	v_mov_b32_e32 v30, v68
	v_mov_b32_e32 v31, v69

; #define MFMA16(a, b, c) __builtin_amdgcn_mfma_f32_16x16x32_bf16(a, b, c, 0, 0, 0)
; #define SGB_(mask_, n_) __builtin_amdgcn_sched_group_barrier(mask_, n_, 0)
; template <int WM, int WN> ...
;   static_assert(WM == 4 && WN == 4, "128x128 block tile");
;   constexpr int APAN = 128 * 64 + PPAD, BPAN = 128 * 64 + PPAD;
;   bf16x8 fa0[4], fb0[4], fa1[4], fb1[4];
; #pragma unroll
;   for (int n = 0; n < 4; ++n) fb0[n] = LDSF(cur + boff + n * 1024);
; #pragma unroll
;   for (int m = 0; m < 4; ++m) fa0[m] = LDSF(cur + aoff + m * 1024);
;   acc[3][0] = MFMA16(pa, pb0, acc[3][0]);
;   acc[3][1] = MFMA16(pa, pb1, acc[3][1]);
;   acc[3][2] = MFMA16(pa, pb2, acc[3][2]);
;   acc[3][3] = MFMA16(pa, pb3, acc[3][3]);
; #pragma unroll
;   for (int n = 0; n < 4; ++n) acc[0][n] = MFMA16(fa0[0], fb0[n], acc[0][n]);
; #pragma unroll
;   for (int m = 0; m < 4; ++m) fa1[m] = LDSF(cur + aoff + APAN + m * 1024);
; #pragma unroll
;   for (int n = 0; n < 4; ++n) acc[1][n] = MFMA16(fa0[1], fb0[n], acc[1][n]);
; #pragma unroll
;   for (int n = 0; n < 4; ++n) fb1[n] = LDSF(cur + boff + BPAN + n * 1024);
; #pragma unroll
;   for (int n = 0; n < 4; ++n) acc[2][n] = MFMA16(fa0[2], fb0[n], acc[2][n]);
;   *reinterpret_cast<uint4*>(nxt + wao) = a0;
;   *reinterpret_cast<uint4*>(nxt + wao + 32 * 64) = a1;
; #pragma unroll
;   for (int n = 0; n < 4; ++n) acc[3][n] = MFMA16(fa0[3], fb0[n], acc[3][n]);
;   *reinterpret_cast<uint4*>(nxt + wao + 64 * 64) = a2;
;   *reinterpret_cast<uint4*>(nxt + wao + 96 * 64) = a3;
; #pragma unroll
;   for (int n = 0; n < 4; ++n) acc[0][n] = MFMA16(fa1[0], fb1[n], acc[0][n]);
;   *reinterpret_cast<uint4*>(nxt + wbo) = b0;
;   *reinterpret_cast<uint4*>(nxt + wbo + 32 * 64) = b1;
; #pragma unroll
;   for (int n = 0; n < 4; ++n) acc[1][n] = MFMA16(fa1[1], fb1[n], acc[1][n]);
;   *reinterpret_cast<uint4*>(nxt + wbo + 64 * 64) = b2;
;   *reinterpret_cast<uint4*>(nxt + wbo + 96 * 64) = b3;
; #pragma unroll
;   for (int n = 0; n < 4; ++n) acc[2][n] = MFMA16(fa1[2], fb1[n], acc[2][n]);
;   pa = fa1[3];
;   pb0 = fb1[0]; pb1 = fb1[1]; pb2 = fb1[2]; pb3 = fb1[3];
;   SGB_(0x100, 5);
;   SGB_(0x008, 4);
; #pragma unroll
;   for (int i_ = 0; i_ < 11; ++i_) { SGB_(0x008, 1); SGB_(0x100, 1); }
; #pragma unroll
;   for (int i_ = 0; i_ < 8; ++i_) { SGB_(0x008, 2); SGB_(0x200, 1); SGB_(0x020, 1); }
;   SGB_(0x008, 1);
; }
.LBB0_318:
	s_add_i32 s44, s7, 2
	s_add_i32 s7, s7, 4
	s_min_u32 s7, s7, 15
	s_lshl_b32 s7, s7, 7
	s_add_u32 s92, s10, s7
	s_addc_u32 s93, s11, 0
	s_add_u32 s94, s12, s7
	s_addc_u32 s95, s13, 0
	ds_read_b128 v[144:147], v124
	ds_read_b128 v[128:131], v125 offset:16512
	ds_read_b128 v[132:135], v125 offset:17536
	ds_read_b128 v[136:139], v125 offset:18560
	ds_read_b128 v[140:143], v125 offset:19584
	v_mfma_f32_16x16x32_bf16 v[64:67], v[48:51], v[64:67], v[92:95]
	v_mfma_f32_16x16x32_bf16 v[88:91], v[48:51], v[104:107], v[88:91]
	s_waitcnt vmcnt(7)
	ds_write_b128 v126, v[32:35] offset:33024
	global_load_dwordx4 v[32:35], v116, s[92:93]
	s_add_u32 s48, s10, s7
	s_addc_u32 s49, s11, 0
	v_mfma_f32_16x16x32_bf16 v[80:83], v[48:51], v[112:115], v[80:83]
	v_mfma_f32_16x16x32_bf16 v[48:51], v[48:51], v[108:111], v[56:59]
	s_waitcnt lgkmcnt(4)
	v_mfma_f32_16x16x32_bf16 v[56:59], v[144:147], v[128:131], v[100:103]
	ds_read_b128 v[92:95], v124 offset:1024
	s_waitcnt lgkmcnt(4)
	v_mfma_f32_16x16x32_bf16 v[96:99], v[144:147], v[132:135], v[96:99]
	s_waitcnt vmcnt(7)
	ds_write_b128 v126, v[20:23] offset:35072
	global_load_dwordx4 v[20:23], v118, s[92:93]
	ds_read_b128 v[100:103], v124 offset:2048
	s_waitcnt lgkmcnt(5)
	v_mfma_f32_16x16x32_bf16 v[84:87], v[144:147], v[136:139], v[84:87]
	ds_read_b128 v[104:107], v124 offset:3072
	s_waitcnt lgkmcnt(5)
	v_mfma_f32_16x16x32_bf16 v[76:79], v[144:147], v[140:143], v[76:79]
	ds_read_b128 v[108:111], v124 offset:8256
	s_waitcnt lgkmcnt(4)
	v_mfma_f32_16x16x32_bf16 v[72:75], v[92:95], v[128:131], v[72:75]
	ds_read_b128 v[112:115], v124 offset:9280
	v_mfma_f32_16x16x32_bf16 v[68:71], v[92:95], v[132:135], v[68:71]
	ds_read_b128 v[144:147], v124 offset:10304
	v_mfma_f32_16x16x32_bf16 v[60:63], v[92:95], v[136:139], v[60:63]
	s_waitcnt vmcnt(7)
	ds_write_b128 v126, v[16:19] offset:37120
	global_load_dwordx4 v[16:19], v120, s[92:93]
	ds_read_b128 v[148:151], v124 offset:11328
	v_mfma_f32_16x16x32_bf16 v[52:55], v[92:95], v[140:143], v[52:55]
	ds_read_b128 v[92:95], v125 offset:24768
	s_waitcnt lgkmcnt(7)
	v_mfma_f32_16x16x32_bf16 v[44:47], v[100:103], v[128:131], v[44:47]
	ds_read_b128 v[152:155], v125 offset:25792
	v_mfma_f32_16x16x32_bf16 v[40:43], v[100:103], v[132:135], v[40:43]
	ds_read_b128 v[156:159], v125 offset:26816
	v_mfma_f32_16x16x32_bf16 v[36:39], v[100:103], v[136:139], v[36:39]
	s_waitcnt vmcnt(7)
	ds_write_b128 v126, v[24:27] offset:39168
	global_load_dwordx4 v[24:27], v122, s[92:93]
	ds_read_b128 v[160:163], v125 offset:27840
	v_mfma_f32_16x16x32_bf16 v[28:31], v[100:103], v[140:143], v[28:31]
	s_waitcnt lgkmcnt(10)
	v_mfma_f32_16x16x32_bf16 v[64:67], v[104:107], v[128:131], v[64:67]
	v_mfma_f32_16x16x32_bf16 v[88:91], v[104:107], v[132:135], v[88:91]
	v_mfma_f32_16x16x32_bf16 v[80:83], v[104:107], v[136:139], v[80:83]
	v_mfma_f32_16x16x32_bf16 v[48:51], v[104:107], v[140:143], v[48:51]
	s_waitcnt vmcnt(7)
	ds_write_b128 v126, v[12:15] offset:49536
	global_load_dwordx4 v[12:15], v116, s[94:95]
	s_waitcnt lgkmcnt(5)
	v_mfma_f32_16x16x32_bf16 v[56:59], v[108:111], v[92:95], v[56:59]
	s_add_u32 s48, s12, s7
	s_addc_u32 s49, s13, 0
	s_waitcnt lgkmcnt(4)
	v_mfma_f32_16x16x32_bf16 v[96:99], v[108:111], v[152:155], v[96:99]
	s_min_u32 s7, s44, 12
	s_lshl_b32 s7, s7, 7
	s_waitcnt lgkmcnt(3)
	v_mfma_f32_16x16x32_bf16 v[84:87], v[108:111], v[156:159], v[84:87]
	s_waitcnt lgkmcnt(1)
	v_mfma_f32_16x16x32_bf16 v[76:79], v[108:111], v[160:163], v[76:79]
	s_waitcnt vmcnt(7)
	ds_write_b128 v126, v[8:11] offset:51584
	global_load_dwordx4 v[8:11], v118, s[94:95]
	v_mfma_f32_16x16x32_bf16 v[72:75], v[112:115], v[92:95], v[72:75]
	v_mfma_f32_16x16x32_bf16 v[68:71], v[112:115], v[152:155], v[68:71]
	v_mfma_f32_16x16x32_bf16 v[60:63], v[112:115], v[156:159], v[60:63]
	v_mfma_f32_16x16x32_bf16 v[52:55], v[112:115], v[160:163], v[52:55]
	v_mfma_f32_16x16x32_bf16 v[44:47], v[144:147], v[92:95], v[44:47]
	s_waitcnt vmcnt(7)
	ds_write_b128 v126, v[4:7] offset:53632
	global_load_dwordx4 v[4:7], v120, s[94:95]
	v_mfma_f32_16x16x32_bf16 v[40:43], v[144:147], v[152:155], v[40:43]
	s_add_u32 s48, s10, s7
	s_addc_u32 s49, s11, 0
	s_add_u32 s50, s12, s7
	v_mfma_f32_16x16x32_bf16 v[36:39], v[144:147], v[156:159], v[36:39]
	s_addc_u32 s51, s13, 0
	v_mfma_f32_16x16x32_bf16 v[28:31], v[144:147], v[160:163], v[28:31]
	v_mfma_f32_16x16x32_bf16 v[92:95], v[148:151], v[92:95], v[64:67]
	s_waitcnt vmcnt(7)
	ds_write_b128 v126, v[0:3] offset:55680
	global_load_dwordx4 v[0:3], v122, s[94:95]
	v_mfma_f32_16x16x32_bf16 v[88:91], v[148:151], v[152:155], v[88:91]
	v_mfma_f32_16x16x32_bf16 v[80:83], v[148:151], v[156:159], v[80:83]
	v_mfma_f32_16x16x32_bf16 v[100:103], v[148:151], v[160:163], v[48:51]
	s_waitcnt lgkmcnt(0)
	s_barrier
; template <int WM, int WN> ...
;   static_assert(WM == 4 && WN == 4, "128x128 block tile");
;   constexpr int APAN = 128 * 64 + PPAD, BPAN = 128 * 64 + PPAD;
;   bf16x8 fa0[4], fb0[4], fa1[4], fb1[4];
; #pragma unroll
;   for (int n = 0; n < 4; ++n) fb0[n] = LDSF(cur + boff + n * 1024);
; #pragma unroll
;   for (int m = 0; m < 4; ++m) fa0[m] = LDSF(cur + aoff + m * 1024);
;   acc[3][0] = MFMA16(pa, pb0, acc[3][0]);
;   acc[3][1] = MFMA16(pa, pb1, acc[3][1]);
;   acc[3][2] = MFMA16(pa, pb2, acc[3][2]);
;   acc[3][3] = MFMA16(pa, pb3, acc[3][3]);
; #pragma unroll
;   for (int n = 0; n < 4; ++n) acc[0][n] = MFMA16(fa0[0], fb0[n], acc[0][n]);
; #pragma unroll
;   for (int m = 0; m < 4; ++m) fa1[m] = LDSF(cur + aoff + APAN + m * 1024);
; #pragma unroll
;   for (int n = 0; n < 4; ++n) acc[1][n] = MFMA16(fa0[1], fb0[n], acc[1][n]);
; #pragma unroll
;   for (int n = 0; n < 4; ++n) fb1[n] = LDSF(cur + boff + BPAN + n * 1024);
; #pragma unroll
;   for (int n = 0; n < 4; ++n) acc[2][n] = MFMA16(fa0[2], fb0[n], acc[2][n]);
;   *reinterpret_cast<uint4*>(nxt + wao) = a0;
;   *reinterpret_cast<uint4*>(nxt + wao + 32 * 64) = a1;
; #pragma unroll
;   for (int n = 0; n < 4; ++n) acc[3][n] = MFMA16(fa0[3], fb0[n], acc[3][n]);
;   *reinterpret_cast<uint4*>(nxt + wao + 64 * 64) = a2;
;   *reinterpret_cast<uint4*>(nxt + wao + 96 * 64) = a3;
; #pragma unroll
;   for (int n = 0; n < 4; ++n) acc[0][n] = MFMA16(fa1[0], fb1[n], acc[0][n]);
;   *reinterpret_cast<uint4*>(nxt + wbo) = b0;
;   *reinterpret_cast<uint4*>(nxt + wbo + 32 * 64) = b1;
; #pragma unroll
;   for (int n = 0; n < 4; ++n) acc[1][n] = MFMA16(fa1[1], fb1[n], acc[1][n]);
;   *reinterpret_cast<uint4*>(nxt + wbo + 64 * 64) = b2;
;   *reinterpret_cast<uint4*>(nxt + wbo + 96 * 64) = b3;
; #pragma unroll
;   for (int n = 0; n < 4; ++n) acc[2][n] = MFMA16(fa1[2], fb1[n], acc[2][n]);
;   pa = fa1[3];
;   pb0 = fb1[0]; pb1 = fb1[1]; pb2 = fb1[2]; pb3 = fb1[3];
;   SGB_(0x100, 5);
;   SGB_(0x008, 4);
; #pragma unroll
;   for (int i_ = 0; i_ < 11; ++i_) { SGB_(0x008, 1); SGB_(0x100, 1); }
; #pragma unroll
;   for (int i_ = 0; i_ < 8; ++i_) { SGB_(0x008, 2); SGB_(0x200, 1); SGB_(0x020, 1); }
;   SGB_(0x008, 1);
; }
; template <int WM, int WN, typename SrcF, typename PostF>
; __device__ __forceinline__ void gemm_stream(const int nsteps, SrcF src, PostF post, f32x4 (&acc)[WM][WN], char* smem) {
;     ...
;     SB_;
;     post(kt);
	s_nop 0
	ds_read_b128 v[48:51], v124 offset:33024
	ds_read_b128 v[108:111], v125 offset:49536
	ds_read_b128 v[128:131], v125 offset:50560
	ds_read_b128 v[132:135], v125 offset:51584
	ds_read_b128 v[136:139], v125 offset:52608
	s_waitcnt lgkmcnt(3)
	v_mfma_f32_16x16x32_bf16 v[140:143], v[48:51], v[108:111], v[56:59]
	s_waitcnt lgkmcnt(2)
	v_mfma_f32_16x16x32_bf16 v[96:99], v[48:51], v[128:131], v[96:99]
	s_waitcnt vmcnt(7)
	ds_write_b128 v126, v[32:35]
	global_load_dwordx4 v[32:35], v116, s[48:49] offset:384
	s_waitcnt lgkmcnt(2)
	v_mfma_f32_16x16x32_bf16 v[84:87], v[48:51], v[132:135], v[84:87]
	s_waitcnt lgkmcnt(0)
	v_mfma_f32_16x16x32_bf16 v[76:79], v[48:51], v[136:139], v[76:79]
	ds_read_b128 v[48:51], v124 offset:34048
	s_waitcnt lgkmcnt(0)
	v_mfma_f32_16x16x32_bf16 v[72:75], v[48:51], v[108:111], v[72:75]
	s_waitcnt vmcnt(7)
	ds_write_b128 v126, v[20:23] offset:2048
	global_load_dwordx4 v[20:23], v118, s[48:49] offset:384
	ds_read_b128 v[56:59], v124 offset:35072
	v_mfma_f32_16x16x32_bf16 v[68:71], v[48:51], v[128:131], v[68:71]
	ds_read_b128 v[144:147], v124 offset:36096
	v_mfma_f32_16x16x32_bf16 v[60:63], v[48:51], v[132:135], v[60:63]
	ds_read_b128 v[148:151], v124 offset:41280
	v_mfma_f32_16x16x32_bf16 v[52:55], v[48:51], v[136:139], v[52:55]
	ds_read_b128 v[152:155], v124 offset:42304
	s_waitcnt lgkmcnt(3)
	v_mfma_f32_16x16x32_bf16 v[44:47], v[56:59], v[108:111], v[44:47]
	s_waitcnt vmcnt(7)
	ds_write_b128 v126, v[16:19] offset:4096
	global_load_dwordx4 v[16:19], v120, s[48:49] offset:384
	ds_read_b128 v[156:159], v124 offset:43328
	v_mfma_f32_16x16x32_bf16 v[40:43], v[56:59], v[128:131], v[40:43]
	ds_read_b128 v[48:51], v124 offset:44352
	v_mfma_f32_16x16x32_bf16 v[36:39], v[56:59], v[132:135], v[36:39]
	ds_read_b128 v[64:67], v125 offset:57792
	v_mfma_f32_16x16x32_bf16 v[28:31], v[56:59], v[136:139], v[28:31]
	s_waitcnt vmcnt(7)
	ds_write_b128 v126, v[24:27] offset:6144
	global_load_dwordx4 v[24:27], v122, s[48:49] offset:384
	ds_read_b128 v[104:107], v125 offset:58816
	s_waitcnt lgkmcnt(8)
	v_mfma_f32_16x16x32_bf16 v[92:95], v[144:147], v[108:111], v[92:95]
	ds_read_b128 v[112:115], v125 offset:59840
	v_mfma_f32_16x16x32_bf16 v[88:91], v[144:147], v[128:131], v[88:91]
	ds_read_b128 v[108:111], v125 offset:60864
	v_mfma_f32_16x16x32_bf16 v[80:83], v[144:147], v[132:135], v[80:83]
	v_mfma_f32_16x16x32_bf16 v[56:59], v[144:147], v[136:139], v[100:103]
	s_waitcnt vmcnt(7)
	ds_write_b128 v126, v[12:15] offset:16512
	global_load_dwordx4 v[12:15], v116, s[50:51] offset:384
	s_waitcnt lgkmcnt(5)
	v_mfma_f32_16x16x32_bf16 v[100:103], v[148:151], v[64:67], v[140:143]
	s_waitcnt lgkmcnt(3)
	v_mfma_f32_16x16x32_bf16 v[96:99], v[148:151], v[104:107], v[96:99]
	s_waitcnt lgkmcnt(2)
	v_mfma_f32_16x16x32_bf16 v[84:87], v[148:151], v[112:115], v[84:87]
	s_waitcnt vmcnt(7)
	ds_write_b128 v126, v[8:11] offset:18560
	global_load_dwordx4 v[8:11], v118, s[50:51] offset:384
	s_waitcnt lgkmcnt(2)
	v_mfma_f32_16x16x32_bf16 v[76:79], v[148:151], v[108:111], v[76:79]
	v_mfma_f32_16x16x32_bf16 v[72:75], v[152:155], v[64:67], v[72:75]
	v_mfma_f32_16x16x32_bf16 v[68:71], v[152:155], v[104:107], v[68:71]
	v_mfma_f32_16x16x32_bf16 v[60:63], v[152:155], v[112:115], v[60:63]
	s_waitcnt vmcnt(7)
	ds_write_b128 v126, v[4:7] offset:20608
	global_load_dwordx4 v[4:7], v120, s[50:51] offset:384
	v_mfma_f32_16x16x32_bf16 v[52:55], v[152:155], v[108:111], v[52:55]
	v_mfma_f32_16x16x32_bf16 v[44:47], v[156:159], v[64:67], v[44:47]
	v_mfma_f32_16x16x32_bf16 v[40:43], v[156:159], v[104:107], v[40:43]
	s_waitcnt vmcnt(7)
	ds_write_b128 v126, v[0:3] offset:22656
	global_load_dwordx4 v[0:3], v122, s[50:51] offset:384
	v_mfma_f32_16x16x32_bf16 v[36:39], v[156:159], v[112:115], v[36:39]
	v_mfma_f32_16x16x32_bf16 v[28:31], v[156:159], v[108:111], v[28:31]
	s_cmp_lt_u32 s44, 12
	s_mov_b32 s7, s44
	s_waitcnt lgkmcnt(0)
	s_barrier
	s_cbranch_scc1 .LBB0_318
	ds_read_b128 v[144:147], v124
	ds_read_b128 v[128:131], v125 offset:16512
	ds_read_b128 v[132:135], v125 offset:17536
	ds_read_b128 v[136:139], v125 offset:18560
	ds_read_b128 v[140:143], v125 offset:19584
	v_mfma_f32_16x16x32_bf16 v[64:67], v[48:51], v[64:67], v[92:95]
	s_add_i32 s44, s7, 2
	s_add_i32 s7, s7, 4
	s_min_u32 s7, s7, 15
	v_mfma_f32_16x16x32_bf16 v[88:91], v[48:51], v[104:107], v[88:91]
	s_lshl_b32 s7, s7, 7
	s_add_u32 s48, s10, s7
	s_addc_u32 s49, s11, 0
	v_mfma_f32_16x16x32_bf16 v[80:83], v[48:51], v[112:115], v[80:83]
	v_mfma_f32_16x16x32_bf16 v[48:51], v[48:51], v[108:111], v[56:59]
	s_waitcnt lgkmcnt(3)
	v_mfma_f32_16x16x32_bf16 v[56:59], v[144:147], v[128:131], v[100:103]
	ds_read_b128 v[92:95], v124 offset:1024
	s_waitcnt lgkmcnt(3)
	v_mfma_f32_16x16x32_bf16 v[96:99], v[144:147], v[132:135], v[96:99]
	ds_read_b128 v[100:103], v124 offset:2048
	s_waitcnt lgkmcnt(3)
	v_mfma_f32_16x16x32_bf16 v[84:87], v[144:147], v[136:139], v[84:87]
	ds_read_b128 v[104:107], v124 offset:3072
	s_waitcnt lgkmcnt(3)
	v_mfma_f32_16x16x32_bf16 v[76:79], v[144:147], v[140:143], v[76:79]
	ds_read_b128 v[108:111], v124 offset:8256
	s_waitcnt lgkmcnt(3)
	v_mfma_f32_16x16x32_bf16 v[72:75], v[92:95], v[128:131], v[72:75]
	ds_read_b128 v[112:115], v124 offset:9280
	v_mfma_f32_16x16x32_bf16 v[68:71], v[92:95], v[132:135], v[68:71]
	ds_read_b128 v[144:147], v124 offset:10304
	v_mfma_f32_16x16x32_bf16 v[60:63], v[92:95], v[136:139], v[60:63]
	ds_read_b128 v[148:151], v124 offset:11328
	v_mfma_f32_16x16x32_bf16 v[52:55], v[92:95], v[140:143], v[52:55]
	ds_read_b128 v[92:95], v125 offset:24768
	s_waitcnt lgkmcnt(6)
; #define MFMA16(a, b, c) __builtin_amdgcn_mfma_f32_16x16x32_bf16(a, b, c, 0, 0, 0)
; #define SGB_(mask_, n_) __builtin_amdgcn_sched_group_barrier(mask_, n_, 0)
; template <int WM, int WN> ...
;   static_assert(WM == 4 && WN == 4, "128x128 block tile");
;   constexpr int APAN = 128 * 64 + PPAD, BPAN = 128 * 64 + PPAD;
;   bf16x8 fa0[4], fb0[4], fa1[4], fb1[4];
; #pragma unroll
;   for (int n = 0; n < 4; ++n) fb0[n] = LDSF(cur + boff + n * 1024);
; #pragma unroll
;   for (int m = 0; m < 4; ++m) fa0[m] = LDSF(cur + aoff + m * 1024);
;   acc[3][0] = MFMA16(pa, pb0, acc[3][0]);
;   acc[3][1] = MFMA16(pa, pb1, acc[3][1]);
;   acc[3][2] = MFMA16(pa, pb2, acc[3][2]);
;   acc[3][3] = MFMA16(pa, pb3, acc[3][3]);
; #pragma unroll
;   for (int n = 0; n < 4; ++n) acc[0][n] = MFMA16(fa0[0], fb0[n], acc[0][n]);
; #pragma unroll
;   for (int m = 0; m < 4; ++m) fa1[m] = LDSF(cur + aoff + APAN + m * 1024);
; #pragma unroll
;   for (int n = 0; n < 4; ++n) acc[1][n] = MFMA16(fa0[1], fb0[n], acc[1][n]);
; #pragma unroll
;   for (int n = 0; n < 4; ++n) fb1[n] = LDSF(cur + boff + BPAN + n * 1024);
; #pragma unroll
;   for (int n = 0; n < 4; ++n) acc[2][n] = MFMA16(fa0[2], fb0[n], acc[2][n]);
;   *reinterpret_cast<uint4*>(nxt + wao) = a0;
;   *reinterpret_cast<uint4*>(nxt + wao + 32 * 64) = a1;
; #pragma unroll
;   for (int n = 0; n < 4; ++n) acc[3][n] = MFMA16(fa0[3], fb0[n], acc[3][n]);
;   *reinterpret_cast<uint4*>(nxt + wao + 64 * 64) = a2;
;   *reinterpret_cast<uint4*>(nxt + wao + 96 * 64) = a3;
; #pragma unroll
;   for (int n = 0; n < 4; ++n) acc[0][n] = MFMA16(fa1[0], fb1[n], acc[0][n]);
;   *reinterpret_cast<uint4*>(nxt + wbo) = b0;
;   *reinterpret_cast<uint4*>(nxt + wbo + 32 * 64) = b1;
; #pragma unroll
;   for (int n = 0; n < 4; ++n) acc[1][n] = MFMA16(fa1[1], fb1[n], acc[1][n]);
;   *reinterpret_cast<uint4*>(nxt + wbo + 64 * 64) = b2;
;   *reinterpret_cast<uint4*>(nxt + wbo + 96 * 64) = b3;
; #pragma unroll
;   for (int n = 0; n < 4; ++n) acc[2][n] = MFMA16(fa1[2], fb1[n], acc[2][n]);
;   pa = fa1[3];
;   pb0 = fb1[0]; pb1 = fb1[1]; pb2 = fb1[2]; pb3 = fb1[3];
;   SGB_(0x100, 5);
;   SGB_(0x008, 4);
; #pragma unroll
;   for (int i_ = 0; i_ < 11; ++i_) { SGB_(0x008, 1); SGB_(0x100, 1); }
; #pragma unroll
;   for (int i_ = 0; i_ < 8; ++i_) { SGB_(0x008, 2); SGB_(0x200, 1); SGB_(0x020, 1); }
;   SGB_(0x008, 1);
; }
	v_mfma_f32_16x16x32_bf16 v[44:47], v[100:103], v[128:131], v[44:47]
	ds_read_b128 v[152:155], v125 offset:25792
	v_mfma_f32_16x16x32_bf16 v[40:43], v[100:103], v[132:135], v[40:43]
	ds_read_b128 v[156:159], v125 offset:26816
	v_mfma_f32_16x16x32_bf16 v[36:39], v[100:103], v[136:139], v[36:39]
	ds_read_b128 v[160:163], v125 offset:27840
	v_mfma_f32_16x16x32_bf16 v[28:31], v[100:103], v[140:143], v[28:31]
	s_waitcnt lgkmcnt(8)
	v_mfma_f32_16x16x32_bf16 v[64:67], v[104:107], v[128:131], v[64:67]
	s_waitcnt vmcnt(7)
	ds_write_b128 v126, v[32:35] offset:33024
	v_mfma_f32_16x16x32_bf16 v[88:91], v[104:107], v[132:135], v[88:91]
	v_mfma_f32_16x16x32_bf16 v[80:83], v[104:107], v[136:139], v[80:83]
	s_waitcnt vmcnt(6)
	ds_write_b128 v126, v[20:23] offset:35072
	v_mfma_f32_16x16x32_bf16 v[48:51], v[104:107], v[140:143], v[48:51]
	s_waitcnt lgkmcnt(5)
	v_mfma_f32_16x16x32_bf16 v[56:59], v[108:111], v[92:95], v[56:59]
	s_waitcnt vmcnt(5)
	ds_write_b128 v126, v[16:19] offset:37120
	s_add_u32 s48, s12, s7
	s_addc_u32 s49, s13, 0
	s_waitcnt lgkmcnt(5)
	v_mfma_f32_16x16x32_bf16 v[96:99], v[108:111], v[152:155], v[96:99]
	s_min_u32 s7, s44, 12
	s_lshl_b32 s7, s7, 7
	s_waitcnt lgkmcnt(4)
	v_mfma_f32_16x16x32_bf16 v[84:87], v[108:111], v[156:159], v[84:87]
	s_waitcnt vmcnt(4)
	ds_write_b128 v126, v[24:27] offset:39168
	s_waitcnt lgkmcnt(4)
	v_mfma_f32_16x16x32_bf16 v[76:79], v[108:111], v[160:163], v[76:79]
	v_mfma_f32_16x16x32_bf16 v[72:75], v[112:115], v[92:95], v[72:75]
	s_waitcnt vmcnt(3)
	ds_write_b128 v126, v[12:15] offset:49536
	v_mfma_f32_16x16x32_bf16 v[68:71], v[112:115], v[152:155], v[68:71]
	v_mfma_f32_16x16x32_bf16 v[60:63], v[112:115], v[156:159], v[60:63]
	s_waitcnt vmcnt(2)
	ds_write_b128 v126, v[8:11] offset:51584
	v_mfma_f32_16x16x32_bf16 v[52:55], v[112:115], v[160:163], v[52:55]
	v_mfma_f32_16x16x32_bf16 v[44:47], v[144:147], v[92:95], v[44:47]
	s_waitcnt vmcnt(1)
	ds_write_b128 v126, v[4:7] offset:53632
	v_mfma_f32_16x16x32_bf16 v[40:43], v[144:147], v[152:155], v[40:43]
	s_add_u32 s48, s10, s7
	s_addc_u32 s49, s11, 0
	s_add_u32 s50, s12, s7
	v_mfma_f32_16x16x32_bf16 v[36:39], v[144:147], v[156:159], v[36:39]
	s_waitcnt vmcnt(0)
	ds_write_b128 v126, v[0:3] offset:55680
	s_addc_u32 s51, s13, 0
	v_mfma_f32_16x16x32_bf16 v[28:31], v[144:147], v[160:163], v[28:31]
	v_mfma_f32_16x16x32_bf16 v[92:95], v[148:151], v[92:95], v[64:67]
	v_mfma_f32_16x16x32_bf16 v[88:91], v[148:151], v[152:155], v[88:91]
	v_mfma_f32_16x16x32_bf16 v[80:83], v[148:151], v[156:159], v[80:83]
	v_mfma_f32_16x16x32_bf16 v[100:103], v[148:151], v[160:163], v[48:51]
	s_waitcnt lgkmcnt(0)
	s_barrier
	s_nop 0
	ds_read_b128 v[48:51], v124 offset:33024
	ds_read_b128 v[108:111], v125 offset:49536
	ds_read_b128 v[128:131], v125 offset:50560
	ds_read_b128 v[132:135], v125 offset:51584
	ds_read_b128 v[136:139], v125 offset:52608
	s_waitcnt lgkmcnt(3)
	v_mfma_f32_16x16x32_bf16 v[140:143], v[48:51], v[108:111], v[56:59]
	s_waitcnt lgkmcnt(2)
	v_mfma_f32_16x16x32_bf16 v[96:99], v[48:51], v[128:131], v[96:99]
	s_waitcnt lgkmcnt(1)
	v_mfma_f32_16x16x32_bf16 v[84:87], v[48:51], v[132:135], v[84:87]
	s_waitcnt lgkmcnt(0)
	v_mfma_f32_16x16x32_bf16 v[76:79], v[48:51], v[136:139], v[76:79]
	ds_read_b128 v[48:51], v124 offset:34048
	s_waitcnt lgkmcnt(0)
	v_mfma_f32_16x16x32_bf16 v[72:75], v[48:51], v[108:111], v[72:75]
	ds_read_b128 v[56:59], v124 offset:35072
	v_mfma_f32_16x16x32_bf16 v[68:71], v[48:51], v[128:131], v[68:71]
	ds_read_b128 v[144:147], v124 offset:36096
	v_mfma_f32_16x16x32_bf16 v[60:63], v[48:51], v[132:135], v[60:63]
	ds_read_b128 v[148:151], v124 offset:41280
	v_mfma_f32_16x16x32_bf16 v[52:55], v[48:51], v[136:139], v[52:55]
	ds_read_b128 v[152:155], v124 offset:42304
	s_waitcnt lgkmcnt(3)
	v_mfma_f32_16x16x32_bf16 v[44:47], v[56:59], v[108:111], v[44:47]
	ds_read_b128 v[156:159], v124 offset:43328
	v_mfma_f32_16x16x32_bf16 v[40:43], v[56:59], v[128:131], v[40:43]
	ds_read_b128 v[48:51], v124 offset:44352
	v_mfma_f32_16x16x32_bf16 v[36:39], v[56:59], v[132:135], v[36:39]
	ds_read_b128 v[64:67], v125 offset:57792
	v_mfma_f32_16x16x32_bf16 v[28:31], v[56:59], v[136:139], v[28:31]
	ds_read_b128 v[104:107], v125 offset:58816
	s_waitcnt lgkmcnt(6)
	v_mfma_f32_16x16x32_bf16 v[92:95], v[144:147], v[108:111], v[92:95]
	ds_read_b128 v[112:115], v125 offset:59840
	v_mfma_f32_16x16x32_bf16 v[88:91], v[144:147], v[128:131], v[88:91]
	ds_read_b128 v[108:111], v125 offset:60864
	v_mfma_f32_16x16x32_bf16 v[80:83], v[144:147], v[132:135], v[80:83]
	v_mfma_f32_16x16x32_bf16 v[56:59], v[144:147], v[136:139], v[100:103]
	s_waitcnt lgkmcnt(3)
	v_mfma_f32_16x16x32_bf16 v[100:103], v[148:151], v[64:67], v[140:143]
	s_waitcnt lgkmcnt(2)
	v_mfma_f32_16x16x32_bf16 v[96:99], v[148:151], v[104:107], v[96:99]
	s_waitcnt lgkmcnt(1)
	v_mfma_f32_16x16x32_bf16 v[84:87], v[148:151], v[112:115], v[84:87]
	s_waitcnt lgkmcnt(0)
	v_mfma_f32_16x16x32_bf16 v[76:79], v[148:151], v[108:111], v[76:79]
	v_mfma_f32_16x16x32_bf16 v[72:75], v[152:155], v[64:67], v[72:75]
	v_mfma_f32_16x16x32_bf16 v[68:71], v[152:155], v[104:107], v[68:71]
	v_mfma_f32_16x16x32_bf16 v[60:63], v[152:155], v[112:115], v[60:63]
	v_mfma_f32_16x16x32_bf16 v[52:55], v[152:155], v[108:111], v[52:55]
	v_mfma_f32_16x16x32_bf16 v[44:47], v[156:159], v[64:67], v[44:47]
	v_mfma_f32_16x16x32_bf16 v[40:43], v[156:159], v[104:107], v[40:43]
	v_mfma_f32_16x16x32_bf16 v[36:39], v[156:159], v[112:115], v[36:39]
	v_mfma_f32_16x16x32_bf16 v[28:31], v[156:159], v[108:111], v[28:31]
	s_cmp_lt_u32 s44, 14
	s_mov_b32 s7, s44
	s_waitcnt lgkmcnt(0)
	s_barrier
; #define MFMA16(a, b, c) __builtin_amdgcn_mfma_f32_16x16x32_bf16(a, b, c, 0, 0, 0)
; template <int WM, int WN, typename SrcF, typename PostF>
; __device__ __forceinline__ void gemm_stream(const int nsteps, SrcF src, PostF post, f32x4 (&acc)[WM][WN], char* smem) {
;     ...
;   acc[3][0] = MFMA16(pa, pb0, acc[3][0]);
;   acc[3][1] = MFMA16(pa, pb1, acc[3][1]);
;   acc[3][2] = MFMA16(pa, pb2, acc[3][2]);
;   acc[3][3] = MFMA16(pa, pb3, acc[3][3]);
; template <int WM, int WN>
; __device__ __forceinline__ void store_tile_bf16(const f32x4 (&acc)[WM][WN], u16* dst, int ld, char* smem) {
;   constexpr int BM = 32 * WM, BN = 32 * WN, STR = BN + 8;
;   const int tid = opaque_tid(), lane = tid & 63, wid = tid >> 6;
;   const int wr = wid >> 1, wc = wid & 1, fr = lane & 15, fq = lane >> 4;
;   u16* T = reinterpret_cast<u16*>(smem);
; #pragma unroll
;   for (int m = 0; m < WM; ++m)
; #pragma unroll
;     for (int n = 0; n < WN; ++n)
; #pragma unroll
;       for (int j = 0; j < 4; ++j)
;         T[(wr * 16 * WM + m * 16 + fq * 4 + j) * STR + wc * 16 * WN + n * 16 + fr] = f2bf(acc[m][n][j]);
;   __syncthreads();
	s_waitcnt vmcnt(5)
	v_mov_b32_e32 v16, v232
	s_waitcnt vmcnt(0)
	v_mfma_f32_16x16x32_bf16 v[0:3], v[48:51], v[64:67], v[92:95]
	v_lshrrev_b32_e32 v18, 2, v16
	v_lshrrev_b32_e32 v17, 1, v16
	v_and_b32_e32 v18, 12, v18
	v_and_or_b32 v17, v17, s40, v18
	v_and_b32_e32 v18, 0x4f, v16
	v_mul_lo_u32 v17, v17, s42
	v_lshl_add_u32 v17, v18, 1, v17
	v_cvt_pk_bf16_f32 v18, v101, v102
	ds_write_b16 v17, v18 offset:272
	ds_write_b16_d16_hi v17, v18 offset:544
	v_cvt_pk_bf16_f32 v18, v103, v96
	ds_write_b16 v17, v18 offset:816
	ds_write_b16_d16_hi v17, v18 offset:32
	v_cvt_pk_bf16_f32 v18, v97, v98
	ds_write_b16 v17, v18 offset:304
	ds_write_b16_d16_hi v17, v18 offset:576
	v_cvt_pk_bf16_f32 v18, v99, v84
	ds_write_b16 v17, v18 offset:848
	ds_write_b16_d16_hi v17, v18 offset:64
	v_cvt_pk_bf16_f32 v18, v85, v86
	ds_write_b16 v17, v18 offset:336
	ds_write_b16_d16_hi v17, v18 offset:608
	v_cvt_pk_bf16_f32 v18, v87, v76
	ds_write_b16 v17, v18 offset:880
	ds_write_b16_d16_hi v17, v18 offset:96
	v_cvt_pk_bf16_f32 v18, v77, v78
	ds_write_b16 v17, v18 offset:368
	ds_write_b16_d16_hi v17, v18 offset:640
	v_cvt_pk_bf16_f32 v18, v79, v72
	ds_write_b16 v17, v18 offset:912
	ds_write_b16_d16_hi v17, v18 offset:4352
	v_cvt_pk_bf16_f32 v18, v73, v74
	ds_write_b16 v17, v18 offset:4624
	ds_write_b16_d16_hi v17, v18 offset:4896
	v_cvt_pk_bf16_f32 v18, v75, v68
	ds_write_b16 v17, v18 offset:5168
	ds_write_b16_d16_hi v17, v18 offset:4384
	v_cvt_pk_bf16_f32 v18, v69, v70
	ds_write_b16 v17, v18 offset:4656
	ds_write_b16_d16_hi v17, v18 offset:4928
	v_cvt_pk_bf16_f32 v18, v71, v60
	ds_write_b16 v17, v18 offset:5200
	ds_write_b16_d16_hi v17, v18 offset:4416
	v_cvt_pk_bf16_f32 v18, v61, v62
	ds_write_b16 v17, v18 offset:4688
	ds_write_b16_d16_hi v17, v18 offset:4960
	v_cvt_pk_bf16_f32 v18, v63, v52
	ds_write_b16 v17, v18 offset:5232
	ds_write_b16_d16_hi v17, v18 offset:4448
	v_cvt_pk_bf16_f32 v18, v53, v54
	ds_write_b16 v17, v18 offset:4720
	ds_write_b16_d16_hi v17, v18 offset:4992
	v_cvt_pk_bf16_f32 v18, v55, v44
	ds_write_b16 v17, v18 offset:5264
	ds_write_b16_d16_hi v17, v18 offset:8704
	v_cvt_pk_bf16_f32 v18, v45, v46
	ds_write_b16 v17, v18 offset:8976
	ds_write_b16_d16_hi v17, v18 offset:9248
	v_cvt_pk_bf16_f32 v18, v47, v40
	ds_write_b16 v17, v18 offset:9520
	ds_write_b16_d16_hi v17, v18 offset:8736
	v_cvt_pk_bf16_f32 v18, v41, v42
	ds_write_b16 v17, v18 offset:9008
	ds_write_b16_d16_hi v17, v18 offset:9280
	v_cvt_pk_bf16_f32 v18, v43, v36
	ds_write_b16 v17, v18 offset:9552
	ds_write_b16_d16_hi v17, v18 offset:8768
	v_cvt_pk_bf16_f32 v18, v37, v38
	ds_write_b16 v17, v18 offset:9040
	ds_write_b16_d16_hi v17, v18 offset:9312
	v_cvt_pk_bf16_f32 v18, v39, v28
	ds_write_b16 v17, v18 offset:9584
	ds_write_b16_d16_hi v17, v18 offset:8800
	v_cvt_pk_bf16_f32 v18, v29, v30
	ds_write_b16 v17, v18 offset:9072
	ds_write_b16_d16_hi v17, v18 offset:9344
	v_cvt_pk_bf16_f32 v18, 0, v31
	ds_write_b16_d16_hi v17, v18 offset:9616
	v_cvt_pk_bf16_f32 v0, 0, v0
	ds_write_b16_d16_hi v17, v0 offset:13056
	v_cvt_pk_bf16_f32 v0, 0, v1
	v_mfma_f32_16x16x32_bf16 v[4:7], v[48:51], v[104:107], v[88:91]
	ds_write_b16_d16_hi v17, v0 offset:13328
	v_cvt_pk_bf16_f32 v0, v2, v3
	ds_write_b16 v17, v0 offset:13600
	ds_write_b16_d16_hi v17, v0 offset:13872
	s_nop 0
	s_nop 1
	s_nop 0
	v_cvt_pk_bf16_f32 v0, 0, v4
	ds_write_b16_d16_hi v17, v0 offset:13088
	v_cvt_pk_bf16_f32 v0, 0, v5
	v_mfma_f32_16x16x32_bf16 v[8:11], v[48:51], v[112:115], v[80:83]
	ds_write_b16_d16_hi v17, v0 offset:13360
	v_cvt_pk_bf16_f32 v0, v6, v7
	ds_write_b16 v17, v0 offset:13632
	ds_write_b16_d16_hi v17, v0 offset:13904
	s_nop 0
	s_nop 1
	s_nop 0
	v_cvt_pk_bf16_f32 v0, 0, v8
	ds_write_b16_d16_hi v17, v0 offset:13120
	v_cvt_pk_bf16_f32 v0, 0, v9
	v_mfma_f32_16x16x32_bf16 v[12:15], v[48:51], v[108:111], v[56:59]
	ds_write_b16_d16_hi v17, v0 offset:13392
	v_cvt_pk_bf16_f32 v0, v10, v11
	ds_write_b16 v17, v0 offset:13664
	ds_write_b16_d16_hi v17, v0 offset:13936
	s_nop 0
	s_nop 1
	s_nop 0
	v_cvt_pk_bf16_f32 v0, v12, v13
	ds_write_b16 v17, v0 offset:13152
	ds_write_b16_d16_hi v17, v0 offset:13424
	v_cvt_pk_bf16_f32 v0, 0, v14
	ds_write_b16_d16_hi v17, v0 offset:13696
	s_lshl_b64 s[8:9], s[8:9], 1
	v_cvt_pk_bf16_f32 v0, 0, v15
	s_add_u32 s8, s26, s8
	ds_write_b16_d16_hi v17, v0 offset:13968
	v_ashrrev_i32_e32 v0, 31, v16
	s_addc_u32 s9, s27, s9
	s_lshl_b32 s6, s6, 7
	v_lshrrev_b32_e32 v0, 28, v0
	s_ashr_i32 s7, s6, 31
	v_add_u32_e32 v0, v16, v0
	s_lshl_b64 s[6:7], s[6:7], 1
	v_ashrrev_i32_e32 v4, 4, v0
	v_and_b32_e32 v0, -16, v0
	s_add_u32 s6, s8, s6
	v_sub_u32_e32 v0, v16, v0
	v_ashrrev_i32_e32 v5, 31, v4
	s_addc_u32 s7, s9, s7
	v_mul_lo_u32 v1, v4, s42
	v_lshlrev_b32_e32 v6, 3, v0
	v_lshlrev_b64 v[4:5], 11, v[4:5]
	v_ashrrev_i32_e32 v7, 31, v6
	v_lshl_add_u64 v[4:5], s[6:7], 0, v[4:5]
	v_lshl_add_u64 v[8:9], v[6:7], 1, v[4:5]
	v_add_u32_e32 v4, 0x100, v16
	v_ashrrev_i32_e32 v5, 31, v4
	v_cvt_pk_bf16_f32 v19, 0, v100
	v_lshl_add_u32 v0, v0, 4, v1
	v_lshrrev_b32_e32 v5, 28, v5
	ds_write_b16_d16_hi v17, v19
	s_waitcnt lgkmcnt(0)
	s_barrier
; template <int WM, int WN>
; __device__ __forceinline__ void store_tile_bf16(const f32x4 (&acc)[WM][WN], u16* dst, int ld, char* smem) {
;     ...
;   constexpr int CPR = BN / 8;
; #pragma unroll
;   for (int i = 0; i < BM * CPR / 256; ++i) {
;     int q = tid + 256 * i, row = q / CPR, c = q % CPR;
;     uint4 v = *reinterpret_cast<const uint4*>(T + row * STR + c * 8);
;     *reinterpret_cast<uint4*>(dst + (size_t)row * ld + c * 8) = v;
;   }
	ds_read_b128 v[0:3], v0
	v_add_u32_e32 v5, v4, v5
	v_ashrrev_i32_e32 v10, 4, v5
	v_and_b32_e32 v5, -16, v5
	v_sub_u32_e32 v11, v4, v5
	v_mul_lo_u32 v4, v10, s42
	v_lshl_add_u32 v4, v11, 4, v4
	ds_read_b128 v[4:7], v4
	s_waitcnt lgkmcnt(1)
	global_store_dwordx4 v[8:9], v[0:3], off
	s_add_i32 s43, s43, s61
	s_cmp_lt_i32 s43, s62
	v_lshlrev_b32_e32 v0, 3, v11
	v_ashrrev_i32_e32 v11, 31, v10
	v_lshlrev_b64 v[2:3], 11, v[10:11]
	v_ashrrev_i32_e32 v1, 31, v0
	v_lshl_add_u64 v[2:3], s[6:7], 0, v[2:3]
	v_lshl_add_u64 v[0:1], v[0:1], 1, v[2:3]
	s_waitcnt lgkmcnt(0)
	global_store_dwordx4 v[0:1], v[4:7], off
	v_add_u32_e32 v0, 0x200, v16
	v_ashrrev_i32_e32 v1, 31, v0
	v_lshrrev_b32_e32 v1, 28, v1
	v_add_u32_e32 v1, v0, v1
	v_ashrrev_i32_e32 v4, 4, v1
	v_and_b32_e32 v1, -16, v1
	v_sub_u32_e32 v0, v0, v1
	v_ashrrev_i32_e32 v5, 31, v4
	v_mul_lo_u32 v1, v4, s42
	v_lshlrev_b32_e32 v6, 3, v0
	v_lshlrev_b64 v[4:5], 11, v[4:5]
	v_ashrrev_i32_e32 v7, 31, v6
	v_lshl_add_u64 v[4:5], s[6:7], 0, v[4:5]
	v_lshl_add_u64 v[8:9], v[6:7], 1, v[4:5]
	v_add_u32_e32 v4, 0x300, v16
	v_ashrrev_i32_e32 v5, 31, v4
	v_lshl_add_u32 v0, v0, 4, v1
	v_lshrrev_b32_e32 v5, 28, v5
	ds_read_b128 v[0:3], v0
	v_add_u32_e32 v5, v4, v5
	v_ashrrev_i32_e32 v10, 4, v5
	v_and_b32_e32 v5, -16, v5
	v_sub_u32_e32 v11, v4, v5
	v_mul_lo_u32 v4, v10, s42
	v_lshl_add_u32 v4, v11, 4, v4
	ds_read_b128 v[4:7], v4
	s_waitcnt lgkmcnt(1)
	global_store_dwordx4 v[8:9], v[0:3], off
	s_nop 1
	v_lshlrev_b32_e32 v0, 3, v11
	v_ashrrev_i32_e32 v11, 31, v10
	v_lshlrev_b64 v[2:3], 11, v[10:11]
	v_ashrrev_i32_e32 v1, 31, v0
	v_lshl_add_u64 v[2:3], s[6:7], 0, v[2:3]
	v_lshl_add_u64 v[0:1], v[0:1], 1, v[2:3]
	s_waitcnt lgkmcnt(0)
	global_store_dwordx4 v[0:1], v[4:7], off
	v_add_u32_e32 v0, 0x400, v16
	v_ashrrev_i32_e32 v1, 31, v0
	v_lshrrev_b32_e32 v1, 28, v1
	v_add_u32_e32 v1, v0, v1
	v_ashrrev_i32_e32 v4, 4, v1
	v_and_b32_e32 v1, -16, v1
	v_sub_u32_e32 v0, v0, v1
	v_ashrrev_i32_e32 v5, 31, v4
	v_mul_lo_u32 v1, v4, s42
	v_lshlrev_b32_e32 v6, 3, v0
	v_lshlrev_b64 v[4:5], 11, v[4:5]
	v_ashrrev_i32_e32 v7, 31, v6
	v_lshl_add_u64 v[4:5], s[6:7], 0, v[4:5]
	v_lshl_add_u64 v[8:9], v[6:7], 1, v[4:5]
	v_add_u32_e32 v4, 0x500, v16
	v_ashrrev_i32_e32 v5, 31, v4
	v_lshl_add_u32 v0, v0, 4, v1
	v_lshrrev_b32_e32 v5, 28, v5
	ds_read_b128 v[0:3], v0
	v_add_u32_e32 v5, v4, v5
	v_ashrrev_i32_e32 v10, 4, v5
	v_and_b32_e32 v5, -16, v5
	v_sub_u32_e32 v11, v4, v5
	v_mul_lo_u32 v4, v10, s42
	v_lshl_add_u32 v4, v11, 4, v4
	ds_read_b128 v[4:7], v4
	s_waitcnt lgkmcnt(1)
	global_store_dwordx4 v[8:9], v[0:3], off
	s_nop 1
	v_lshlrev_b32_e32 v0, 3, v11
	v_ashrrev_i32_e32 v11, 31, v10
	v_lshlrev_b64 v[2:3], 11, v[10:11]
	v_ashrrev_i32_e32 v1, 31, v0
	v_lshl_add_u64 v[2:3], s[6:7], 0, v[2:3]
	v_lshl_add_u64 v[0:1], v[0:1], 1, v[2:3]
	s_waitcnt lgkmcnt(0)
	global_store_dwordx4 v[0:1], v[4:7], off
	v_add_u32_e32 v0, 0x600, v16
	v_ashrrev_i32_e32 v1, 31, v0
	v_lshrrev_b32_e32 v1, 28, v1
	v_add_u32_e32 v1, v0, v1
	v_ashrrev_i32_e32 v4, 4, v1
	v_and_b32_e32 v1, -16, v1
	v_sub_u32_e32 v0, v0, v1
	v_ashrrev_i32_e32 v5, 31, v4
	v_mul_lo_u32 v1, v4, s42
	v_lshlrev_b32_e32 v6, 3, v0
	v_lshlrev_b64 v[4:5], 11, v[4:5]
	v_ashrrev_i32_e32 v7, 31, v6
	v_lshl_add_u64 v[4:5], s[6:7], 0, v[4:5]
	v_lshl_add_u64 v[8:9], v[6:7], 1, v[4:5]
	v_add_u32_e32 v4, 0x700, v16
	v_ashrrev_i32_e32 v5, 31, v4
	v_lshl_add_u32 v0, v0, 4, v1
	v_lshrrev_b32_e32 v5, 28, v5
	ds_read_b128 v[0:3], v0
	v_add_u32_e32 v5, v4, v5
	v_ashrrev_i32_e32 v10, 4, v5
	v_and_b32_e32 v5, -16, v5
	v_sub_u32_e32 v11, v4, v5
	v_mul_lo_u32 v4, v10, s42
	v_lshl_add_u32 v4, v11, 4, v4
	ds_read_b128 v[4:7], v4
	s_waitcnt lgkmcnt(1)
	global_store_dwordx4 v[8:9], v[0:3], off
	s_nop 1
	v_lshlrev_b32_e32 v0, 3, v11
	v_ashrrev_i32_e32 v11, 31, v10
	v_lshlrev_b64 v[2:3], 11, v[10:11]
	v_ashrrev_i32_e32 v1, 31, v0
	v_lshl_add_u64 v[2:3], s[6:7], 0, v[2:3]
	v_lshl_add_u64 v[0:1], v[0:1], 1, v[2:3]
	s_waitcnt lgkmcnt(0)
	global_store_dwordx4 v[0:1], v[4:7], off
	s_cbranch_scc1 .LBB0_317

; #define MFMA16(a, b, c) __builtin_amdgcn_mfma_f32_16x16x32_bf16(a, b, c, 0, 0, 0)
; #define SGB_(mask_, n_) __builtin_amdgcn_sched_group_barrier(mask_, n_, 0)
; template <int WM, int WN> ...
;   static_assert(WM == 4 && WN == 4, "128x128 block tile");
;   constexpr int APAN = 128 * 64 + PPAD, BPAN = 128 * 64 + PPAD;
;   bf16x8 fa0[4], fb0[4], fa1[4], fb1[4];
; #pragma unroll
;   for (int n = 0; n < 4; ++n) fb0[n] = LDSF(cur + boff + n * 1024);
; #pragma unroll
;   for (int m = 0; m < 4; ++m) fa0[m] = LDSF(cur + aoff + m * 1024);
;   acc[3][0] = MFMA16(pa, pb0, acc[3][0]);
;   acc[3][1] = MFMA16(pa, pb1, acc[3][1]);
;   acc[3][2] = MFMA16(pa, pb2, acc[3][2]);
;   acc[3][3] = MFMA16(pa, pb3, acc[3][3]);
; #pragma unroll
;   for (int n = 0; n < 4; ++n) acc[0][n] = MFMA16(fa0[0], fb0[n], acc[0][n]);
; #pragma unroll
;   for (int m = 0; m < 4; ++m) fa1[m] = LDSF(cur + aoff + APAN + m * 1024);
; #pragma unroll
;   for (int n = 0; n < 4; ++n) acc[1][n] = MFMA16(fa0[1], fb0[n], acc[1][n]);
; #pragma unroll
;   for (int n = 0; n < 4; ++n) fb1[n] = LDSF(cur + boff + BPAN + n * 1024);
; #pragma unroll
;   for (int n = 0; n < 4; ++n) acc[2][n] = MFMA16(fa0[2], fb0[n], acc[2][n]);
;   *reinterpret_cast<uint4*>(nxt + wao) = a0;
;   *reinterpret_cast<uint4*>(nxt + wao + 32 * 64) = a1;
; #pragma unroll
;   for (int n = 0; n < 4; ++n) acc[3][n] = MFMA16(fa0[3], fb0[n], acc[3][n]);
;   *reinterpret_cast<uint4*>(nxt + wao + 64 * 64) = a2;
;   *reinterpret_cast<uint4*>(nxt + wao + 96 * 64) = a3;
; #pragma unroll
;   for (int n = 0; n < 4; ++n) acc[0][n] = MFMA16(fa1[0], fb1[n], acc[0][n]);
;   *reinterpret_cast<uint4*>(nxt + wbo) = b0;
;   *reinterpret_cast<uint4*>(nxt + wbo + 32 * 64) = b1;
; #pragma unroll
;   for (int n = 0; n < 4; ++n) acc[1][n] = MFMA16(fa1[1], fb1[n], acc[1][n]);
;   *reinterpret_cast<uint4*>(nxt + wbo + 64 * 64) = b2;
;   *reinterpret_cast<uint4*>(nxt + wbo + 96 * 64) = b3;
; #pragma unroll
;   for (int n = 0; n < 4; ++n) acc[2][n] = MFMA16(fa1[2], fb1[n], acc[2][n]);
;   pa = fa1[3];
;   pb0 = fb1[0]; pb1 = fb1[1]; pb2 = fb1[2]; pb3 = fb1[3];
;   SGB_(0x100, 5);
;   SGB_(0x008, 4);
; #pragma unroll
;   for (int i_ = 0; i_ < 11; ++i_) { SGB_(0x008, 1); SGB_(0x100, 1); }
; #pragma unroll
;   for (int i_ = 0; i_ < 8; ++i_) { SGB_(0x008, 2); SGB_(0x200, 1); SGB_(0x020, 1); }
;   SGB_(0x008, 1);
; }
.LBB0_425:
	s_add_i32 s17, s14, 2
	s_add_i32 s14, s14, 4
	s_min_u32 s14, s14, 15
	s_lshl_b32 s14, s14, 7
	s_add_u32 s92, s24, s14
	s_addc_u32 s93, s25, 0
	s_add_u32 s94, s26, s14
	s_addc_u32 s95, s27, 0
	ds_read_b128 v[148:151], v119
	ds_read_b128 v[132:135], v130 offset:16512
	ds_read_b128 v[136:139], v130 offset:17536
	ds_read_b128 v[140:143], v130 offset:18560
	ds_read_b128 v[144:147], v130 offset:19584
	v_mfma_f32_16x16x32_bf16 v[84:87], v[80:83], v[84:87], v[100:103]
	v_mfma_f32_16x16x32_bf16 v[96:99], v[80:83], v[104:107], v[96:99]
	s_waitcnt vmcnt(7)
	ds_write_b128 v131, v[76:79] offset:33024
	global_load_dwordx4 v[76:79], v116, s[92:93]
	s_add_u32 s64, s24, s14
	s_addc_u32 s65, s25, 0
	v_mfma_f32_16x16x32_bf16 v[92:95], v[80:83], v[108:111], v[92:95]
	v_mfma_f32_16x16x32_bf16 v[80:83], v[80:83], v[112:115], v[88:91]
	s_waitcnt lgkmcnt(4)
	v_mfma_f32_16x16x32_bf16 v[44:47], v[148:151], v[132:135], v[44:47]
	s_nop 0
	ds_read_b128 v[88:91], v119 offset:1024
	s_waitcnt lgkmcnt(4)
	v_mfma_f32_16x16x32_bf16 v[40:43], v[148:151], v[136:139], v[40:43]
	s_waitcnt vmcnt(7)
	ds_write_b128 v131, v[68:71] offset:35072
	global_load_dwordx4 v[68:71], v120, s[92:93]
	ds_read_b128 v[100:103], v119 offset:2048
	s_waitcnt lgkmcnt(5)
	v_mfma_f32_16x16x32_bf16 v[36:39], v[148:151], v[140:143], v[36:39]
	ds_read_b128 v[104:107], v119 offset:3072
	s_waitcnt lgkmcnt(5)
	v_mfma_f32_16x16x32_bf16 v[32:35], v[148:151], v[144:147], v[32:35]
	ds_read_b128 v[108:111], v119 offset:8256
	s_waitcnt lgkmcnt(4)
	v_mfma_f32_16x16x32_bf16 v[28:31], v[88:91], v[132:135], v[28:31]
	ds_read_b128 v[112:115], v119 offset:9280
	v_mfma_f32_16x16x32_bf16 v[24:27], v[88:91], v[136:139], v[24:27]
	ds_read_b128 v[148:151], v119 offset:10304
	v_mfma_f32_16x16x32_bf16 v[20:23], v[88:91], v[140:143], v[20:23]
	s_waitcnt vmcnt(7)
	ds_write_b128 v131, v[64:67] offset:37120
	global_load_dwordx4 v[64:67], v122, s[92:93]
	ds_read_b128 v[152:155], v119 offset:11328
	v_mfma_f32_16x16x32_bf16 v[16:19], v[88:91], v[144:147], v[16:19]
	ds_read_b128 v[88:91], v130 offset:24768
	s_waitcnt lgkmcnt(7)
	v_mfma_f32_16x16x32_bf16 v[12:15], v[100:103], v[132:135], v[12:15]
	ds_read_b128 v[156:159], v130 offset:25792
	v_mfma_f32_16x16x32_bf16 v[8:11], v[100:103], v[136:139], v[8:11]
	ds_read_b128 v[160:163], v130 offset:26816
	v_mfma_f32_16x16x32_bf16 v[4:7], v[100:103], v[140:143], v[4:7]
	s_waitcnt vmcnt(7)
	ds_write_b128 v131, v[72:75] offset:39168
	global_load_dwordx4 v[72:75], v124, s[92:93]
	ds_read_b128 v[164:167], v130 offset:27840
	v_mfma_f32_16x16x32_bf16 v[0:3], v[100:103], v[144:147], v[0:3]
	s_waitcnt lgkmcnt(10)
	v_mfma_f32_16x16x32_bf16 v[84:87], v[104:107], v[132:135], v[84:87]
	v_mfma_f32_16x16x32_bf16 v[96:99], v[104:107], v[136:139], v[96:99]
	v_mfma_f32_16x16x32_bf16 v[92:95], v[104:107], v[140:143], v[92:95]
	v_mfma_f32_16x16x32_bf16 v[80:83], v[104:107], v[144:147], v[80:83]
	s_waitcnt vmcnt(7)
	ds_write_b128 v131, v[60:63] offset:49536
	global_load_dwordx4 v[60:63], v116, s[94:95]
	s_waitcnt lgkmcnt(5)
	v_mfma_f32_16x16x32_bf16 v[44:47], v[108:111], v[88:91], v[44:47]
	s_add_u32 s64, s26, s14
	s_addc_u32 s65, s27, 0
	s_waitcnt lgkmcnt(4)
	v_mfma_f32_16x16x32_bf16 v[40:43], v[108:111], v[156:159], v[40:43]
	s_min_u32 s14, s17, 12
	s_lshl_b32 s14, s14, 7
	s_waitcnt lgkmcnt(3)
	v_mfma_f32_16x16x32_bf16 v[36:39], v[108:111], v[160:163], v[36:39]
	s_waitcnt lgkmcnt(1)
	v_mfma_f32_16x16x32_bf16 v[32:35], v[108:111], v[164:167], v[32:35]
	s_waitcnt vmcnt(7)
	ds_write_b128 v131, v[56:59] offset:51584
	global_load_dwordx4 v[56:59], v120, s[94:95]
	v_mfma_f32_16x16x32_bf16 v[28:31], v[112:115], v[88:91], v[28:31]
	v_mfma_f32_16x16x32_bf16 v[24:27], v[112:115], v[156:159], v[24:27]
	v_mfma_f32_16x16x32_bf16 v[20:23], v[112:115], v[160:163], v[20:23]
	v_mfma_f32_16x16x32_bf16 v[16:19], v[112:115], v[164:167], v[16:19]
	v_mfma_f32_16x16x32_bf16 v[12:15], v[148:151], v[88:91], v[12:15]
	s_waitcnt vmcnt(7)
	ds_write_b128 v131, v[52:55] offset:53632
	global_load_dwordx4 v[52:55], v122, s[94:95]
	v_mfma_f32_16x16x32_bf16 v[8:11], v[148:151], v[156:159], v[8:11]
	s_add_u32 s64, s24, s14
	s_addc_u32 s65, s25, 0
	s_add_u32 s66, s26, s14
	v_mfma_f32_16x16x32_bf16 v[4:7], v[148:151], v[160:163], v[4:7]
	s_addc_u32 s67, s27, 0
	v_mfma_f32_16x16x32_bf16 v[0:3], v[148:151], v[164:167], v[0:3]
	v_mfma_f32_16x16x32_bf16 v[88:91], v[152:155], v[88:91], v[84:87]
	s_waitcnt vmcnt(7)
	ds_write_b128 v131, v[48:51] offset:55680
	global_load_dwordx4 v[48:51], v124, s[94:95]
	v_mfma_f32_16x16x32_bf16 v[96:99], v[152:155], v[156:159], v[96:99]
	v_mfma_f32_16x16x32_bf16 v[92:95], v[152:155], v[160:163], v[92:95]
	v_mfma_f32_16x16x32_bf16 v[132:135], v[152:155], v[164:167], v[80:83]
	s_waitcnt lgkmcnt(0)
	s_barrier
; template <int WM, int WN> ...
;   static_assert(WM == 4 && WN == 4, "128x128 block tile");
;   constexpr int APAN = 128 * 64 + PPAD, BPAN = 128 * 64 + PPAD;
;   bf16x8 fa0[4], fb0[4], fa1[4], fb1[4];
; #pragma unroll
;   for (int n = 0; n < 4; ++n) fb0[n] = LDSF(cur + boff + n * 1024);
; #pragma unroll
;   for (int m = 0; m < 4; ++m) fa0[m] = LDSF(cur + aoff + m * 1024);
;   acc[3][0] = MFMA16(pa, pb0, acc[3][0]);
;   acc[3][1] = MFMA16(pa, pb1, acc[3][1]);
;   acc[3][2] = MFMA16(pa, pb2, acc[3][2]);
;   acc[3][3] = MFMA16(pa, pb3, acc[3][3]);
; #pragma unroll
;   for (int n = 0; n < 4; ++n) acc[0][n] = MFMA16(fa0[0], fb0[n], acc[0][n]);
; #pragma unroll
;   for (int m = 0; m < 4; ++m) fa1[m] = LDSF(cur + aoff + APAN + m * 1024);
; #pragma unroll
;   for (int n = 0; n < 4; ++n) acc[1][n] = MFMA16(fa0[1], fb0[n], acc[1][n]);
; #pragma unroll
;   for (int n = 0; n < 4; ++n) fb1[n] = LDSF(cur + boff + BPAN + n * 1024);
; #pragma unroll
;   for (int n = 0; n < 4; ++n) acc[2][n] = MFMA16(fa0[2], fb0[n], acc[2][n]);
;   *reinterpret_cast<uint4*>(nxt + wao) = a0;
;   *reinterpret_cast<uint4*>(nxt + wao + 32 * 64) = a1;
; #pragma unroll
;   for (int n = 0; n < 4; ++n) acc[3][n] = MFMA16(fa0[3], fb0[n], acc[3][n]);
;   *reinterpret_cast<uint4*>(nxt + wao + 64 * 64) = a2;
;   *reinterpret_cast<uint4*>(nxt + wao + 96 * 64) = a3;
; #pragma unroll
;   for (int n = 0; n < 4; ++n) acc[0][n] = MFMA16(fa1[0], fb1[n], acc[0][n]);
;   *reinterpret_cast<uint4*>(nxt + wbo) = b0;
;   *reinterpret_cast<uint4*>(nxt + wbo + 32 * 64) = b1;
; #pragma unroll
;   for (int n = 0; n < 4; ++n) acc[1][n] = MFMA16(fa1[1], fb1[n], acc[1][n]);
;   *reinterpret_cast<uint4*>(nxt + wbo + 64 * 64) = b2;
;   *reinterpret_cast<uint4*>(nxt + wbo + 96 * 64) = b3;
; #pragma unroll
;   for (int n = 0; n < 4; ++n) acc[2][n] = MFMA16(fa1[2], fb1[n], acc[2][n]);
;   pa = fa1[3];
;   pb0 = fb1[0]; pb1 = fb1[1]; pb2 = fb1[2]; pb3 = fb1[3];
;   SGB_(0x100, 5);
;   SGB_(0x008, 4);
; #pragma unroll
;   for (int i_ = 0; i_ < 11; ++i_) { SGB_(0x008, 1); SGB_(0x100, 1); }
; #pragma unroll
;   for (int i_ = 0; i_ < 8; ++i_) { SGB_(0x008, 2); SGB_(0x200, 1); SGB_(0x020, 1); }
;   SGB_(0x008, 1);
; }
; template <int WM, int WN, typename SrcF, typename PostF>
; __device__ __forceinline__ void gemm_stream(const int nsteps, SrcF src, PostF post, f32x4 (&acc)[WM][WN], char* smem) {
;     ...
;     SB_;
;     post(kt);
	s_nop 0
	ds_read_b128 v[80:83], v119 offset:33024
	ds_read_b128 v[100:103], v130 offset:49536
	ds_read_b128 v[112:115], v130 offset:50560
	ds_read_b128 v[136:139], v130 offset:51584
	ds_read_b128 v[140:143], v130 offset:52608
	s_waitcnt lgkmcnt(3)
	v_mfma_f32_16x16x32_bf16 v[44:47], v[80:83], v[100:103], v[44:47]
	s_waitcnt lgkmcnt(2)
	v_mfma_f32_16x16x32_bf16 v[40:43], v[80:83], v[112:115], v[40:43]
	s_waitcnt vmcnt(7)
	ds_write_b128 v131, v[76:79]
	global_load_dwordx4 v[76:79], v116, s[64:65] offset:384
	s_waitcnt lgkmcnt(2)
	v_mfma_f32_16x16x32_bf16 v[36:39], v[80:83], v[136:139], v[36:39]
	s_waitcnt lgkmcnt(0)
	v_mfma_f32_16x16x32_bf16 v[32:35], v[80:83], v[140:143], v[32:35]
	ds_read_b128 v[80:83], v119 offset:34048
	s_waitcnt lgkmcnt(0)
	v_mfma_f32_16x16x32_bf16 v[28:31], v[80:83], v[100:103], v[28:31]
	s_waitcnt vmcnt(7)
	ds_write_b128 v131, v[68:71] offset:2048
	global_load_dwordx4 v[68:71], v120, s[64:65] offset:384
	ds_read_b128 v[104:107], v119 offset:35072
	v_mfma_f32_16x16x32_bf16 v[24:27], v[80:83], v[112:115], v[24:27]
	ds_read_b128 v[144:147], v119 offset:36096
	v_mfma_f32_16x16x32_bf16 v[20:23], v[80:83], v[136:139], v[20:23]
	ds_read_b128 v[148:151], v119 offset:41280
	v_mfma_f32_16x16x32_bf16 v[16:19], v[80:83], v[140:143], v[16:19]
	ds_read_b128 v[152:155], v119 offset:42304
	s_waitcnt lgkmcnt(3)
	v_mfma_f32_16x16x32_bf16 v[12:15], v[104:107], v[100:103], v[12:15]
	s_waitcnt vmcnt(7)
	ds_write_b128 v131, v[64:67] offset:4096
	global_load_dwordx4 v[64:67], v122, s[64:65] offset:384
	ds_read_b128 v[156:159], v119 offset:43328
	v_mfma_f32_16x16x32_bf16 v[8:11], v[104:107], v[112:115], v[8:11]
	ds_read_b128 v[80:83], v119 offset:44352
	v_mfma_f32_16x16x32_bf16 v[4:7], v[104:107], v[136:139], v[4:7]
	ds_read_b128 v[84:87], v130 offset:57792
	v_mfma_f32_16x16x32_bf16 v[0:3], v[104:107], v[140:143], v[0:3]
	s_waitcnt vmcnt(7)
	ds_write_b128 v131, v[72:75] offset:6144
	global_load_dwordx4 v[72:75], v124, s[64:65] offset:384
	ds_read_b128 v[104:107], v130 offset:58816
	s_waitcnt lgkmcnt(8)
	v_mfma_f32_16x16x32_bf16 v[100:103], v[144:147], v[100:103], v[88:91]
	ds_read_b128 v[108:111], v130 offset:59840
	v_mfma_f32_16x16x32_bf16 v[96:99], v[144:147], v[112:115], v[96:99]
	ds_read_b128 v[112:115], v130 offset:60864
	v_mfma_f32_16x16x32_bf16 v[92:95], v[144:147], v[136:139], v[92:95]
	v_mfma_f32_16x16x32_bf16 v[88:91], v[144:147], v[140:143], v[132:135]
	s_waitcnt vmcnt(7)
	ds_write_b128 v131, v[60:63] offset:16512
	global_load_dwordx4 v[60:63], v116, s[66:67] offset:384
	s_waitcnt lgkmcnt(5)
	v_mfma_f32_16x16x32_bf16 v[44:47], v[148:151], v[84:87], v[44:47]
	s_waitcnt lgkmcnt(3)
	v_mfma_f32_16x16x32_bf16 v[40:43], v[148:151], v[104:107], v[40:43]
	s_waitcnt lgkmcnt(2)
	v_mfma_f32_16x16x32_bf16 v[36:39], v[148:151], v[108:111], v[36:39]
	s_waitcnt vmcnt(7)
	ds_write_b128 v131, v[56:59] offset:18560
	global_load_dwordx4 v[56:59], v120, s[66:67] offset:384
	s_waitcnt lgkmcnt(2)
	v_mfma_f32_16x16x32_bf16 v[32:35], v[148:151], v[112:115], v[32:35]
	v_mfma_f32_16x16x32_bf16 v[28:31], v[152:155], v[84:87], v[28:31]
	v_mfma_f32_16x16x32_bf16 v[24:27], v[152:155], v[104:107], v[24:27]
	v_mfma_f32_16x16x32_bf16 v[20:23], v[152:155], v[108:111], v[20:23]
	s_waitcnt vmcnt(7)
	ds_write_b128 v131, v[52:55] offset:20608
	global_load_dwordx4 v[52:55], v122, s[66:67] offset:384
	v_mfma_f32_16x16x32_bf16 v[16:19], v[152:155], v[112:115], v[16:19]
	v_mfma_f32_16x16x32_bf16 v[12:15], v[156:159], v[84:87], v[12:15]
	v_mfma_f32_16x16x32_bf16 v[8:11], v[156:159], v[104:107], v[8:11]
	s_waitcnt vmcnt(7)
	ds_write_b128 v131, v[48:51] offset:22656
	global_load_dwordx4 v[48:51], v124, s[66:67] offset:384
	v_mfma_f32_16x16x32_bf16 v[4:7], v[156:159], v[108:111], v[4:7]
	v_mfma_f32_16x16x32_bf16 v[0:3], v[156:159], v[112:115], v[0:3]
	s_cmp_lt_u32 s17, 12
	s_mov_b32 s14, s17
	s_waitcnt lgkmcnt(0)
	s_barrier
	s_cbranch_scc1 .LBB0_425
	ds_read_b128 v[148:151], v119
	ds_read_b128 v[132:135], v130 offset:16512
	ds_read_b128 v[136:139], v130 offset:17536
	ds_read_b128 v[140:143], v130 offset:18560
	ds_read_b128 v[144:147], v130 offset:19584
	v_mfma_f32_16x16x32_bf16 v[84:87], v[80:83], v[84:87], v[100:103]
	s_add_i32 s17, s14, 2
	s_add_i32 s14, s14, 4
	s_min_u32 s14, s14, 15
	v_mfma_f32_16x16x32_bf16 v[96:99], v[80:83], v[104:107], v[96:99]
	s_lshl_b32 s14, s14, 7
	s_add_u32 s64, s24, s14
	s_addc_u32 s65, s25, 0
	v_mfma_f32_16x16x32_bf16 v[92:95], v[80:83], v[108:111], v[92:95]
	v_mfma_f32_16x16x32_bf16 v[80:83], v[80:83], v[112:115], v[88:91]
	s_waitcnt lgkmcnt(3)
	v_mfma_f32_16x16x32_bf16 v[44:47], v[148:151], v[132:135], v[44:47]
	s_nop 0
	ds_read_b128 v[88:91], v119 offset:1024
	s_waitcnt lgkmcnt(3)
	v_mfma_f32_16x16x32_bf16 v[40:43], v[148:151], v[136:139], v[40:43]
	ds_read_b128 v[100:103], v119 offset:2048
	s_waitcnt lgkmcnt(3)
	v_mfma_f32_16x16x32_bf16 v[36:39], v[148:151], v[140:143], v[36:39]
	ds_read_b128 v[104:107], v119 offset:3072
	s_waitcnt lgkmcnt(3)
	v_mfma_f32_16x16x32_bf16 v[32:35], v[148:151], v[144:147], v[32:35]
	ds_read_b128 v[108:111], v119 offset:8256
	s_waitcnt lgkmcnt(3)
	v_mfma_f32_16x16x32_bf16 v[28:31], v[88:91], v[132:135], v[28:31]
	ds_read_b128 v[112:115], v119 offset:9280
	v_mfma_f32_16x16x32_bf16 v[24:27], v[88:91], v[136:139], v[24:27]
	ds_read_b128 v[148:151], v119 offset:10304
	v_mfma_f32_16x16x32_bf16 v[20:23], v[88:91], v[140:143], v[20:23]
	ds_read_b128 v[152:155], v119 offset:11328
	v_mfma_f32_16x16x32_bf16 v[16:19], v[88:91], v[144:147], v[16:19]
	ds_read_b128 v[88:91], v130 offset:24768
	s_waitcnt lgkmcnt(6)
; #define MFMA16(a, b, c) __builtin_amdgcn_mfma_f32_16x16x32_bf16(a, b, c, 0, 0, 0)
; #define SGB_(mask_, n_) __builtin_amdgcn_sched_group_barrier(mask_, n_, 0)
; template <int WM, int WN> ...
;   static_assert(WM == 4 && WN == 4, "128x128 block tile");
;   constexpr int APAN = 128 * 64 + PPAD, BPAN = 128 * 64 + PPAD;
;   bf16x8 fa0[4], fb0[4], fa1[4], fb1[4];
; #pragma unroll
;   for (int n = 0; n < 4; ++n) fb0[n] = LDSF(cur + boff + n * 1024);
; #pragma unroll
;   for (int m = 0; m < 4; ++m) fa0[m] = LDSF(cur + aoff + m * 1024);
;   acc[3][0] = MFMA16(pa, pb0, acc[3][0]);
;   acc[3][1] = MFMA16(pa, pb1, acc[3][1]);
;   acc[3][2] = MFMA16(pa, pb2, acc[3][2]);
;   acc[3][3] = MFMA16(pa, pb3, acc[3][3]);
; #pragma unroll
;   for (int n = 0; n < 4; ++n) acc[0][n] = MFMA16(fa0[0], fb0[n], acc[0][n]);
; #pragma unroll
;   for (int m = 0; m < 4; ++m) fa1[m] = LDSF(cur + aoff + APAN + m * 1024);
; #pragma unroll
;   for (int n = 0; n < 4; ++n) acc[1][n] = MFMA16(fa0[1], fb0[n], acc[1][n]);
; #pragma unroll
;   for (int n = 0; n < 4; ++n) fb1[n] = LDSF(cur + boff + BPAN + n * 1024);
; #pragma unroll
;   for (int n = 0; n < 4; ++n) acc[2][n] = MFMA16(fa0[2], fb0[n], acc[2][n]);
;   *reinterpret_cast<uint4*>(nxt + wao) = a0;
;   *reinterpret_cast<uint4*>(nxt + wao + 32 * 64) = a1;
; #pragma unroll
;   for (int n = 0; n < 4; ++n) acc[3][n] = MFMA16(fa0[3], fb0[n], acc[3][n]);
;   *reinterpret_cast<uint4*>(nxt + wao + 64 * 64) = a2;
;   *reinterpret_cast<uint4*>(nxt + wao + 96 * 64) = a3;
; #pragma unroll
;   for (int n = 0; n < 4; ++n) acc[0][n] = MFMA16(fa1[0], fb1[n], acc[0][n]);
;   *reinterpret_cast<uint4*>(nxt + wbo) = b0;
;   *reinterpret_cast<uint4*>(nxt + wbo + 32 * 64) = b1;
; #pragma unroll
;   for (int n = 0; n < 4; ++n) acc[1][n] = MFMA16(fa1[1], fb1[n], acc[1][n]);
;   *reinterpret_cast<uint4*>(nxt + wbo + 64 * 64) = b2;
;   *reinterpret_cast<uint4*>(nxt + wbo + 96 * 64) = b3;
; #pragma unroll
;   for (int n = 0; n < 4; ++n) acc[2][n] = MFMA16(fa1[2], fb1[n], acc[2][n]);
;   pa = fa1[3];
;   pb0 = fb1[0]; pb1 = fb1[1]; pb2 = fb1[2]; pb3 = fb1[3];
;   SGB_(0x100, 5);
;   SGB_(0x008, 4);
; #pragma unroll
;   for (int i_ = 0; i_ < 11; ++i_) { SGB_(0x008, 1); SGB_(0x100, 1); }
; #pragma unroll
;   for (int i_ = 0; i_ < 8; ++i_) { SGB_(0x008, 2); SGB_(0x200, 1); SGB_(0x020, 1); }
;   SGB_(0x008, 1);
; }
	v_mfma_f32_16x16x32_bf16 v[12:15], v[100:103], v[132:135], v[12:15]
	ds_read_b128 v[156:159], v130 offset:25792
	v_mfma_f32_16x16x32_bf16 v[8:11], v[100:103], v[136:139], v[8:11]
	ds_read_b128 v[160:163], v130 offset:26816
	v_mfma_f32_16x16x32_bf16 v[4:7], v[100:103], v[140:143], v[4:7]
	ds_read_b128 v[164:167], v130 offset:27840
	v_mfma_f32_16x16x32_bf16 v[0:3], v[100:103], v[144:147], v[0:3]
	s_waitcnt lgkmcnt(8)
	v_mfma_f32_16x16x32_bf16 v[84:87], v[104:107], v[132:135], v[84:87]
	s_waitcnt vmcnt(7)
	ds_write_b128 v131, v[76:79] offset:33024
	v_mfma_f32_16x16x32_bf16 v[96:99], v[104:107], v[136:139], v[96:99]
	v_mfma_f32_16x16x32_bf16 v[92:95], v[104:107], v[140:143], v[92:95]
	s_waitcnt vmcnt(6)
	ds_write_b128 v131, v[68:71] offset:35072
	v_mfma_f32_16x16x32_bf16 v[80:83], v[104:107], v[144:147], v[80:83]
	s_waitcnt lgkmcnt(5)
	v_mfma_f32_16x16x32_bf16 v[44:47], v[108:111], v[88:91], v[44:47]
	s_waitcnt vmcnt(5)
	ds_write_b128 v131, v[64:67] offset:37120
	s_add_u32 s64, s26, s14
	s_addc_u32 s65, s27, 0
	s_waitcnt lgkmcnt(5)
	v_mfma_f32_16x16x32_bf16 v[40:43], v[108:111], v[156:159], v[40:43]
	s_min_u32 s14, s17, 12
	s_lshl_b32 s14, s14, 7
	s_waitcnt lgkmcnt(4)
	v_mfma_f32_16x16x32_bf16 v[36:39], v[108:111], v[160:163], v[36:39]
	s_waitcnt vmcnt(4)
	ds_write_b128 v131, v[72:75] offset:39168
	s_waitcnt lgkmcnt(4)
	v_mfma_f32_16x16x32_bf16 v[32:35], v[108:111], v[164:167], v[32:35]
	v_mfma_f32_16x16x32_bf16 v[28:31], v[112:115], v[88:91], v[28:31]
	s_waitcnt vmcnt(3)
	ds_write_b128 v131, v[60:63] offset:49536
	v_mfma_f32_16x16x32_bf16 v[24:27], v[112:115], v[156:159], v[24:27]
	v_mfma_f32_16x16x32_bf16 v[20:23], v[112:115], v[160:163], v[20:23]
	s_waitcnt vmcnt(2)
	ds_write_b128 v131, v[56:59] offset:51584
	v_mfma_f32_16x16x32_bf16 v[16:19], v[112:115], v[164:167], v[16:19]
	v_mfma_f32_16x16x32_bf16 v[12:15], v[148:151], v[88:91], v[12:15]
	s_waitcnt vmcnt(1)
	ds_write_b128 v131, v[52:55] offset:53632
	v_mfma_f32_16x16x32_bf16 v[8:11], v[148:151], v[156:159], v[8:11]
	s_add_u32 s64, s24, s14
	s_addc_u32 s65, s25, 0
	s_add_u32 s66, s26, s14
	v_mfma_f32_16x16x32_bf16 v[4:7], v[148:151], v[160:163], v[4:7]
	s_waitcnt vmcnt(0)
	ds_write_b128 v131, v[48:51] offset:55680
	s_addc_u32 s67, s27, 0
	v_mfma_f32_16x16x32_bf16 v[0:3], v[148:151], v[164:167], v[0:3]
	v_mfma_f32_16x16x32_bf16 v[88:91], v[152:155], v[88:91], v[84:87]
	v_mfma_f32_16x16x32_bf16 v[96:99], v[152:155], v[156:159], v[96:99]
	v_mfma_f32_16x16x32_bf16 v[92:95], v[152:155], v[160:163], v[92:95]
	v_mfma_f32_16x16x32_bf16 v[132:135], v[152:155], v[164:167], v[80:83]
	s_waitcnt lgkmcnt(0)
	s_barrier
	s_nop 0
	ds_read_b128 v[80:83], v119 offset:33024
	ds_read_b128 v[100:103], v130 offset:49536
	ds_read_b128 v[112:115], v130 offset:50560
	ds_read_b128 v[136:139], v130 offset:51584
	ds_read_b128 v[140:143], v130 offset:52608
	s_waitcnt lgkmcnt(3)
	v_mfma_f32_16x16x32_bf16 v[44:47], v[80:83], v[100:103], v[44:47]
	s_waitcnt lgkmcnt(2)
	v_mfma_f32_16x16x32_bf16 v[40:43], v[80:83], v[112:115], v[40:43]
	s_waitcnt lgkmcnt(1)
	v_mfma_f32_16x16x32_bf16 v[36:39], v[80:83], v[136:139], v[36:39]
	s_waitcnt lgkmcnt(0)
	v_mfma_f32_16x16x32_bf16 v[32:35], v[80:83], v[140:143], v[32:35]
	ds_read_b128 v[80:83], v119 offset:34048
	s_waitcnt lgkmcnt(0)
	v_mfma_f32_16x16x32_bf16 v[28:31], v[80:83], v[100:103], v[28:31]
	ds_read_b128 v[104:107], v119 offset:35072
	v_mfma_f32_16x16x32_bf16 v[24:27], v[80:83], v[112:115], v[24:27]
	ds_read_b128 v[144:147], v119 offset:36096
	v_mfma_f32_16x16x32_bf16 v[20:23], v[80:83], v[136:139], v[20:23]
	ds_read_b128 v[148:151], v119 offset:41280
	v_mfma_f32_16x16x32_bf16 v[16:19], v[80:83], v[140:143], v[16:19]
	ds_read_b128 v[152:155], v119 offset:42304
	s_waitcnt lgkmcnt(3)
	v_mfma_f32_16x16x32_bf16 v[12:15], v[104:107], v[100:103], v[12:15]
	ds_read_b128 v[156:159], v119 offset:43328
	v_mfma_f32_16x16x32_bf16 v[8:11], v[104:107], v[112:115], v[8:11]
	ds_read_b128 v[80:83], v119 offset:44352
	v_mfma_f32_16x16x32_bf16 v[4:7], v[104:107], v[136:139], v[4:7]
	ds_read_b128 v[84:87], v130 offset:57792
	v_mfma_f32_16x16x32_bf16 v[0:3], v[104:107], v[140:143], v[0:3]
	ds_read_b128 v[104:107], v130 offset:58816
	s_waitcnt lgkmcnt(6)
	v_mfma_f32_16x16x32_bf16 v[100:103], v[144:147], v[100:103], v[88:91]
	ds_read_b128 v[108:111], v130 offset:59840
	v_mfma_f32_16x16x32_bf16 v[96:99], v[144:147], v[112:115], v[96:99]
	ds_read_b128 v[112:115], v130 offset:60864
	v_mfma_f32_16x16x32_bf16 v[92:95], v[144:147], v[136:139], v[92:95]
	v_mfma_f32_16x16x32_bf16 v[88:91], v[144:147], v[140:143], v[132:135]
	s_waitcnt lgkmcnt(3)
	v_mfma_f32_16x16x32_bf16 v[44:47], v[148:151], v[84:87], v[44:47]
	s_waitcnt lgkmcnt(2)
	v_mfma_f32_16x16x32_bf16 v[40:43], v[148:151], v[104:107], v[40:43]
	s_waitcnt lgkmcnt(1)
	v_mfma_f32_16x16x32_bf16 v[36:39], v[148:151], v[108:111], v[36:39]
	s_waitcnt lgkmcnt(0)
	v_mfma_f32_16x16x32_bf16 v[32:35], v[148:151], v[112:115], v[32:35]
	v_mfma_f32_16x16x32_bf16 v[28:31], v[152:155], v[84:87], v[28:31]
	v_mfma_f32_16x16x32_bf16 v[24:27], v[152:155], v[104:107], v[24:27]
	v_mfma_f32_16x16x32_bf16 v[20:23], v[152:155], v[108:111], v[20:23]
	v_mfma_f32_16x16x32_bf16 v[16:19], v[152:155], v[112:115], v[16:19]
	v_mfma_f32_16x16x32_bf16 v[12:15], v[156:159], v[84:87], v[12:15]
	v_mfma_f32_16x16x32_bf16 v[8:11], v[156:159], v[104:107], v[8:11]
	v_mfma_f32_16x16x32_bf16 v[4:7], v[156:159], v[108:111], v[4:7]
	v_mfma_f32_16x16x32_bf16 v[0:3], v[156:159], v[112:115], v[0:3]
	s_cmp_lt_u32 s17, 14
	s_mov_b32 s14, s17
	s_waitcnt lgkmcnt(0)
	s_barrier
; #define MFMA16(a, b, c) __builtin_amdgcn_mfma_f32_16x16x32_bf16(a, b, c, 0, 0, 0)
; template <int WM, int WN, typename SrcF, typename PostF>
; __device__ __forceinline__ void gemm_stream(const int nsteps, SrcF src, PostF post, f32x4 (&acc)[WM][WN], char* smem) {
;     ...
;   acc[3][0] = MFMA16(pa, pb0, acc[3][0]);
;   acc[3][1] = MFMA16(pa, pb1, acc[3][1]);
;   acc[3][2] = MFMA16(pa, pb2, acc[3][2]);
;   acc[3][3] = MFMA16(pa, pb3, acc[3][3]);
; __device__ void phase_inproj(const Params& p, int layer, char* smem) {
;     ...
;     const int row0 = rb * 128 + wr * 64, col0 = cb * 128 + wc * 64;
;     if (cb >= 12 && cb <= 16) {
; #pragma unroll
;       for (int m = 0; m < 4; ++m)
; #pragma unroll
;         for (int j = 0; j < 4; ++j) {
;           int row = row0 + m * 16 + fq * 4 + j;
;           int pos = row & (SEQ - 1);
; #pragma unroll
;           for (int n = 0; n < 2; ++n) {
;             float2 cs2 = RT[pos * 32 + n * 16 + fr];
;             float c = cs2.x, s = cs2.y;
;             float x1 = acc[m][n][j], x2 = acc[m][n + 2][j];
;             acc[m][n][j] = x1 * c - x2 * s;
;             acc[m][n + 2][j] = x2 * c + x1 * s;
;           }
;         }
	s_waitcnt vmcnt(3)
	v_mfma_f32_16x16x32_bf16 v[60:63], v[80:83], v[84:87], v[100:103]
	s_add_i32 s14, s22, -12
	s_cmp_gt_u32 s14, 4
	s_waitcnt vmcnt(2)
	v_mfma_f32_16x16x32_bf16 v[56:59], v[80:83], v[104:107], v[96:99]
	s_waitcnt vmcnt(1)
	v_mfma_f32_16x16x32_bf16 v[52:55], v[80:83], v[108:111], v[92:95]
	s_waitcnt vmcnt(0)
	v_mfma_f32_16x16x32_bf16 v[48:51], v[80:83], v[112:115], v[88:91]
	s_cbranch_scc1 .LBB0_428
	v_lshl_add_u32 v64, s16, 7, v126
	v_and_or_b32 v64, v64, s43, v127
	v_lshl_or_b32 v116, v64, 8, v128
	v_lshl_add_u64 v[92:93], s[12:13], 0, v[116:117]
	v_add_co_u32_e32 v94, vcc, s48, v92
	global_load_dwordx2 v[68:69], v116, s[12:13]
	global_load_dwordx2 v[64:65], v116, s[12:13] offset:256
	global_load_dwordx2 v[66:67], v116, s[12:13] offset:384
	global_load_dwordx2 v[72:73], v116, s[12:13] offset:512
	global_load_dwordx2 v[76:77], v116, s[12:13] offset:128
	global_load_dwordx2 v[74:75], v116, s[12:13] offset:640
	global_load_dwordx2 v[70:71], v116, s[12:13] offset:768
	global_load_dwordx2 v[78:79], v116, s[12:13] offset:896
	v_addc_co_u32_e32 v95, vcc, 0, v93, vcc
	v_add_co_u32_e32 v96, vcc, s49, v92
	s_waitcnt vmcnt(7)
	v_mov_b32_e32 v124, v68
	v_addc_co_u32_e32 v97, vcc, 0, v93, vcc
	global_load_dwordx2 v[82:83], v[96:97], off offset:-4096
	global_load_dwordx2 v[80:81], v[94:95], off offset:256
	global_load_dwordx2 v[84:85], v[94:95], off offset:384
	global_load_dwordx2 v[88:89], v[94:95], off offset:512
	global_load_dwordx2 v[98:99], v[94:95], off offset:128
	global_load_dwordx2 v[90:91], v[94:95], off offset:640
	global_load_dwordx2 v[86:87], v[94:95], off offset:768
	s_waitcnt vmcnt(13)
	v_mov_b32_e32 v125, v64
	v_mov_b32_e32 v64, v69
	s_waitcnt vmcnt(10)
	v_mov_b32_e32 v68, v76
	v_mul_f32_e32 v76, v46, v72
	v_mul_f32_e32 v130, v38, v73
	v_mul_f32_e32 v72, v38, v72
	v_mul_f32_e32 v132, v46, v73
	s_waitcnt vmcnt(9)
	v_mul_f32_e32 v134, v42, v74
	v_mul_f32_e32 v138, v42, v75
	v_mov_b32_e32 v38, v47
	v_mov_b32_e32 v46, v39
	v_mov_b32_e32 v42, v35
	v_add_co_u32_e32 v92, vcc, s50, v92
	v_mov_b32_e32 v69, v66
	v_mov_b32_e32 v66, v77
	v_mul_f32_e32 v136, v34, v75
	v_mul_f32_e32 v74, v34, v74
	v_mov_b32_e32 v34, v43
	v_pk_mul_f32 v[140:141], v[44:45], v[64:65]
	v_pk_mul_f32 v[64:65], v[36:37], v[64:65]
	s_waitcnt vmcnt(8)
	v_pk_mul_f32 v[38:39], v[38:39], v[70:71]
	v_pk_mul_f32 v[46:47], v[46:47], v[70:71]
	s_waitcnt vmcnt(7)
	v_pk_mul_f32 v[42:43], v[42:43], v[78:79]
	v_addc_co_u32_e32 v93, vcc, 0, v93, vcc
	v_pk_mul_f32 v[142:143], v[40:41], v[66:67]
	v_pk_mul_f32 v[66:67], v[32:33], v[66:67]
	v_pk_mul_f32 v[34:35], v[34:35], v[78:79]
	v_mov_b32_e32 v77, v38
	v_mov_b32_e32 v131, v39
	v_pk_fma_f32 v[44:45], v[44:45], v[124:125], v[64:65] neg_lo:[0,0,1] neg_hi:[0,0,1]
	v_mov_b32_e32 v73, v46
	v_mov_b32_e32 v133, v47
	v_mov_b32_e32 v75, v42
	v_mov_b32_e32 v139, v43
	global_load_dwordx2 v[94:95], v[94:95], off offset:896
	s_nop 0
	global_load_dwordx2 v[100:101], v[96:97], off
	global_load_dwordx2 v[102:103], v[96:97], off offset:256
	global_load_dwordx2 v[104:105], v[96:97], off offset:384
	global_load_dwordx2 v[106:107], v[96:97], off offset:128
	global_load_dwordx2 v[108:109], v[96:97], off offset:512
	global_load_dwordx2 v[110:111], v[96:97], off offset:640
	global_load_dwordx2 v[112:113], v[96:97], off offset:768
	s_nop 0
	global_load_dwordx2 v[96:97], v[96:97], off offset:896
	s_nop 0
	global_load_dwordx2 v[114:115], v[92:93], off offset:640
	global_load_dwordx2 v[120:121], v[92:93], off offset:768
	global_load_dwordx2 v[122:123], v[92:93], off offset:896
	v_mov_b32_e32 v135, v34
	v_mov_b32_e32 v137, v35
	v_pk_fma_f32 v[40:41], v[40:41], v[68:69], v[66:67] neg_lo:[0,0,1] neg_hi:[0,0,1]
	v_pk_fma_f32 v[32:33], v[32:33], v[68:69], v[142:143]
	v_pk_add_f32 v[46:47], v[76:77], v[130:131] neg_lo:[0,1] neg_hi:[0,1]
	v_pk_add_f32 v[38:39], v[72:73], v[132:133]
	v_pk_add_f32 v[34:35], v[74:75], v[138:139]
	global_load_dwordx2 v[74:75], v[92:93], off
	global_load_dwordx2 v[76:77], v[92:93], off offset:256
	v_pk_fma_f32 v[36:37], v[36:37], v[124:125], v[140:141]
	v_pk_add_f32 v[42:43], v[134:135], v[136:137] neg_lo:[0,1] neg_hi:[0,1]
	s_waitcnt vmcnt(20)
	v_mov_b32_e32 v64, v82
	s_waitcnt vmcnt(19)
	v_mov_b32_e32 v65, v80
	v_mov_b32_e32 v80, v83
	s_waitcnt vmcnt(18)
	v_mov_b32_e32 v71, v84
	s_waitcnt vmcnt(16)
	v_mov_b32_e32 v84, v99
	v_pk_mul_f32 v[66:67], v[28:29], v[80:81]
	v_pk_mul_f32 v[68:69], v[20:21], v[80:81]
	v_pk_mul_f32 v[72:73], v[24:25], v[84:85]
	v_pk_mul_f32 v[78:79], v[16:17], v[84:85]
	global_load_dwordx2 v[80:81], v[92:93], off offset:384
	global_load_dwordx2 v[82:83], v[92:93], off offset:512
	global_load_dwordx2 v[84:85], v[92:93], off offset:128
	v_mov_b32_e32 v70, v98
	v_mul_f32_e32 v92, v30, v88
	v_mul_f32_e32 v98, v22, v89
	v_mul_f32_e32 v88, v22, v88
	v_mul_f32_e32 v124, v30, v89
	s_waitcnt vmcnt(18)
; __device__ void phase_inproj(const Params& p, int layer, char* smem) {
;     ...
;     if (cb >= 12 && cb <= 16) {
; #pragma unroll
;       for (int m = 0; m < 4; ++m)
; #pragma unroll
;         for (int j = 0; j < 4; ++j) {
;           int row = row0 + m * 16 + fq * 4 + j;
;           int pos = row & (SEQ - 1);
; #pragma unroll
;           for (int n = 0; n < 2; ++n) {
;             float2 cs2 = RT[pos * 32 + n * 16 + fr];
;             float c = cs2.x, s = cs2.y;
;             float x1 = acc[m][n][j], x2 = acc[m][n + 2][j];
;             acc[m][n][j] = x1 * c - x2 * s;
;             acc[m][n + 2][j] = x2 * c + x1 * s;
;           }
;         }
	v_mul_f32_e32 v130, v26, v90
	v_mul_f32_e32 v132, v18, v91
	v_mul_f32_e32 v90, v18, v90
	v_mul_f32_e32 v134, v26, v91
	v_mov_b32_e32 v22, v31
	v_mov_b32_e32 v30, v23
	v_mov_b32_e32 v18, v27
	v_mov_b32_e32 v26, v19
	s_waitcnt vmcnt(17)
	v_pk_mul_f32 v[136:137], v[22:23], v[86:87]
	v_pk_mul_f32 v[22:23], v[30:31], v[86:87]
	v_mov_b32_e32 v93, v136
	v_mov_b32_e32 v89, v22
	v_mov_b32_e32 v125, v23
	v_mov_b32_e32 v99, v137
	v_pk_add_f32 v[22:23], v[88:89], v[124:125]
	v_pk_fma_f32 v[24:25], v[24:25], v[70:71], v[78:79] neg_lo:[0,0,1] neg_hi:[0,0,1]
	v_pk_fma_f32 v[16:17], v[16:17], v[70:71], v[72:73]
	s_waitcnt vmcnt(16)
	v_pk_mul_f32 v[30:31], v[18:19], v[94:95]
	v_pk_mul_f32 v[18:19], v[26:27], v[94:95]
	s_waitcnt vmcnt(14)
	v_mov_b32_e32 v27, v102
	v_mov_b32_e32 v91, v18
	v_mov_b32_e32 v135, v19
	v_pk_add_f32 v[18:19], v[90:91], v[134:135]
	v_mov_b32_e32 v102, v101
	s_waitcnt vmcnt(13)
	v_mov_b32_e32 v71, v104
	s_waitcnt vmcnt(12)
	v_mov_b32_e32 v104, v107
	s_waitcnt vmcnt(11)
	v_mul_f32_e32 v88, v6, v109
	v_mul_f32_e32 v90, v6, v108
	v_mov_b32_e32 v6, v15
	v_pk_fma_f32 v[28:29], v[28:29], v[64:65], v[68:69] neg_lo:[0,0,1] neg_hi:[0,0,1]
	v_pk_add_f32 v[68:69], v[92:93], v[98:99] neg_lo:[0,1] neg_hi:[0,1]
	v_pk_fma_f32 v[20:21], v[20:21], v[64:65], v[66:67]
	v_mov_b32_e32 v26, v100
	v_pk_mul_f32 v[64:65], v[12:13], v[102:103]
	v_pk_mul_f32 v[66:67], v[4:5], v[102:103]
	v_mov_b32_e32 v70, v106
	v_pk_mul_f32 v[72:73], v[8:9], v[104:105]
	v_pk_mul_f32 v[78:79], v[0:1], v[104:105]
	v_mul_f32_e32 v86, v14, v108
	v_mul_f32_e32 v92, v14, v109
	s_waitcnt vmcnt(10)
	v_mul_f32_e32 v94, v10, v110
	v_mul_f32_e32 v98, v2, v111
	v_mul_f32_e32 v100, v2, v110
	v_mul_f32_e32 v102, v10, v111
	s_waitcnt vmcnt(9)
	v_pk_mul_f32 v[104:105], v[6:7], v[112:113]
	v_mov_b32_e32 v14, v7
	v_mov_b32_e32 v2, v11
	v_mov_b32_e32 v10, v3
	v_mov_b32_e32 v87, v104
	v_mov_b32_e32 v89, v105
	v_pk_mul_f32 v[6:7], v[14:15], v[112:113]
	s_waitcnt vmcnt(8)
	v_pk_mul_f32 v[14:15], v[2:3], v[96:97]
	v_pk_fma_f32 v[8:9], v[8:9], v[70:71], v[78:79] neg_lo:[0,0,1] neg_hi:[0,0,1]
	v_pk_mul_f32 v[2:3], v[10:11], v[96:97]
	v_pk_fma_f32 v[0:1], v[0:1], v[70:71], v[72:73]
	s_waitcnt vmcnt(3)
	v_mov_b32_e32 v11, v76
	v_mov_b32_e32 v76, v75
	v_pk_fma_f32 v[12:13], v[12:13], v[26:27], v[66:67] neg_lo:[0,0,1] neg_hi:[0,0,1]
	v_pk_add_f32 v[66:67], v[86:87], v[88:89] neg_lo:[0,1] neg_hi:[0,1]
	v_mov_b32_e32 v91, v6
	v_mov_b32_e32 v93, v7
	v_pk_fma_f32 v[4:5], v[4:5], v[26:27], v[64:65]
	v_mov_b32_e32 v10, v74
	v_pk_mul_f32 v[26:27], v[60:61], v[76:77]
	v_pk_mul_f32 v[64:65], v[52:53], v[76:77]
	v_mul_f32_e32 v86, v50, v115
	v_mul_f32_e32 v88, v50, v114
	v_mov_b32_e32 v50, v59
	v_pk_add_f32 v[6:7], v[90:91], v[92:93]
	v_mul_f32_e32 v90, v58, v115
	v_pk_fma_f32 v[60:61], v[60:61], v[10:11], v[64:65] neg_lo:[0,0,1] neg_hi:[0,0,1]
	v_pk_fma_f32 v[52:53], v[52:53], v[10:11], v[26:27]
	s_waitcnt vmcnt(2)
	v_mov_b32_e32 v71, v80
	s_waitcnt vmcnt(1)
	v_mul_f32_e32 v78, v54, v83
	s_waitcnt vmcnt(0)
	v_mov_b32_e32 v80, v85
	v_pk_mul_f32 v[72:73], v[56:57], v[80:81]
	v_pk_mul_f32 v[74:75], v[48:49], v[80:81]
	v_mul_f32_e32 v80, v54, v82
	v_mov_b32_e32 v54, v63
	v_mov_b32_e32 v70, v84
	v_mul_f32_e32 v76, v62, v82
	v_mul_f32_e32 v82, v62, v83
	v_mul_f32_e32 v84, v58, v114
	v_pk_mul_f32 v[92:93], v[54:55], v[120:121]
	v_mov_b32_e32 v62, v55
	v_pk_mul_f32 v[10:11], v[50:51], v[122:123]
	v_mov_b32_e32 v58, v51
	v_mov_b32_e32 v131, v30
	v_mov_b32_e32 v133, v31
	v_mov_b32_e32 v95, v14
	v_mov_b32_e32 v99, v15
	v_mov_b32_e32 v77, v92
	v_mov_b32_e32 v79, v93
	v_pk_mul_f32 v[54:55], v[62:63], v[120:121]
	v_mov_b32_e32 v85, v10
	v_mov_b32_e32 v87, v11
	v_pk_mul_f32 v[26:27], v[58:59], v[122:123]
	v_pk_add_f32 v[30:31], v[130:131], v[132:133] neg_lo:[0,1] neg_hi:[0,1]
	v_pk_add_f32 v[14:15], v[94:95], v[98:99] neg_lo:[0,1] neg_hi:[0,1]
	v_mov_b32_e32 v101, v2
	v_mov_b32_e32 v103, v3
	v_pk_add_f32 v[64:65], v[76:77], v[78:79] neg_lo:[0,1] neg_hi:[0,1]
	v_mov_b32_e32 v81, v54
	v_mov_b32_e32 v83, v55
	v_pk_add_f32 v[10:11], v[84:85], v[86:87] neg_lo:[0,1] neg_hi:[0,1]
	v_mov_b32_e32 v89, v26
	v_mov_b32_e32 v91, v27
	v_pk_add_f32 v[2:3], v[100:101], v[102:103]
	v_pk_add_f32 v[54:55], v[80:81], v[82:83]
	v_pk_fma_f32 v[56:57], v[56:57], v[70:71], v[74:75] neg_lo:[0,0,1] neg_hi:[0,0,1]
	v_pk_fma_f32 v[48:49], v[48:49], v[70:71], v[72:73]
	v_pk_add_f32 v[50:51], v[88:89], v[90:91]
	v_mov_b32_e32 v58, v10
	v_mov_b32_e32 v59, v11
	v_mov_b32_e32 v62, v64
	v_mov_b32_e32 v63, v65
	v_mov_b32_e32 v10, v14
	v_mov_b32_e32 v11, v15
	v_mov_b32_e32 v14, v66
	v_mov_b32_e32 v15, v67
	v_mov_b32_e32 v26, v30
	v_mov_b32_e32 v27, v31
	v_mov_b32_e32 v30, v68
	v_mov_b32_e32 v31, v69

; #define MFMA16(a, b, c) __builtin_amdgcn_mfma_f32_16x16x32_bf16(a, b, c, 0, 0, 0)
; #define SGB_(mask_, n_) __builtin_amdgcn_sched_group_barrier(mask_, n_, 0)
; template <int WM, int WN> ...
;   static_assert(WM == 4 && WN == 4, "128x128 block tile");
;   constexpr int APAN = 128 * 64 + PPAD, BPAN = 128 * 64 + PPAD;
;   bf16x8 fa0[4], fb0[4], fa1[4], fb1[4];
; #pragma unroll
;   for (int n = 0; n < 4; ++n) fb0[n] = LDSF(cur + boff + n * 1024);
; #pragma unroll
;   for (int m = 0; m < 4; ++m) fa0[m] = LDSF(cur + aoff + m * 1024);
;   acc[3][0] = MFMA16(pa, pb0, acc[3][0]);
;   acc[3][1] = MFMA16(pa, pb1, acc[3][1]);
;   acc[3][2] = MFMA16(pa, pb2, acc[3][2]);
;   acc[3][3] = MFMA16(pa, pb3, acc[3][3]);
; #pragma unroll
;   for (int n = 0; n < 4; ++n) acc[0][n] = MFMA16(fa0[0], fb0[n], acc[0][n]);
; #pragma unroll
;   for (int m = 0; m < 4; ++m) fa1[m] = LDSF(cur + aoff + APAN + m * 1024);
; #pragma unroll
;   for (int n = 0; n < 4; ++n) acc[1][n] = MFMA16(fa0[1], fb0[n], acc[1][n]);
; #pragma unroll
;   for (int n = 0; n < 4; ++n) fb1[n] = LDSF(cur + boff + BPAN + n * 1024);
; #pragma unroll
;   for (int n = 0; n < 4; ++n) acc[2][n] = MFMA16(fa0[2], fb0[n], acc[2][n]);
;   *reinterpret_cast<uint4*>(nxt + wao) = a0;
;   *reinterpret_cast<uint4*>(nxt + wao + 32 * 64) = a1;
; #pragma unroll
;   for (int n = 0; n < 4; ++n) acc[3][n] = MFMA16(fa0[3], fb0[n], acc[3][n]);
;   *reinterpret_cast<uint4*>(nxt + wao + 64 * 64) = a2;
;   *reinterpret_cast<uint4*>(nxt + wao + 96 * 64) = a3;
; #pragma unroll
;   for (int n = 0; n < 4; ++n) acc[0][n] = MFMA16(fa1[0], fb1[n], acc[0][n]);
;   *reinterpret_cast<uint4*>(nxt + wbo) = b0;
;   *reinterpret_cast<uint4*>(nxt + wbo + 32 * 64) = b1;
; #pragma unroll
;   for (int n = 0; n < 4; ++n) acc[1][n] = MFMA16(fa1[1], fb1[n], acc[1][n]);
;   *reinterpret_cast<uint4*>(nxt + wbo + 64 * 64) = b2;
;   *reinterpret_cast<uint4*>(nxt + wbo + 96 * 64) = b3;
; #pragma unroll
;   for (int n = 0; n < 4; ++n) acc[2][n] = MFMA16(fa1[2], fb1[n], acc[2][n]);
;   pa = fa1[3];
;   pb0 = fb1[0]; pb1 = fb1[1]; pb2 = fb1[2]; pb3 = fb1[3];
;   SGB_(0x100, 5);
;   SGB_(0x008, 4);
; #pragma unroll
;   for (int i_ = 0; i_ < 11; ++i_) { SGB_(0x008, 1); SGB_(0x100, 1); }
; #pragma unroll
;   for (int i_ = 0; i_ < 8; ++i_) { SGB_(0x008, 2); SGB_(0x200, 1); SGB_(0x020, 1); }
;   SGB_(0x008, 1);
; }
.LBB0_639:
	s_add_i32 s44, s13, 2
	s_add_i32 s13, s13, 4
	s_min_u32 s13, s13, 15
	s_lshl_b32 s13, s13, 7
	s_add_u32 s92, s16, s13
	s_addc_u32 s93, s17, 0
	s_add_u32 s94, s20, s13
	s_addc_u32 s95, s21, 0
	ds_read_b128 v[144:147], v124
	ds_read_b128 v[128:131], v125 offset:16512
	ds_read_b128 v[132:135], v125 offset:17536
	ds_read_b128 v[136:139], v125 offset:18560
	ds_read_b128 v[140:143], v125 offset:19584
	v_mfma_f32_16x16x32_bf16 v[64:67], v[48:51], v[64:67], v[92:95]
	v_mfma_f32_16x16x32_bf16 v[88:91], v[48:51], v[104:107], v[88:91]
	s_waitcnt vmcnt(7)
	ds_write_b128 v126, v[32:35] offset:33024
	global_load_dwordx4 v[32:35], v116, s[92:93]
	s_add_u32 s48, s16, s13
	s_addc_u32 s49, s17, 0
	v_mfma_f32_16x16x32_bf16 v[80:83], v[48:51], v[112:115], v[80:83]
	v_mfma_f32_16x16x32_bf16 v[48:51], v[48:51], v[108:111], v[56:59]
	s_waitcnt lgkmcnt(4)
	v_mfma_f32_16x16x32_bf16 v[56:59], v[144:147], v[128:131], v[100:103]
	ds_read_b128 v[92:95], v124 offset:1024
	s_waitcnt lgkmcnt(4)
	v_mfma_f32_16x16x32_bf16 v[96:99], v[144:147], v[132:135], v[96:99]
	s_waitcnt vmcnt(7)
	ds_write_b128 v126, v[20:23] offset:35072
	global_load_dwordx4 v[20:23], v118, s[92:93]
	ds_read_b128 v[100:103], v124 offset:2048
	s_waitcnt lgkmcnt(5)
	v_mfma_f32_16x16x32_bf16 v[84:87], v[144:147], v[136:139], v[84:87]
	ds_read_b128 v[104:107], v124 offset:3072
	s_waitcnt lgkmcnt(5)
	v_mfma_f32_16x16x32_bf16 v[76:79], v[144:147], v[140:143], v[76:79]
	ds_read_b128 v[108:111], v124 offset:8256
	s_waitcnt lgkmcnt(4)
	v_mfma_f32_16x16x32_bf16 v[72:75], v[92:95], v[128:131], v[72:75]
	ds_read_b128 v[112:115], v124 offset:9280
	v_mfma_f32_16x16x32_bf16 v[68:71], v[92:95], v[132:135], v[68:71]
	ds_read_b128 v[144:147], v124 offset:10304
	v_mfma_f32_16x16x32_bf16 v[60:63], v[92:95], v[136:139], v[60:63]
	s_waitcnt vmcnt(7)
	ds_write_b128 v126, v[16:19] offset:37120
	global_load_dwordx4 v[16:19], v120, s[92:93]
	ds_read_b128 v[148:151], v124 offset:11328
	v_mfma_f32_16x16x32_bf16 v[52:55], v[92:95], v[140:143], v[52:55]
	ds_read_b128 v[92:95], v125 offset:24768
	s_waitcnt lgkmcnt(7)
	v_mfma_f32_16x16x32_bf16 v[44:47], v[100:103], v[128:131], v[44:47]
	ds_read_b128 v[152:155], v125 offset:25792
	v_mfma_f32_16x16x32_bf16 v[40:43], v[100:103], v[132:135], v[40:43]
	ds_read_b128 v[156:159], v125 offset:26816
	v_mfma_f32_16x16x32_bf16 v[36:39], v[100:103], v[136:139], v[36:39]
	s_waitcnt vmcnt(7)
	ds_write_b128 v126, v[24:27] offset:39168
	global_load_dwordx4 v[24:27], v122, s[92:93]
	ds_read_b128 v[160:163], v125 offset:27840
	v_mfma_f32_16x16x32_bf16 v[28:31], v[100:103], v[140:143], v[28:31]
	s_waitcnt lgkmcnt(10)
	v_mfma_f32_16x16x32_bf16 v[64:67], v[104:107], v[128:131], v[64:67]
	v_mfma_f32_16x16x32_bf16 v[88:91], v[104:107], v[132:135], v[88:91]
	v_mfma_f32_16x16x32_bf16 v[80:83], v[104:107], v[136:139], v[80:83]
	v_mfma_f32_16x16x32_bf16 v[48:51], v[104:107], v[140:143], v[48:51]
	s_waitcnt vmcnt(7)
	ds_write_b128 v126, v[12:15] offset:49536
	global_load_dwordx4 v[12:15], v116, s[94:95]
	s_waitcnt lgkmcnt(5)
	v_mfma_f32_16x16x32_bf16 v[56:59], v[108:111], v[92:95], v[56:59]
	s_add_u32 s48, s20, s13
	s_addc_u32 s49, s21, 0
	s_waitcnt lgkmcnt(4)
	v_mfma_f32_16x16x32_bf16 v[96:99], v[108:111], v[152:155], v[96:99]
	s_min_u32 s13, s44, 12
	s_lshl_b32 s13, s13, 7
	s_waitcnt lgkmcnt(3)
	v_mfma_f32_16x16x32_bf16 v[84:87], v[108:111], v[156:159], v[84:87]
	s_waitcnt lgkmcnt(1)
	v_mfma_f32_16x16x32_bf16 v[76:79], v[108:111], v[160:163], v[76:79]
	s_waitcnt vmcnt(7)
	ds_write_b128 v126, v[8:11] offset:51584
	global_load_dwordx4 v[8:11], v118, s[94:95]
	v_mfma_f32_16x16x32_bf16 v[72:75], v[112:115], v[92:95], v[72:75]
	v_mfma_f32_16x16x32_bf16 v[68:71], v[112:115], v[152:155], v[68:71]
	v_mfma_f32_16x16x32_bf16 v[60:63], v[112:115], v[156:159], v[60:63]
	v_mfma_f32_16x16x32_bf16 v[52:55], v[112:115], v[160:163], v[52:55]
	v_mfma_f32_16x16x32_bf16 v[44:47], v[144:147], v[92:95], v[44:47]
	s_waitcnt vmcnt(7)
	ds_write_b128 v126, v[4:7] offset:53632
	global_load_dwordx4 v[4:7], v120, s[94:95]
	v_mfma_f32_16x16x32_bf16 v[40:43], v[144:147], v[152:155], v[40:43]
	s_add_u32 s48, s16, s13
	s_addc_u32 s49, s17, 0
	s_add_u32 s50, s20, s13
	v_mfma_f32_16x16x32_bf16 v[36:39], v[144:147], v[156:159], v[36:39]
	s_addc_u32 s51, s21, 0
	v_mfma_f32_16x16x32_bf16 v[28:31], v[144:147], v[160:163], v[28:31]
	v_mfma_f32_16x16x32_bf16 v[92:95], v[148:151], v[92:95], v[64:67]
	s_waitcnt vmcnt(7)
	ds_write_b128 v126, v[0:3] offset:55680
	global_load_dwordx4 v[0:3], v122, s[94:95]
	v_mfma_f32_16x16x32_bf16 v[88:91], v[148:151], v[152:155], v[88:91]
	v_mfma_f32_16x16x32_bf16 v[80:83], v[148:151], v[156:159], v[80:83]
	v_mfma_f32_16x16x32_bf16 v[100:103], v[148:151], v[160:163], v[48:51]
	s_waitcnt lgkmcnt(0)
	s_barrier
; template <int WM, int WN> ...
;   static_assert(WM == 4 && WN == 4, "128x128 block tile");
;   constexpr int APAN = 128 * 64 + PPAD, BPAN = 128 * 64 + PPAD;
;   bf16x8 fa0[4], fb0[4], fa1[4], fb1[4];
; #pragma unroll
;   for (int n = 0; n < 4; ++n) fb0[n] = LDSF(cur + boff + n * 1024);
; #pragma unroll
;   for (int m = 0; m < 4; ++m) fa0[m] = LDSF(cur + aoff + m * 1024);
;   acc[3][0] = MFMA16(pa, pb0, acc[3][0]);
;   acc[3][1] = MFMA16(pa, pb1, acc[3][1]);
;   acc[3][2] = MFMA16(pa, pb2, acc[3][2]);
;   acc[3][3] = MFMA16(pa, pb3, acc[3][3]);
; #pragma unroll
;   for (int n = 0; n < 4; ++n) acc[0][n] = MFMA16(fa0[0], fb0[n], acc[0][n]);
; #pragma unroll
;   for (int m = 0; m < 4; ++m) fa1[m] = LDSF(cur + aoff + APAN + m * 1024);
; #pragma unroll
;   for (int n = 0; n < 4; ++n) acc[1][n] = MFMA16(fa0[1], fb0[n], acc[1][n]);
; #pragma unroll
;   for (int n = 0; n < 4; ++n) fb1[n] = LDSF(cur + boff + BPAN + n * 1024);
; #pragma unroll
;   for (int n = 0; n < 4; ++n) acc[2][n] = MFMA16(fa0[2], fb0[n], acc[2][n]);
;   *reinterpret_cast<uint4*>(nxt + wao) = a0;
;   *reinterpret_cast<uint4*>(nxt + wao + 32 * 64) = a1;
; #pragma unroll
;   for (int n = 0; n < 4; ++n) acc[3][n] = MFMA16(fa0[3], fb0[n], acc[3][n]);
;   *reinterpret_cast<uint4*>(nxt + wao + 64 * 64) = a2;
;   *reinterpret_cast<uint4*>(nxt + wao + 96 * 64) = a3;
; #pragma unroll
;   for (int n = 0; n < 4; ++n) acc[0][n] = MFMA16(fa1[0], fb1[n], acc[0][n]);
;   *reinterpret_cast<uint4*>(nxt + wbo) = b0;
;   *reinterpret_cast<uint4*>(nxt + wbo + 32 * 64) = b1;
; #pragma unroll
;   for (int n = 0; n < 4; ++n) acc[1][n] = MFMA16(fa1[1], fb1[n], acc[1][n]);
;   *reinterpret_cast<uint4*>(nxt + wbo + 64 * 64) = b2;
;   *reinterpret_cast<uint4*>(nxt + wbo + 96 * 64) = b3;
; #pragma unroll
;   for (int n = 0; n < 4; ++n) acc[2][n] = MFMA16(fa1[2], fb1[n], acc[2][n]);
;   pa = fa1[3];
;   pb0 = fb1[0]; pb1 = fb1[1]; pb2 = fb1[2]; pb3 = fb1[3];
;   SGB_(0x100, 5);
;   SGB_(0x008, 4);
; #pragma unroll
;   for (int i_ = 0; i_ < 11; ++i_) { SGB_(0x008, 1); SGB_(0x100, 1); }
; #pragma unroll
;   for (int i_ = 0; i_ < 8; ++i_) { SGB_(0x008, 2); SGB_(0x200, 1); SGB_(0x020, 1); }
;   SGB_(0x008, 1);
; }
; template <int WM, int WN, typename SrcF, typename PostF>
; __device__ __forceinline__ void gemm_stream(const int nsteps, SrcF src, PostF post, f32x4 (&acc)[WM][WN], char* smem) {
;     ...
;     SB_;
;     post(kt);
	s_nop 0
	ds_read_b128 v[48:51], v124 offset:33024
	ds_read_b128 v[108:111], v125 offset:49536
	ds_read_b128 v[128:131], v125 offset:50560
	ds_read_b128 v[132:135], v125 offset:51584
	ds_read_b128 v[136:139], v125 offset:52608
	s_waitcnt lgkmcnt(3)
	v_mfma_f32_16x16x32_bf16 v[140:143], v[48:51], v[108:111], v[56:59]
	s_waitcnt lgkmcnt(2)
	v_mfma_f32_16x16x32_bf16 v[96:99], v[48:51], v[128:131], v[96:99]
	s_waitcnt vmcnt(7)
	ds_write_b128 v126, v[32:35]
	global_load_dwordx4 v[32:35], v116, s[48:49] offset:384
	s_waitcnt lgkmcnt(2)
	v_mfma_f32_16x16x32_bf16 v[84:87], v[48:51], v[132:135], v[84:87]
	s_waitcnt lgkmcnt(0)
	v_mfma_f32_16x16x32_bf16 v[76:79], v[48:51], v[136:139], v[76:79]
	ds_read_b128 v[48:51], v124 offset:34048
	s_waitcnt lgkmcnt(0)
	v_mfma_f32_16x16x32_bf16 v[72:75], v[48:51], v[108:111], v[72:75]
	s_waitcnt vmcnt(7)
	ds_write_b128 v126, v[20:23] offset:2048
	global_load_dwordx4 v[20:23], v118, s[48:49] offset:384
	ds_read_b128 v[56:59], v124 offset:35072
	v_mfma_f32_16x16x32_bf16 v[68:71], v[48:51], v[128:131], v[68:71]
	ds_read_b128 v[144:147], v124 offset:36096
	v_mfma_f32_16x16x32_bf16 v[60:63], v[48:51], v[132:135], v[60:63]
	ds_read_b128 v[148:151], v124 offset:41280
	v_mfma_f32_16x16x32_bf16 v[52:55], v[48:51], v[136:139], v[52:55]
	ds_read_b128 v[152:155], v124 offset:42304
	s_waitcnt lgkmcnt(3)
	v_mfma_f32_16x16x32_bf16 v[44:47], v[56:59], v[108:111], v[44:47]
	s_waitcnt vmcnt(7)
	ds_write_b128 v126, v[16:19] offset:4096
	global_load_dwordx4 v[16:19], v120, s[48:49] offset:384
	ds_read_b128 v[156:159], v124 offset:43328
	v_mfma_f32_16x16x32_bf16 v[40:43], v[56:59], v[128:131], v[40:43]
	ds_read_b128 v[48:51], v124 offset:44352
	v_mfma_f32_16x16x32_bf16 v[36:39], v[56:59], v[132:135], v[36:39]
	ds_read_b128 v[64:67], v125 offset:57792
	v_mfma_f32_16x16x32_bf16 v[28:31], v[56:59], v[136:139], v[28:31]
	s_waitcnt vmcnt(7)
	ds_write_b128 v126, v[24:27] offset:6144
	global_load_dwordx4 v[24:27], v122, s[48:49] offset:384
	ds_read_b128 v[104:107], v125 offset:58816
	s_waitcnt lgkmcnt(8)
	v_mfma_f32_16x16x32_bf16 v[92:95], v[144:147], v[108:111], v[92:95]
	ds_read_b128 v[112:115], v125 offset:59840
	v_mfma_f32_16x16x32_bf16 v[88:91], v[144:147], v[128:131], v[88:91]
	ds_read_b128 v[108:111], v125 offset:60864
	v_mfma_f32_16x16x32_bf16 v[80:83], v[144:147], v[132:135], v[80:83]
	v_mfma_f32_16x16x32_bf16 v[56:59], v[144:147], v[136:139], v[100:103]
	s_waitcnt vmcnt(7)
	ds_write_b128 v126, v[12:15] offset:16512
	global_load_dwordx4 v[12:15], v116, s[50:51] offset:384
	s_waitcnt lgkmcnt(5)
	v_mfma_f32_16x16x32_bf16 v[100:103], v[148:151], v[64:67], v[140:143]
	s_waitcnt lgkmcnt(3)
	v_mfma_f32_16x16x32_bf16 v[96:99], v[148:151], v[104:107], v[96:99]
	s_waitcnt lgkmcnt(2)
	v_mfma_f32_16x16x32_bf16 v[84:87], v[148:151], v[112:115], v[84:87]
	s_waitcnt vmcnt(7)
	ds_write_b128 v126, v[8:11] offset:18560
	global_load_dwordx4 v[8:11], v118, s[50:51] offset:384
	s_waitcnt lgkmcnt(2)
	v_mfma_f32_16x16x32_bf16 v[76:79], v[148:151], v[108:111], v[76:79]
	v_mfma_f32_16x16x32_bf16 v[72:75], v[152:155], v[64:67], v[72:75]
	v_mfma_f32_16x16x32_bf16 v[68:71], v[152:155], v[104:107], v[68:71]
	v_mfma_f32_16x16x32_bf16 v[60:63], v[152:155], v[112:115], v[60:63]
	s_waitcnt vmcnt(7)
	ds_write_b128 v126, v[4:7] offset:20608
	global_load_dwordx4 v[4:7], v120, s[50:51] offset:384
	v_mfma_f32_16x16x32_bf16 v[52:55], v[152:155], v[108:111], v[52:55]
	v_mfma_f32_16x16x32_bf16 v[44:47], v[156:159], v[64:67], v[44:47]
	v_mfma_f32_16x16x32_bf16 v[40:43], v[156:159], v[104:107], v[40:43]
	s_waitcnt vmcnt(7)
	ds_write_b128 v126, v[0:3] offset:22656
	global_load_dwordx4 v[0:3], v122, s[50:51] offset:384
	v_mfma_f32_16x16x32_bf16 v[36:39], v[156:159], v[112:115], v[36:39]
	v_mfma_f32_16x16x32_bf16 v[28:31], v[156:159], v[108:111], v[28:31]
	s_cmp_lt_u32 s44, 12
	s_mov_b32 s13, s44
	s_waitcnt lgkmcnt(0)
	s_barrier
	s_cbranch_scc1 .LBB0_639
	ds_read_b128 v[144:147], v124
	ds_read_b128 v[128:131], v125 offset:16512
	ds_read_b128 v[132:135], v125 offset:17536
	ds_read_b128 v[136:139], v125 offset:18560
	ds_read_b128 v[140:143], v125 offset:19584
	v_mfma_f32_16x16x32_bf16 v[64:67], v[48:51], v[64:67], v[92:95]
	s_add_i32 s44, s13, 2
	s_add_i32 s13, s13, 4
	s_min_u32 s13, s13, 15
	v_mfma_f32_16x16x32_bf16 v[88:91], v[48:51], v[104:107], v[88:91]
	s_lshl_b32 s13, s13, 7
	s_add_u32 s48, s16, s13
	s_addc_u32 s49, s17, 0
	v_mfma_f32_16x16x32_bf16 v[80:83], v[48:51], v[112:115], v[80:83]
	v_mfma_f32_16x16x32_bf16 v[48:51], v[48:51], v[108:111], v[56:59]
	s_waitcnt lgkmcnt(3)
	v_mfma_f32_16x16x32_bf16 v[56:59], v[144:147], v[128:131], v[100:103]
	ds_read_b128 v[92:95], v124 offset:1024
	s_waitcnt lgkmcnt(3)
	v_mfma_f32_16x16x32_bf16 v[96:99], v[144:147], v[132:135], v[96:99]
	ds_read_b128 v[100:103], v124 offset:2048
	s_waitcnt lgkmcnt(3)
	v_mfma_f32_16x16x32_bf16 v[84:87], v[144:147], v[136:139], v[84:87]
	ds_read_b128 v[104:107], v124 offset:3072
	s_waitcnt lgkmcnt(3)
	v_mfma_f32_16x16x32_bf16 v[76:79], v[144:147], v[140:143], v[76:79]
	ds_read_b128 v[108:111], v124 offset:8256
	s_waitcnt lgkmcnt(3)
	v_mfma_f32_16x16x32_bf16 v[72:75], v[92:95], v[128:131], v[72:75]
	ds_read_b128 v[112:115], v124 offset:9280
	v_mfma_f32_16x16x32_bf16 v[68:71], v[92:95], v[132:135], v[68:71]
	ds_read_b128 v[144:147], v124 offset:10304
	v_mfma_f32_16x16x32_bf16 v[60:63], v[92:95], v[136:139], v[60:63]
	ds_read_b128 v[148:151], v124 offset:11328
	v_mfma_f32_16x16x32_bf16 v[52:55], v[92:95], v[140:143], v[52:55]
	ds_read_b128 v[92:95], v125 offset:24768
	s_waitcnt lgkmcnt(6)
; #define MFMA16(a, b, c) __builtin_amdgcn_mfma_f32_16x16x32_bf16(a, b, c, 0, 0, 0)
; #define SGB_(mask_, n_) __builtin_amdgcn_sched_group_barrier(mask_, n_, 0)
; template <int WM, int WN> ...
;   static_assert(WM == 4 && WN == 4, "128x128 block tile");
;   constexpr int APAN = 128 * 64 + PPAD, BPAN = 128 * 64 + PPAD;
;   bf16x8 fa0[4], fb0[4], fa1[4], fb1[4];
; #pragma unroll
;   for (int n = 0; n < 4; ++n) fb0[n] = LDSF(cur + boff + n * 1024);
; #pragma unroll
;   for (int m = 0; m < 4; ++m) fa0[m] = LDSF(cur + aoff + m * 1024);
;   acc[3][0] = MFMA16(pa, pb0, acc[3][0]);
;   acc[3][1] = MFMA16(pa, pb1, acc[3][1]);
;   acc[3][2] = MFMA16(pa, pb2, acc[3][2]);
;   acc[3][3] = MFMA16(pa, pb3, acc[3][3]);
; #pragma unroll
;   for (int n = 0; n < 4; ++n) acc[0][n] = MFMA16(fa0[0], fb0[n], acc[0][n]);
; #pragma unroll
;   for (int m = 0; m < 4; ++m) fa1[m] = LDSF(cur + aoff + APAN + m * 1024);
; #pragma unroll
;   for (int n = 0; n < 4; ++n) acc[1][n] = MFMA16(fa0[1], fb0[n], acc[1][n]);
; #pragma unroll
;   for (int n = 0; n < 4; ++n) fb1[n] = LDSF(cur + boff + BPAN + n * 1024);
; #pragma unroll
;   for (int n = 0; n < 4; ++n) acc[2][n] = MFMA16(fa0[2], fb0[n], acc[2][n]);
;   *reinterpret_cast<uint4*>(nxt + wao) = a0;
;   *reinterpret_cast<uint4*>(nxt + wao + 32 * 64) = a1;
; #pragma unroll
;   for (int n = 0; n < 4; ++n) acc[3][n] = MFMA16(fa0[3], fb0[n], acc[3][n]);
;   *reinterpret_cast<uint4*>(nxt + wao + 64 * 64) = a2;
;   *reinterpret_cast<uint4*>(nxt + wao + 96 * 64) = a3;
; #pragma unroll
;   for (int n = 0; n < 4; ++n) acc[0][n] = MFMA16(fa1[0], fb1[n], acc[0][n]);
;   *reinterpret_cast<uint4*>(nxt + wbo) = b0;
;   *reinterpret_cast<uint4*>(nxt + wbo + 32 * 64) = b1;
; #pragma unroll
;   for (int n = 0; n < 4; ++n) acc[1][n] = MFMA16(fa1[1], fb1[n], acc[1][n]);
;   *reinterpret_cast<uint4*>(nxt + wbo + 64 * 64) = b2;
;   *reinterpret_cast<uint4*>(nxt + wbo + 96 * 64) = b3;
; #pragma unroll
;   for (int n = 0; n < 4; ++n) acc[2][n] = MFMA16(fa1[2], fb1[n], acc[2][n]);
;   pa = fa1[3];
;   pb0 = fb1[0]; pb1 = fb1[1]; pb2 = fb1[2]; pb3 = fb1[3];
;   SGB_(0x100, 5);
;   SGB_(0x008, 4);
; #pragma unroll
;   for (int i_ = 0; i_ < 11; ++i_) { SGB_(0x008, 1); SGB_(0x100, 1); }
; #pragma unroll
;   for (int i_ = 0; i_ < 8; ++i_) { SGB_(0x008, 2); SGB_(0x200, 1); SGB_(0x020, 1); }
;   SGB_(0x008, 1);
; }
	v_mfma_f32_16x16x32_bf16 v[44:47], v[100:103], v[128:131], v[44:47]
	ds_read_b128 v[152:155], v125 offset:25792
	v_mfma_f32_16x16x32_bf16 v[40:43], v[100:103], v[132:135], v[40:43]
	ds_read_b128 v[156:159], v125 offset:26816
	v_mfma_f32_16x16x32_bf16 v[36:39], v[100:103], v[136:139], v[36:39]
	ds_read_b128 v[160:163], v125 offset:27840
	v_mfma_f32_16x16x32_bf16 v[28:31], v[100:103], v[140:143], v[28:31]
	s_waitcnt lgkmcnt(8)
	v_mfma_f32_16x16x32_bf16 v[64:67], v[104:107], v[128:131], v[64:67]
	s_waitcnt vmcnt(7)
	ds_write_b128 v126, v[32:35] offset:33024
	v_mfma_f32_16x16x32_bf16 v[88:91], v[104:107], v[132:135], v[88:91]
	v_mfma_f32_16x16x32_bf16 v[80:83], v[104:107], v[136:139], v[80:83]
	s_waitcnt vmcnt(6)
	ds_write_b128 v126, v[20:23] offset:35072
	v_mfma_f32_16x16x32_bf16 v[48:51], v[104:107], v[140:143], v[48:51]
	s_waitcnt lgkmcnt(5)
	v_mfma_f32_16x16x32_bf16 v[56:59], v[108:111], v[92:95], v[56:59]
	s_waitcnt vmcnt(5)
	ds_write_b128 v126, v[16:19] offset:37120
	s_add_u32 s48, s20, s13
	s_addc_u32 s49, s21, 0
	s_waitcnt lgkmcnt(5)
	v_mfma_f32_16x16x32_bf16 v[96:99], v[108:111], v[152:155], v[96:99]
	s_min_u32 s13, s44, 12
	s_lshl_b32 s13, s13, 7
	s_waitcnt lgkmcnt(4)
	v_mfma_f32_16x16x32_bf16 v[84:87], v[108:111], v[156:159], v[84:87]
	s_waitcnt vmcnt(4)
	ds_write_b128 v126, v[24:27] offset:39168
	s_waitcnt lgkmcnt(4)
	v_mfma_f32_16x16x32_bf16 v[76:79], v[108:111], v[160:163], v[76:79]
	v_mfma_f32_16x16x32_bf16 v[72:75], v[112:115], v[92:95], v[72:75]
	s_waitcnt vmcnt(3)
	ds_write_b128 v126, v[12:15] offset:49536
	v_mfma_f32_16x16x32_bf16 v[68:71], v[112:115], v[152:155], v[68:71]
	v_mfma_f32_16x16x32_bf16 v[60:63], v[112:115], v[156:159], v[60:63]
	s_waitcnt vmcnt(2)
	ds_write_b128 v126, v[8:11] offset:51584
	v_mfma_f32_16x16x32_bf16 v[52:55], v[112:115], v[160:163], v[52:55]
	v_mfma_f32_16x16x32_bf16 v[44:47], v[144:147], v[92:95], v[44:47]
	s_waitcnt vmcnt(1)
	ds_write_b128 v126, v[4:7] offset:53632
	v_mfma_f32_16x16x32_bf16 v[40:43], v[144:147], v[152:155], v[40:43]
	s_add_u32 s48, s16, s13
	s_addc_u32 s49, s17, 0
	s_add_u32 s50, s20, s13
	v_mfma_f32_16x16x32_bf16 v[36:39], v[144:147], v[156:159], v[36:39]
	s_waitcnt vmcnt(0)
	ds_write_b128 v126, v[0:3] offset:55680
	s_addc_u32 s51, s21, 0
	v_mfma_f32_16x16x32_bf16 v[28:31], v[144:147], v[160:163], v[28:31]
	v_mfma_f32_16x16x32_bf16 v[92:95], v[148:151], v[92:95], v[64:67]
	v_mfma_f32_16x16x32_bf16 v[88:91], v[148:151], v[152:155], v[88:91]
	v_mfma_f32_16x16x32_bf16 v[80:83], v[148:151], v[156:159], v[80:83]
	v_mfma_f32_16x16x32_bf16 v[100:103], v[148:151], v[160:163], v[48:51]
	s_waitcnt lgkmcnt(0)
	s_barrier
	s_nop 0
	ds_read_b128 v[48:51], v124 offset:33024
	ds_read_b128 v[108:111], v125 offset:49536
	ds_read_b128 v[128:131], v125 offset:50560
	ds_read_b128 v[132:135], v125 offset:51584
	ds_read_b128 v[136:139], v125 offset:52608
	s_waitcnt lgkmcnt(3)
	v_mfma_f32_16x16x32_bf16 v[140:143], v[48:51], v[108:111], v[56:59]
	s_waitcnt lgkmcnt(2)
	v_mfma_f32_16x16x32_bf16 v[96:99], v[48:51], v[128:131], v[96:99]
	s_waitcnt lgkmcnt(1)
	v_mfma_f32_16x16x32_bf16 v[84:87], v[48:51], v[132:135], v[84:87]
	s_waitcnt lgkmcnt(0)
	v_mfma_f32_16x16x32_bf16 v[76:79], v[48:51], v[136:139], v[76:79]
	ds_read_b128 v[48:51], v124 offset:34048
	s_waitcnt lgkmcnt(0)
	v_mfma_f32_16x16x32_bf16 v[72:75], v[48:51], v[108:111], v[72:75]
	ds_read_b128 v[56:59], v124 offset:35072
	v_mfma_f32_16x16x32_bf16 v[68:71], v[48:51], v[128:131], v[68:71]
	ds_read_b128 v[144:147], v124 offset:36096
	v_mfma_f32_16x16x32_bf16 v[60:63], v[48:51], v[132:135], v[60:63]
	ds_read_b128 v[148:151], v124 offset:41280
	v_mfma_f32_16x16x32_bf16 v[52:55], v[48:51], v[136:139], v[52:55]
	ds_read_b128 v[152:155], v124 offset:42304
	s_waitcnt lgkmcnt(3)
	v_mfma_f32_16x16x32_bf16 v[44:47], v[56:59], v[108:111], v[44:47]
	ds_read_b128 v[156:159], v124 offset:43328
	v_mfma_f32_16x16x32_bf16 v[40:43], v[56:59], v[128:131], v[40:43]
	ds_read_b128 v[48:51], v124 offset:44352
	v_mfma_f32_16x16x32_bf16 v[36:39], v[56:59], v[132:135], v[36:39]
	ds_read_b128 v[64:67], v125 offset:57792
	v_mfma_f32_16x16x32_bf16 v[28:31], v[56:59], v[136:139], v[28:31]
	ds_read_b128 v[104:107], v125 offset:58816
	s_waitcnt lgkmcnt(6)
	v_mfma_f32_16x16x32_bf16 v[92:95], v[144:147], v[108:111], v[92:95]
	ds_read_b128 v[112:115], v125 offset:59840
	v_mfma_f32_16x16x32_bf16 v[88:91], v[144:147], v[128:131], v[88:91]
	ds_read_b128 v[108:111], v125 offset:60864
	v_mfma_f32_16x16x32_bf16 v[80:83], v[144:147], v[132:135], v[80:83]
	v_mfma_f32_16x16x32_bf16 v[56:59], v[144:147], v[136:139], v[100:103]
	s_waitcnt lgkmcnt(3)
	v_mfma_f32_16x16x32_bf16 v[100:103], v[148:151], v[64:67], v[140:143]
	s_waitcnt lgkmcnt(2)
	v_mfma_f32_16x16x32_bf16 v[96:99], v[148:151], v[104:107], v[96:99]
	s_waitcnt lgkmcnt(1)
	v_mfma_f32_16x16x32_bf16 v[84:87], v[148:151], v[112:115], v[84:87]
	s_waitcnt lgkmcnt(0)
	v_mfma_f32_16x16x32_bf16 v[76:79], v[148:151], v[108:111], v[76:79]
	v_mfma_f32_16x16x32_bf16 v[72:75], v[152:155], v[64:67], v[72:75]
	v_mfma_f32_16x16x32_bf16 v[68:71], v[152:155], v[104:107], v[68:71]
	v_mfma_f32_16x16x32_bf16 v[60:63], v[152:155], v[112:115], v[60:63]
	v_mfma_f32_16x16x32_bf16 v[52:55], v[152:155], v[108:111], v[52:55]
	v_mfma_f32_16x16x32_bf16 v[44:47], v[156:159], v[64:67], v[44:47]
	v_mfma_f32_16x16x32_bf16 v[40:43], v[156:159], v[104:107], v[40:43]
	v_mfma_f32_16x16x32_bf16 v[36:39], v[156:159], v[112:115], v[36:39]
	v_mfma_f32_16x16x32_bf16 v[28:31], v[156:159], v[108:111], v[28:31]
	s_cmp_lt_u32 s44, 14
	s_mov_b32 s13, s44
	s_waitcnt lgkmcnt(0)
	s_barrier
; #define MFMA16(a, b, c) __builtin_amdgcn_mfma_f32_16x16x32_bf16(a, b, c, 0, 0, 0)
; template <int WM, int WN, typename SrcF, typename PostF>
; __device__ __forceinline__ void gemm_stream(const int nsteps, SrcF src, PostF post, f32x4 (&acc)[WM][WN], char* smem) {
;     ...
;   acc[3][0] = MFMA16(pa, pb0, acc[3][0]);
;   acc[3][1] = MFMA16(pa, pb1, acc[3][1]);
;   acc[3][2] = MFMA16(pa, pb2, acc[3][2]);
;   acc[3][3] = MFMA16(pa, pb3, acc[3][3]);
; template <int WM, int WN>
; __device__ __forceinline__ void store_tile_bf16(const f32x4 (&acc)[WM][WN], u16* dst, int ld, char* smem) {
;   constexpr int BM = 32 * WM, BN = 32 * WN, STR = BN + 8;
;   const int tid = opaque_tid(), lane = tid & 63, wid = tid >> 6;
;   const int wr = wid >> 1, wc = wid & 1, fr = lane & 15, fq = lane >> 4;
;   u16* T = reinterpret_cast<u16*>(smem);
; #pragma unroll
;   for (int m = 0; m < WM; ++m)
; #pragma unroll
;     for (int n = 0; n < WN; ++n)
; #pragma unroll
;       for (int j = 0; j < 4; ++j)
;         T[(wr * 16 * WM + m * 16 + fq * 4 + j) * STR + wc * 16 * WN + n * 16 + fr] = f2bf(acc[m][n][j]);
;   __syncthreads();
	s_waitcnt vmcnt(5)
	v_mov_b32_e32 v16, v232
	s_waitcnt vmcnt(0)
	v_mfma_f32_16x16x32_bf16 v[0:3], v[48:51], v[64:67], v[92:95]
	v_lshrrev_b32_e32 v18, 2, v16
	v_lshrrev_b32_e32 v17, 1, v16
	v_and_b32_e32 v18, 12, v18
	v_and_or_b32 v17, v17, s40, v18
	v_and_b32_e32 v18, 0x4f, v16
	v_mul_lo_u32 v17, v17, s42
	v_lshl_add_u32 v17, v18, 1, v17
	v_cvt_pk_bf16_f32 v18, v101, v102
	ds_write_b16 v17, v18 offset:272
	ds_write_b16_d16_hi v17, v18 offset:544
	v_cvt_pk_bf16_f32 v18, v103, v96
	ds_write_b16 v17, v18 offset:816
	ds_write_b16_d16_hi v17, v18 offset:32
	v_cvt_pk_bf16_f32 v18, v97, v98
	ds_write_b16 v17, v18 offset:304
	ds_write_b16_d16_hi v17, v18 offset:576
	v_cvt_pk_bf16_f32 v18, v99, v84
	ds_write_b16 v17, v18 offset:848
	ds_write_b16_d16_hi v17, v18 offset:64
	v_cvt_pk_bf16_f32 v18, v85, v86
	ds_write_b16 v17, v18 offset:336
	ds_write_b16_d16_hi v17, v18 offset:608
	v_cvt_pk_bf16_f32 v18, v87, v76
	ds_write_b16 v17, v18 offset:880
	ds_write_b16_d16_hi v17, v18 offset:96
	v_cvt_pk_bf16_f32 v18, v77, v78
	ds_write_b16 v17, v18 offset:368
	ds_write_b16_d16_hi v17, v18 offset:640
	v_cvt_pk_bf16_f32 v18, v79, v72
	ds_write_b16 v17, v18 offset:912
	ds_write_b16_d16_hi v17, v18 offset:4352
	v_cvt_pk_bf16_f32 v18, v73, v74
	ds_write_b16 v17, v18 offset:4624
	ds_write_b16_d16_hi v17, v18 offset:4896
	v_cvt_pk_bf16_f32 v18, v75, v68
	ds_write_b16 v17, v18 offset:5168
	ds_write_b16_d16_hi v17, v18 offset:4384
	v_cvt_pk_bf16_f32 v18, v69, v70
	ds_write_b16 v17, v18 offset:4656
	ds_write_b16_d16_hi v17, v18 offset:4928
	v_cvt_pk_bf16_f32 v18, v71, v60
	ds_write_b16 v17, v18 offset:5200
	ds_write_b16_d16_hi v17, v18 offset:4416
	v_cvt_pk_bf16_f32 v18, v61, v62
	ds_write_b16 v17, v18 offset:4688
	ds_write_b16_d16_hi v17, v18 offset:4960
	v_cvt_pk_bf16_f32 v18, v63, v52
	ds_write_b16 v17, v18 offset:5232
	ds_write_b16_d16_hi v17, v18 offset:4448
	v_cvt_pk_bf16_f32 v18, v53, v54
	ds_write_b16 v17, v18 offset:4720
	ds_write_b16_d16_hi v17, v18 offset:4992
	v_cvt_pk_bf16_f32 v18, v55, v44
	ds_write_b16 v17, v18 offset:5264
	ds_write_b16_d16_hi v17, v18 offset:8704
	v_cvt_pk_bf16_f32 v18, v45, v46
	ds_write_b16 v17, v18 offset:8976
	ds_write_b16_d16_hi v17, v18 offset:9248
	v_cvt_pk_bf16_f32 v18, v47, v40
	ds_write_b16 v17, v18 offset:9520
	ds_write_b16_d16_hi v17, v18 offset:8736
	v_cvt_pk_bf16_f32 v18, v41, v42
	ds_write_b16 v17, v18 offset:9008
	ds_write_b16_d16_hi v17, v18 offset:9280
	v_cvt_pk_bf16_f32 v18, v43, v36
	ds_write_b16 v17, v18 offset:9552
	ds_write_b16_d16_hi v17, v18 offset:8768
	v_cvt_pk_bf16_f32 v18, v37, v38
	ds_write_b16 v17, v18 offset:9040
	ds_write_b16_d16_hi v17, v18 offset:9312
	v_cvt_pk_bf16_f32 v18, v39, v28
	ds_write_b16 v17, v18 offset:9584
	ds_write_b16_d16_hi v17, v18 offset:8800
	v_cvt_pk_bf16_f32 v18, v29, v30
	ds_write_b16 v17, v18 offset:9072
	ds_write_b16_d16_hi v17, v18 offset:9344
	v_cvt_pk_bf16_f32 v18, 0, v31
	ds_write_b16_d16_hi v17, v18 offset:9616
	v_cvt_pk_bf16_f32 v0, 0, v0
	ds_write_b16_d16_hi v17, v0 offset:13056
	v_cvt_pk_bf16_f32 v0, 0, v1
	v_mfma_f32_16x16x32_bf16 v[4:7], v[48:51], v[104:107], v[88:91]
	ds_write_b16_d16_hi v17, v0 offset:13328
	v_cvt_pk_bf16_f32 v0, v2, v3
	ds_write_b16 v17, v0 offset:13600
	ds_write_b16_d16_hi v17, v0 offset:13872
	s_nop 0
	s_nop 1
	s_nop 0
	v_cvt_pk_bf16_f32 v0, 0, v4
	ds_write_b16_d16_hi v17, v0 offset:13088
	v_cvt_pk_bf16_f32 v0, 0, v5
	v_mfma_f32_16x16x32_bf16 v[8:11], v[48:51], v[112:115], v[80:83]
	ds_write_b16_d16_hi v17, v0 offset:13360
	v_cvt_pk_bf16_f32 v0, v6, v7
	ds_write_b16 v17, v0 offset:13632
	ds_write_b16_d16_hi v17, v0 offset:13904
	s_nop 0
	s_nop 1
	s_nop 0
	v_cvt_pk_bf16_f32 v0, 0, v8
	ds_write_b16_d16_hi v17, v0 offset:13120
	v_cvt_pk_bf16_f32 v0, 0, v9
	v_mfma_f32_16x16x32_bf16 v[12:15], v[48:51], v[108:111], v[56:59]
	ds_write_b16_d16_hi v17, v0 offset:13392
	v_cvt_pk_bf16_f32 v0, v10, v11
	ds_write_b16 v17, v0 offset:13664
	ds_write_b16_d16_hi v17, v0 offset:13936
	s_nop 0
	s_nop 1
	s_nop 0
	v_cvt_pk_bf16_f32 v0, v12, v13
	ds_write_b16 v17, v0 offset:13152
	ds_write_b16_d16_hi v17, v0 offset:13424
	v_cvt_pk_bf16_f32 v0, 0, v14
	ds_write_b16_d16_hi v17, v0 offset:13696
	s_lshl_b64 s[14:15], s[14:15], 1
	v_cvt_pk_bf16_f32 v0, 0, v15
	s_add_u32 s14, s26, s14
	ds_write_b16_d16_hi v17, v0 offset:13968
	v_ashrrev_i32_e32 v0, 31, v16
	s_addc_u32 s15, s27, s15
	s_lshl_b32 s12, s12, 7
	v_lshrrev_b32_e32 v0, 28, v0
	s_ashr_i32 s13, s12, 31
	v_add_u32_e32 v0, v16, v0
	s_lshl_b64 s[12:13], s[12:13], 1
	v_ashrrev_i32_e32 v4, 4, v0
	v_and_b32_e32 v0, -16, v0
	s_add_u32 s12, s14, s12
	v_sub_u32_e32 v0, v16, v0
	v_ashrrev_i32_e32 v5, 31, v4
	s_addc_u32 s13, s15, s13
	v_mul_lo_u32 v1, v4, s42
	v_lshlrev_b32_e32 v6, 3, v0
	v_lshlrev_b64 v[4:5], 11, v[4:5]
	v_ashrrev_i32_e32 v7, 31, v6
	v_lshl_add_u64 v[4:5], s[12:13], 0, v[4:5]
	v_lshl_add_u64 v[8:9], v[6:7], 1, v[4:5]
	v_add_u32_e32 v4, 0x100, v16
	v_ashrrev_i32_e32 v5, 31, v4
	v_cvt_pk_bf16_f32 v19, 0, v100
	v_lshl_add_u32 v0, v0, 4, v1
	v_lshrrev_b32_e32 v5, 28, v5
	ds_write_b16_d16_hi v17, v19
	s_waitcnt lgkmcnt(0)
	s_barrier
; template <int WM, int WN>
; __device__ __forceinline__ void store_tile_bf16(const f32x4 (&acc)[WM][WN], u16* dst, int ld, char* smem) {
;     ...
;   constexpr int CPR = BN / 8;
; #pragma unroll
;   for (int i = 0; i < BM * CPR / 256; ++i) {
;     int q = tid + 256 * i, row = q / CPR, c = q % CPR;
;     uint4 v = *reinterpret_cast<const uint4*>(T + row * STR + c * 8);
;     *reinterpret_cast<uint4*>(dst + (size_t)row * ld + c * 8) = v;
;   }
	ds_read_b128 v[0:3], v0
	v_add_u32_e32 v5, v4, v5
	v_ashrrev_i32_e32 v10, 4, v5
	v_and_b32_e32 v5, -16, v5
	v_sub_u32_e32 v11, v4, v5
	v_mul_lo_u32 v4, v10, s42
	v_lshl_add_u32 v4, v11, 4, v4
	ds_read_b128 v[4:7], v4
	s_waitcnt lgkmcnt(1)
	global_store_dwordx4 v[8:9], v[0:3], off
	s_add_i32 s43, s43, s61
	s_cmp_lt_i32 s43, s62
	v_lshlrev_b32_e32 v0, 3, v11
	v_ashrrev_i32_e32 v11, 31, v10
	v_lshlrev_b64 v[2:3], 11, v[10:11]
	v_ashrrev_i32_e32 v1, 31, v0
	v_lshl_add_u64 v[2:3], s[12:13], 0, v[2:3]
	v_lshl_add_u64 v[0:1], v[0:1], 1, v[2:3]
	s_waitcnt lgkmcnt(0)
	global_store_dwordx4 v[0:1], v[4:7], off
	v_add_u32_e32 v0, 0x200, v16
	v_ashrrev_i32_e32 v1, 31, v0
	v_lshrrev_b32_e32 v1, 28, v1
	v_add_u32_e32 v1, v0, v1
	v_ashrrev_i32_e32 v4, 4, v1
	v_and_b32_e32 v1, -16, v1
	v_sub_u32_e32 v0, v0, v1
	v_ashrrev_i32_e32 v5, 31, v4
	v_mul_lo_u32 v1, v4, s42
	v_lshlrev_b32_e32 v6, 3, v0
	v_lshlrev_b64 v[4:5], 11, v[4:5]
	v_ashrrev_i32_e32 v7, 31, v6
	v_lshl_add_u64 v[4:5], s[12:13], 0, v[4:5]
	v_lshl_add_u64 v[8:9], v[6:7], 1, v[4:5]
	v_add_u32_e32 v4, 0x300, v16
	v_ashrrev_i32_e32 v5, 31, v4
	v_lshl_add_u32 v0, v0, 4, v1
	v_lshrrev_b32_e32 v5, 28, v5
	ds_read_b128 v[0:3], v0
	v_add_u32_e32 v5, v4, v5
	v_ashrrev_i32_e32 v10, 4, v5
	v_and_b32_e32 v5, -16, v5
	v_sub_u32_e32 v11, v4, v5
	v_mul_lo_u32 v4, v10, s42
	v_lshl_add_u32 v4, v11, 4, v4
	ds_read_b128 v[4:7], v4
	s_waitcnt lgkmcnt(1)
	global_store_dwordx4 v[8:9], v[0:3], off
	s_nop 1
	v_lshlrev_b32_e32 v0, 3, v11
	v_ashrrev_i32_e32 v11, 31, v10
	v_lshlrev_b64 v[2:3], 11, v[10:11]
	v_ashrrev_i32_e32 v1, 31, v0
	v_lshl_add_u64 v[2:3], s[12:13], 0, v[2:3]
	v_lshl_add_u64 v[0:1], v[0:1], 1, v[2:3]
	s_waitcnt lgkmcnt(0)
	global_store_dwordx4 v[0:1], v[4:7], off
	v_add_u32_e32 v0, 0x400, v16
	v_ashrrev_i32_e32 v1, 31, v0
	v_lshrrev_b32_e32 v1, 28, v1
	v_add_u32_e32 v1, v0, v1
	v_ashrrev_i32_e32 v4, 4, v1
	v_and_b32_e32 v1, -16, v1
	v_sub_u32_e32 v0, v0, v1
	v_ashrrev_i32_e32 v5, 31, v4
	v_mul_lo_u32 v1, v4, s42
	v_lshlrev_b32_e32 v6, 3, v0
	v_lshlrev_b64 v[4:5], 11, v[4:5]
	v_ashrrev_i32_e32 v7, 31, v6
	v_lshl_add_u64 v[4:5], s[12:13], 0, v[4:5]
	v_lshl_add_u64 v[8:9], v[6:7], 1, v[4:5]
	v_add_u32_e32 v4, 0x500, v16
	v_ashrrev_i32_e32 v5, 31, v4
	v_lshl_add_u32 v0, v0, 4, v1
	v_lshrrev_b32_e32 v5, 28, v5
	ds_read_b128 v[0:3], v0
	v_add_u32_e32 v5, v4, v5
	v_ashrrev_i32_e32 v10, 4, v5
	v_and_b32_e32 v5, -16, v5
	v_sub_u32_e32 v11, v4, v5
	v_mul_lo_u32 v4, v10, s42
	v_lshl_add_u32 v4, v11, 4, v4
	ds_read_b128 v[4:7], v4
	s_waitcnt lgkmcnt(1)
	global_store_dwordx4 v[8:9], v[0:3], off
	s_nop 1
	v_lshlrev_b32_e32 v0, 3, v11
	v_ashrrev_i32_e32 v11, 31, v10
	v_lshlrev_b64 v[2:3], 11, v[10:11]
	v_ashrrev_i32_e32 v1, 31, v0
	v_lshl_add_u64 v[2:3], s[12:13], 0, v[2:3]
	v_lshl_add_u64 v[0:1], v[0:1], 1, v[2:3]
	s_waitcnt lgkmcnt(0)
	global_store_dwordx4 v[0:1], v[4:7], off
	v_add_u32_e32 v0, 0x600, v16
	v_ashrrev_i32_e32 v1, 31, v0
	v_lshrrev_b32_e32 v1, 28, v1
	v_add_u32_e32 v1, v0, v1
	v_ashrrev_i32_e32 v4, 4, v1
	v_and_b32_e32 v1, -16, v1
	v_sub_u32_e32 v0, v0, v1
	v_ashrrev_i32_e32 v5, 31, v4
	v_mul_lo_u32 v1, v4, s42
	v_lshlrev_b32_e32 v6, 3, v0
	v_lshlrev_b64 v[4:5], 11, v[4:5]
	v_ashrrev_i32_e32 v7, 31, v6
	v_lshl_add_u64 v[4:5], s[12:13], 0, v[4:5]
	v_lshl_add_u64 v[8:9], v[6:7], 1, v[4:5]
	v_add_u32_e32 v4, 0x700, v16
	v_ashrrev_i32_e32 v5, 31, v4
	v_lshl_add_u32 v0, v0, 4, v1
	v_lshrrev_b32_e32 v5, 28, v5
	ds_read_b128 v[0:3], v0
	v_add_u32_e32 v5, v4, v5
	v_ashrrev_i32_e32 v10, 4, v5
	v_and_b32_e32 v5, -16, v5
	v_sub_u32_e32 v11, v4, v5
	v_mul_lo_u32 v4, v10, s42
	v_lshl_add_u32 v4, v11, 4, v4
	ds_read_b128 v[4:7], v4
	s_waitcnt lgkmcnt(1)
	global_store_dwordx4 v[8:9], v[0:3], off
	s_nop 1
	v_lshlrev_b32_e32 v0, 3, v11
	v_ashrrev_i32_e32 v11, 31, v10
	v_lshlrev_b64 v[2:3], 11, v[10:11]
	v_ashrrev_i32_e32 v1, 31, v0
	v_lshl_add_u64 v[2:3], s[12:13], 0, v[2:3]
	v_lshl_add_u64 v[0:1], v[0:1], 1, v[2:3]
	s_waitcnt lgkmcnt(0)
	global_store_dwordx4 v[0:1], v[4:7], off
	s_cbranch_scc1 .LBB0_638

; #define MFMA16(a, b, c) __builtin_amdgcn_mfma_f32_16x16x32_bf16(a, b, c, 0, 0, 0)
; #define SGB_(mask_, n_) __builtin_amdgcn_sched_group_barrier(mask_, n_, 0)
; template <int WM, int WN> ...
;   static_assert(WM == 4 && WN == 4, "128x128 block tile");
;   constexpr int APAN = 128 * 64 + PPAD, BPAN = 128 * 64 + PPAD;
;   bf16x8 fa0[4], fb0[4], fa1[4], fb1[4];
; #pragma unroll
;   for (int n = 0; n < 4; ++n) fb0[n] = LDSF(cur + boff + n * 1024);
; #pragma unroll
;   for (int m = 0; m < 4; ++m) fa0[m] = LDSF(cur + aoff + m * 1024);
;   acc[3][0] = MFMA16(pa, pb0, acc[3][0]);
;   acc[3][1] = MFMA16(pa, pb1, acc[3][1]);
;   acc[3][2] = MFMA16(pa, pb2, acc[3][2]);
;   acc[3][3] = MFMA16(pa, pb3, acc[3][3]);
; #pragma unroll
;   for (int n = 0; n < 4; ++n) acc[0][n] = MFMA16(fa0[0], fb0[n], acc[0][n]);
; #pragma unroll
;   for (int m = 0; m < 4; ++m) fa1[m] = LDSF(cur + aoff + APAN + m * 1024);
; #pragma unroll
;   for (int n = 0; n < 4; ++n) acc[1][n] = MFMA16(fa0[1], fb0[n], acc[1][n]);
; #pragma unroll
;   for (int n = 0; n < 4; ++n) fb1[n] = LDSF(cur + boff + BPAN + n * 1024);
; #pragma unroll
;   for (int n = 0; n < 4; ++n) acc[2][n] = MFMA16(fa0[2], fb0[n], acc[2][n]);
;   *reinterpret_cast<uint4*>(nxt + wao) = a0;
;   *reinterpret_cast<uint4*>(nxt + wao + 32 * 64) = a1;
; #pragma unroll
;   for (int n = 0; n < 4; ++n) acc[3][n] = MFMA16(fa0[3], fb0[n], acc[3][n]);
;   *reinterpret_cast<uint4*>(nxt + wao + 64 * 64) = a2;
;   *reinterpret_cast<uint4*>(nxt + wao + 96 * 64) = a3;
; #pragma unroll
;   for (int n = 0; n < 4; ++n) acc[0][n] = MFMA16(fa1[0], fb1[n], acc[0][n]);
;   *reinterpret_cast<uint4*>(nxt + wbo) = b0;
;   *reinterpret_cast<uint4*>(nxt + wbo + 32 * 64) = b1;
; #pragma unroll
;   for (int n = 0; n < 4; ++n) acc[1][n] = MFMA16(fa1[1], fb1[n], acc[1][n]);
;   *reinterpret_cast<uint4*>(nxt + wbo + 64 * 64) = b2;
;   *reinterpret_cast<uint4*>(nxt + wbo + 96 * 64) = b3;
; #pragma unroll
;   for (int n = 0; n < 4; ++n) acc[2][n] = MFMA16(fa1[2], fb1[n], acc[2][n]);
;   pa = fa1[3];
;   pb0 = fb1[0]; pb1 = fb1[1]; pb2 = fb1[2]; pb3 = fb1[3];
;   SGB_(0x100, 5);
;   SGB_(0x008, 4);
; #pragma unroll
;   for (int i_ = 0; i_ < 11; ++i_) { SGB_(0x008, 1); SGB_(0x100, 1); }
; #pragma unroll
;   for (int i_ = 0; i_ < 8; ++i_) { SGB_(0x008, 2); SGB_(0x200, 1); SGB_(0x020, 1); }
;   SGB_(0x008, 1);
; }
.LBB0_746:
	s_add_i32 s21, s16, 2
	s_add_i32 s16, s16, 4
	s_min_u32 s16, s16, 15
	s_lshl_b32 s16, s16, 7
	s_add_u32 s92, s24, s16
	s_addc_u32 s93, s25, 0
	s_add_u32 s94, s26, s16
	s_addc_u32 s95, s27, 0
	ds_read_b128 v[148:151], v119
	ds_read_b128 v[132:135], v130 offset:16512
	ds_read_b128 v[136:139], v130 offset:17536
	ds_read_b128 v[140:143], v130 offset:18560
	ds_read_b128 v[144:147], v130 offset:19584
	v_mfma_f32_16x16x32_bf16 v[84:87], v[80:83], v[84:87], v[100:103]
	v_mfma_f32_16x16x32_bf16 v[96:99], v[80:83], v[104:107], v[96:99]
	s_waitcnt vmcnt(7)
	ds_write_b128 v131, v[76:79] offset:33024
	global_load_dwordx4 v[76:79], v116, s[92:93]
	s_add_u32 s64, s24, s16
	s_addc_u32 s65, s25, 0
	v_mfma_f32_16x16x32_bf16 v[92:95], v[80:83], v[108:111], v[92:95]
	v_mfma_f32_16x16x32_bf16 v[80:83], v[80:83], v[112:115], v[88:91]
	s_waitcnt lgkmcnt(4)
	v_mfma_f32_16x16x32_bf16 v[44:47], v[148:151], v[132:135], v[44:47]
	s_nop 0
	ds_read_b128 v[88:91], v119 offset:1024
	s_waitcnt lgkmcnt(4)
	v_mfma_f32_16x16x32_bf16 v[40:43], v[148:151], v[136:139], v[40:43]
	s_waitcnt vmcnt(7)
	ds_write_b128 v131, v[68:71] offset:35072
	global_load_dwordx4 v[68:71], v120, s[92:93]
	ds_read_b128 v[100:103], v119 offset:2048
	s_waitcnt lgkmcnt(5)
	v_mfma_f32_16x16x32_bf16 v[36:39], v[148:151], v[140:143], v[36:39]
	ds_read_b128 v[104:107], v119 offset:3072
	s_waitcnt lgkmcnt(5)
	v_mfma_f32_16x16x32_bf16 v[32:35], v[148:151], v[144:147], v[32:35]
	ds_read_b128 v[108:111], v119 offset:8256
	s_waitcnt lgkmcnt(4)
	v_mfma_f32_16x16x32_bf16 v[28:31], v[88:91], v[132:135], v[28:31]
	ds_read_b128 v[112:115], v119 offset:9280
	v_mfma_f32_16x16x32_bf16 v[24:27], v[88:91], v[136:139], v[24:27]
	ds_read_b128 v[148:151], v119 offset:10304
	v_mfma_f32_16x16x32_bf16 v[20:23], v[88:91], v[140:143], v[20:23]
	s_waitcnt vmcnt(7)
	ds_write_b128 v131, v[64:67] offset:37120
	global_load_dwordx4 v[64:67], v122, s[92:93]
	ds_read_b128 v[152:155], v119 offset:11328
	v_mfma_f32_16x16x32_bf16 v[16:19], v[88:91], v[144:147], v[16:19]
	ds_read_b128 v[88:91], v130 offset:24768
	s_waitcnt lgkmcnt(7)
	v_mfma_f32_16x16x32_bf16 v[12:15], v[100:103], v[132:135], v[12:15]
	ds_read_b128 v[156:159], v130 offset:25792
	v_mfma_f32_16x16x32_bf16 v[8:11], v[100:103], v[136:139], v[8:11]
	ds_read_b128 v[160:163], v130 offset:26816
	v_mfma_f32_16x16x32_bf16 v[4:7], v[100:103], v[140:143], v[4:7]
	s_waitcnt vmcnt(7)
	ds_write_b128 v131, v[72:75] offset:39168
	global_load_dwordx4 v[72:75], v124, s[92:93]
	ds_read_b128 v[164:167], v130 offset:27840
	v_mfma_f32_16x16x32_bf16 v[0:3], v[100:103], v[144:147], v[0:3]
	s_waitcnt lgkmcnt(10)
	v_mfma_f32_16x16x32_bf16 v[84:87], v[104:107], v[132:135], v[84:87]
	v_mfma_f32_16x16x32_bf16 v[96:99], v[104:107], v[136:139], v[96:99]
	v_mfma_f32_16x16x32_bf16 v[92:95], v[104:107], v[140:143], v[92:95]
	v_mfma_f32_16x16x32_bf16 v[80:83], v[104:107], v[144:147], v[80:83]
	s_waitcnt vmcnt(7)
	ds_write_b128 v131, v[60:63] offset:49536
	global_load_dwordx4 v[60:63], v116, s[94:95]
	s_waitcnt lgkmcnt(5)
	v_mfma_f32_16x16x32_bf16 v[44:47], v[108:111], v[88:91], v[44:47]
	s_add_u32 s64, s26, s16
	s_addc_u32 s65, s27, 0
	s_waitcnt lgkmcnt(4)
	v_mfma_f32_16x16x32_bf16 v[40:43], v[108:111], v[156:159], v[40:43]
	s_min_u32 s16, s21, 12
	s_lshl_b32 s16, s16, 7
	s_waitcnt lgkmcnt(3)
	v_mfma_f32_16x16x32_bf16 v[36:39], v[108:111], v[160:163], v[36:39]
	s_waitcnt lgkmcnt(1)
	v_mfma_f32_16x16x32_bf16 v[32:35], v[108:111], v[164:167], v[32:35]
	s_waitcnt vmcnt(7)
	ds_write_b128 v131, v[56:59] offset:51584
	global_load_dwordx4 v[56:59], v120, s[94:95]
	v_mfma_f32_16x16x32_bf16 v[28:31], v[112:115], v[88:91], v[28:31]
	v_mfma_f32_16x16x32_bf16 v[24:27], v[112:115], v[156:159], v[24:27]
	v_mfma_f32_16x16x32_bf16 v[20:23], v[112:115], v[160:163], v[20:23]
	v_mfma_f32_16x16x32_bf16 v[16:19], v[112:115], v[164:167], v[16:19]
	v_mfma_f32_16x16x32_bf16 v[12:15], v[148:151], v[88:91], v[12:15]
	s_waitcnt vmcnt(7)
	ds_write_b128 v131, v[52:55] offset:53632
	global_load_dwordx4 v[52:55], v122, s[94:95]
	v_mfma_f32_16x16x32_bf16 v[8:11], v[148:151], v[156:159], v[8:11]
	s_add_u32 s64, s24, s16
	s_addc_u32 s65, s25, 0
	s_add_u32 s66, s26, s16
	v_mfma_f32_16x16x32_bf16 v[4:7], v[148:151], v[160:163], v[4:7]
	s_addc_u32 s67, s27, 0
	v_mfma_f32_16x16x32_bf16 v[0:3], v[148:151], v[164:167], v[0:3]
	v_mfma_f32_16x16x32_bf16 v[88:91], v[152:155], v[88:91], v[84:87]
	s_waitcnt vmcnt(7)
	ds_write_b128 v131, v[48:51] offset:55680
	global_load_dwordx4 v[48:51], v124, s[94:95]
	v_mfma_f32_16x16x32_bf16 v[96:99], v[152:155], v[156:159], v[96:99]
	v_mfma_f32_16x16x32_bf16 v[92:95], v[152:155], v[160:163], v[92:95]
	v_mfma_f32_16x16x32_bf16 v[132:135], v[152:155], v[164:167], v[80:83]
	s_waitcnt lgkmcnt(0)
	s_barrier
; template <int WM, int WN> ...
;   static_assert(WM == 4 && WN == 4, "128x128 block tile");
;   constexpr int APAN = 128 * 64 + PPAD, BPAN = 128 * 64 + PPAD;
;   bf16x8 fa0[4], fb0[4], fa1[4], fb1[4];
; #pragma unroll
;   for (int n = 0; n < 4; ++n) fb0[n] = LDSF(cur + boff + n * 1024);
; #pragma unroll
;   for (int m = 0; m < 4; ++m) fa0[m] = LDSF(cur + aoff + m * 1024);
;   acc[3][0] = MFMA16(pa, pb0, acc[3][0]);
;   acc[3][1] = MFMA16(pa, pb1, acc[3][1]);
;   acc[3][2] = MFMA16(pa, pb2, acc[3][2]);
;   acc[3][3] = MFMA16(pa, pb3, acc[3][3]);
; #pragma unroll
;   for (int n = 0; n < 4; ++n) acc[0][n] = MFMA16(fa0[0], fb0[n], acc[0][n]);
; #pragma unroll
;   for (int m = 0; m < 4; ++m) fa1[m] = LDSF(cur + aoff + APAN + m * 1024);
; #pragma unroll
;   for (int n = 0; n < 4; ++n) acc[1][n] = MFMA16(fa0[1], fb0[n], acc[1][n]);
; #pragma unroll
;   for (int n = 0; n < 4; ++n) fb1[n] = LDSF(cur + boff + BPAN + n * 1024);
; #pragma unroll
;   for (int n = 0; n < 4; ++n) acc[2][n] = MFMA16(fa0[2], fb0[n], acc[2][n]);
;   *reinterpret_cast<uint4*>(nxt + wao) = a0;
;   *reinterpret_cast<uint4*>(nxt + wao + 32 * 64) = a1;
; #pragma unroll
;   for (int n = 0; n < 4; ++n) acc[3][n] = MFMA16(fa0[3], fb0[n], acc[3][n]);
;   *reinterpret_cast<uint4*>(nxt + wao + 64 * 64) = a2;
;   *reinterpret_cast<uint4*>(nxt + wao + 96 * 64) = a3;
; #pragma unroll
;   for (int n = 0; n < 4; ++n) acc[0][n] = MFMA16(fa1[0], fb1[n], acc[0][n]);
;   *reinterpret_cast<uint4*>(nxt + wbo) = b0;
;   *reinterpret_cast<uint4*>(nxt + wbo + 32 * 64) = b1;
; #pragma unroll
;   for (int n = 0; n < 4; ++n) acc[1][n] = MFMA16(fa1[1], fb1[n], acc[1][n]);
;   *reinterpret_cast<uint4*>(nxt + wbo + 64 * 64) = b2;
;   *reinterpret_cast<uint4*>(nxt + wbo + 96 * 64) = b3;
; #pragma unroll
;   for (int n = 0; n < 4; ++n) acc[2][n] = MFMA16(fa1[2], fb1[n], acc[2][n]);
;   pa = fa1[3];
;   pb0 = fb1[0]; pb1 = fb1[1]; pb2 = fb1[2]; pb3 = fb1[3];
;   SGB_(0x100, 5);
;   SGB_(0x008, 4);
; #pragma unroll
;   for (int i_ = 0; i_ < 11; ++i_) { SGB_(0x008, 1); SGB_(0x100, 1); }
; #pragma unroll
;   for (int i_ = 0; i_ < 8; ++i_) { SGB_(0x008, 2); SGB_(0x200, 1); SGB_(0x020, 1); }
;   SGB_(0x008, 1);
; }
; template <int WM, int WN, typename SrcF, typename PostF>
; __device__ __forceinline__ void gemm_stream(const int nsteps, SrcF src, PostF post, f32x4 (&acc)[WM][WN], char* smem) {
;     ...
;     SB_;
;     post(kt);
	s_nop 0
	ds_read_b128 v[80:83], v119 offset:33024
	ds_read_b128 v[100:103], v130 offset:49536
	ds_read_b128 v[112:115], v130 offset:50560
	ds_read_b128 v[136:139], v130 offset:51584
	ds_read_b128 v[140:143], v130 offset:52608
	s_waitcnt lgkmcnt(3)
	v_mfma_f32_16x16x32_bf16 v[44:47], v[80:83], v[100:103], v[44:47]
	s_waitcnt lgkmcnt(2)
	v_mfma_f32_16x16x32_bf16 v[40:43], v[80:83], v[112:115], v[40:43]
	s_waitcnt vmcnt(7)
	ds_write_b128 v131, v[76:79]
	global_load_dwordx4 v[76:79], v116, s[64:65] offset:384
	s_waitcnt lgkmcnt(2)
	v_mfma_f32_16x16x32_bf16 v[36:39], v[80:83], v[136:139], v[36:39]
	s_waitcnt lgkmcnt(0)
	v_mfma_f32_16x16x32_bf16 v[32:35], v[80:83], v[140:143], v[32:35]
	ds_read_b128 v[80:83], v119 offset:34048
	s_waitcnt lgkmcnt(0)
	v_mfma_f32_16x16x32_bf16 v[28:31], v[80:83], v[100:103], v[28:31]
	s_waitcnt vmcnt(7)
	ds_write_b128 v131, v[68:71] offset:2048
	global_load_dwordx4 v[68:71], v120, s[64:65] offset:384
	ds_read_b128 v[104:107], v119 offset:35072
	v_mfma_f32_16x16x32_bf16 v[24:27], v[80:83], v[112:115], v[24:27]
	ds_read_b128 v[144:147], v119 offset:36096
	v_mfma_f32_16x16x32_bf16 v[20:23], v[80:83], v[136:139], v[20:23]
	ds_read_b128 v[148:151], v119 offset:41280
	v_mfma_f32_16x16x32_bf16 v[16:19], v[80:83], v[140:143], v[16:19]
	ds_read_b128 v[152:155], v119 offset:42304
	s_waitcnt lgkmcnt(3)
	v_mfma_f32_16x16x32_bf16 v[12:15], v[104:107], v[100:103], v[12:15]
	s_waitcnt vmcnt(7)
	ds_write_b128 v131, v[64:67] offset:4096
	global_load_dwordx4 v[64:67], v122, s[64:65] offset:384
	ds_read_b128 v[156:159], v119 offset:43328
	v_mfma_f32_16x16x32_bf16 v[8:11], v[104:107], v[112:115], v[8:11]
	ds_read_b128 v[80:83], v119 offset:44352
	v_mfma_f32_16x16x32_bf16 v[4:7], v[104:107], v[136:139], v[4:7]
	ds_read_b128 v[84:87], v130 offset:57792
	v_mfma_f32_16x16x32_bf16 v[0:3], v[104:107], v[140:143], v[0:3]
	s_waitcnt vmcnt(7)
	ds_write_b128 v131, v[72:75] offset:6144
	global_load_dwordx4 v[72:75], v124, s[64:65] offset:384
	ds_read_b128 v[104:107], v130 offset:58816
	s_waitcnt lgkmcnt(8)
	v_mfma_f32_16x16x32_bf16 v[100:103], v[144:147], v[100:103], v[88:91]
	ds_read_b128 v[108:111], v130 offset:59840
	v_mfma_f32_16x16x32_bf16 v[96:99], v[144:147], v[112:115], v[96:99]
	ds_read_b128 v[112:115], v130 offset:60864
	v_mfma_f32_16x16x32_bf16 v[92:95], v[144:147], v[136:139], v[92:95]
	v_mfma_f32_16x16x32_bf16 v[88:91], v[144:147], v[140:143], v[132:135]
	s_waitcnt vmcnt(7)
	ds_write_b128 v131, v[60:63] offset:16512
	global_load_dwordx4 v[60:63], v116, s[66:67] offset:384
	s_waitcnt lgkmcnt(5)
	v_mfma_f32_16x16x32_bf16 v[44:47], v[148:151], v[84:87], v[44:47]
	s_waitcnt lgkmcnt(3)
	v_mfma_f32_16x16x32_bf16 v[40:43], v[148:151], v[104:107], v[40:43]
	s_waitcnt lgkmcnt(2)
	v_mfma_f32_16x16x32_bf16 v[36:39], v[148:151], v[108:111], v[36:39]
	s_waitcnt vmcnt(7)
	ds_write_b128 v131, v[56:59] offset:18560
	global_load_dwordx4 v[56:59], v120, s[66:67] offset:384
	s_waitcnt lgkmcnt(2)
	v_mfma_f32_16x16x32_bf16 v[32:35], v[148:151], v[112:115], v[32:35]
	v_mfma_f32_16x16x32_bf16 v[28:31], v[152:155], v[84:87], v[28:31]
	v_mfma_f32_16x16x32_bf16 v[24:27], v[152:155], v[104:107], v[24:27]
	v_mfma_f32_16x16x32_bf16 v[20:23], v[152:155], v[108:111], v[20:23]
	s_waitcnt vmcnt(7)
	ds_write_b128 v131, v[52:55] offset:20608
	global_load_dwordx4 v[52:55], v122, s[66:67] offset:384
	v_mfma_f32_16x16x32_bf16 v[16:19], v[152:155], v[112:115], v[16:19]
	v_mfma_f32_16x16x32_bf16 v[12:15], v[156:159], v[84:87], v[12:15]
	v_mfma_f32_16x16x32_bf16 v[8:11], v[156:159], v[104:107], v[8:11]
	s_waitcnt vmcnt(7)
	ds_write_b128 v131, v[48:51] offset:22656
	global_load_dwordx4 v[48:51], v124, s[66:67] offset:384
	v_mfma_f32_16x16x32_bf16 v[4:7], v[156:159], v[108:111], v[4:7]
	v_mfma_f32_16x16x32_bf16 v[0:3], v[156:159], v[112:115], v[0:3]
	s_cmp_lt_u32 s21, 12
	s_mov_b32 s16, s21
	s_waitcnt lgkmcnt(0)
	s_barrier
	s_cbranch_scc1 .LBB0_746
	ds_read_b128 v[148:151], v119
	ds_read_b128 v[132:135], v130 offset:16512
	ds_read_b128 v[136:139], v130 offset:17536
	ds_read_b128 v[140:143], v130 offset:18560
	ds_read_b128 v[144:147], v130 offset:19584
	v_mfma_f32_16x16x32_bf16 v[84:87], v[80:83], v[84:87], v[100:103]
	s_add_i32 s21, s16, 2
	s_add_i32 s16, s16, 4
	s_min_u32 s16, s16, 15
	v_mfma_f32_16x16x32_bf16 v[96:99], v[80:83], v[104:107], v[96:99]
	s_lshl_b32 s16, s16, 7
	s_add_u32 s64, s24, s16
	s_addc_u32 s65, s25, 0
	v_mfma_f32_16x16x32_bf16 v[92:95], v[80:83], v[108:111], v[92:95]
	v_mfma_f32_16x16x32_bf16 v[80:83], v[80:83], v[112:115], v[88:91]
	s_waitcnt lgkmcnt(3)
	v_mfma_f32_16x16x32_bf16 v[44:47], v[148:151], v[132:135], v[44:47]
	s_nop 0
	ds_read_b128 v[88:91], v119 offset:1024
	s_waitcnt lgkmcnt(3)
	v_mfma_f32_16x16x32_bf16 v[40:43], v[148:151], v[136:139], v[40:43]
	ds_read_b128 v[100:103], v119 offset:2048
	s_waitcnt lgkmcnt(3)
	v_mfma_f32_16x16x32_bf16 v[36:39], v[148:151], v[140:143], v[36:39]
	ds_read_b128 v[104:107], v119 offset:3072
	s_waitcnt lgkmcnt(3)
	v_mfma_f32_16x16x32_bf16 v[32:35], v[148:151], v[144:147], v[32:35]
	ds_read_b128 v[108:111], v119 offset:8256
	s_waitcnt lgkmcnt(3)
	v_mfma_f32_16x16x32_bf16 v[28:31], v[88:91], v[132:135], v[28:31]
	ds_read_b128 v[112:115], v119 offset:9280
	v_mfma_f32_16x16x32_bf16 v[24:27], v[88:91], v[136:139], v[24:27]
	ds_read_b128 v[148:151], v119 offset:10304
	v_mfma_f32_16x16x32_bf16 v[20:23], v[88:91], v[140:143], v[20:23]
	ds_read_b128 v[152:155], v119 offset:11328
	v_mfma_f32_16x16x32_bf16 v[16:19], v[88:91], v[144:147], v[16:19]
	ds_read_b128 v[88:91], v130 offset:24768
	s_waitcnt lgkmcnt(6)
; #define MFMA16(a, b, c) __builtin_amdgcn_mfma_f32_16x16x32_bf16(a, b, c, 0, 0, 0)
; #define SGB_(mask_, n_) __builtin_amdgcn_sched_group_barrier(mask_, n_, 0)
; template <int WM, int WN> ...
;   static_assert(WM == 4 && WN == 4, "128x128 block tile");
;   constexpr int APAN = 128 * 64 + PPAD, BPAN = 128 * 64 + PPAD;
;   bf16x8 fa0[4], fb0[4], fa1[4], fb1[4];
; #pragma unroll
;   for (int n = 0; n < 4; ++n) fb0[n] = LDSF(cur + boff + n * 1024);
; #pragma unroll
;   for (int m = 0; m < 4; ++m) fa0[m] = LDSF(cur + aoff + m * 1024);
;   acc[3][0] = MFMA16(pa, pb0, acc[3][0]);
;   acc[3][1] = MFMA16(pa, pb1, acc[3][1]);
;   acc[3][2] = MFMA16(pa, pb2, acc[3][2]);
;   acc[3][3] = MFMA16(pa, pb3, acc[3][3]);
; #pragma unroll
;   for (int n = 0; n < 4; ++n) acc[0][n] = MFMA16(fa0[0], fb0[n], acc[0][n]);
; #pragma unroll
;   for (int m = 0; m < 4; ++m) fa1[m] = LDSF(cur + aoff + APAN + m * 1024);
; #pragma unroll
;   for (int n = 0; n < 4; ++n) acc[1][n] = MFMA16(fa0[1], fb0[n], acc[1][n]);
; #pragma unroll
;   for (int n = 0; n < 4; ++n) fb1[n] = LDSF(cur + boff + BPAN + n * 1024);
; #pragma unroll
;   for (int n = 0; n < 4; ++n) acc[2][n] = MFMA16(fa0[2], fb0[n], acc[2][n]);
;   *reinterpret_cast<uint4*>(nxt + wao) = a0;
;   *reinterpret_cast<uint4*>(nxt + wao + 32 * 64) = a1;
; #pragma unroll
;   for (int n = 0; n < 4; ++n) acc[3][n] = MFMA16(fa0[3], fb0[n], acc[3][n]);
;   *reinterpret_cast<uint4*>(nxt + wao + 64 * 64) = a2;
;   *reinterpret_cast<uint4*>(nxt + wao + 96 * 64) = a3;
; #pragma unroll
;   for (int n = 0; n < 4; ++n) acc[0][n] = MFMA16(fa1[0], fb1[n], acc[0][n]);
;   *reinterpret_cast<uint4*>(nxt + wbo) = b0;
;   *reinterpret_cast<uint4*>(nxt + wbo + 32 * 64) = b1;
; #pragma unroll
;   for (int n = 0; n < 4; ++n) acc[1][n] = MFMA16(fa1[1], fb1[n], acc[1][n]);
;   *reinterpret_cast<uint4*>(nxt + wbo + 64 * 64) = b2;
;   *reinterpret_cast<uint4*>(nxt + wbo + 96 * 64) = b3;
; #pragma unroll
;   for (int n = 0; n < 4; ++n) acc[2][n] = MFMA16(fa1[2], fb1[n], acc[2][n]);
;   pa = fa1[3];
;   pb0 = fb1[0]; pb1 = fb1[1]; pb2 = fb1[2]; pb3 = fb1[3];
;   SGB_(0x100, 5);
;   SGB_(0x008, 4);
; #pragma unroll
;   for (int i_ = 0; i_ < 11; ++i_) { SGB_(0x008, 1); SGB_(0x100, 1); }
; #pragma unroll
;   for (int i_ = 0; i_ < 8; ++i_) { SGB_(0x008, 2); SGB_(0x200, 1); SGB_(0x020, 1); }
;   SGB_(0x008, 1);
; }
	v_mfma_f32_16x16x32_bf16 v[12:15], v[100:103], v[132:135], v[12:15]
	ds_read_b128 v[156:159], v130 offset:25792
	v_mfma_f32_16x16x32_bf16 v[8:11], v[100:103], v[136:139], v[8:11]
	ds_read_b128 v[160:163], v130 offset:26816
	v_mfma_f32_16x16x32_bf16 v[4:7], v[100:103], v[140:143], v[4:7]
	ds_read_b128 v[164:167], v130 offset:27840
	v_mfma_f32_16x16x32_bf16 v[0:3], v[100:103], v[144:147], v[0:3]
	s_waitcnt lgkmcnt(8)
	v_mfma_f32_16x16x32_bf16 v[84:87], v[104:107], v[132:135], v[84:87]
	s_waitcnt vmcnt(7)
	ds_write_b128 v131, v[76:79] offset:33024
	v_mfma_f32_16x16x32_bf16 v[96:99], v[104:107], v[136:139], v[96:99]
	v_mfma_f32_16x16x32_bf16 v[92:95], v[104:107], v[140:143], v[92:95]
	s_waitcnt vmcnt(6)
	ds_write_b128 v131, v[68:71] offset:35072
	v_mfma_f32_16x16x32_bf16 v[80:83], v[104:107], v[144:147], v[80:83]
	s_waitcnt lgkmcnt(5)
	v_mfma_f32_16x16x32_bf16 v[44:47], v[108:111], v[88:91], v[44:47]
	s_waitcnt vmcnt(5)
	ds_write_b128 v131, v[64:67] offset:37120
	s_add_u32 s64, s26, s16
	s_addc_u32 s65, s27, 0
	s_waitcnt lgkmcnt(5)
	v_mfma_f32_16x16x32_bf16 v[40:43], v[108:111], v[156:159], v[40:43]
	s_min_u32 s16, s21, 12
	s_lshl_b32 s16, s16, 7
	s_waitcnt lgkmcnt(4)
	v_mfma_f32_16x16x32_bf16 v[36:39], v[108:111], v[160:163], v[36:39]
	s_waitcnt vmcnt(4)
	ds_write_b128 v131, v[72:75] offset:39168
	s_waitcnt lgkmcnt(4)
	v_mfma_f32_16x16x32_bf16 v[32:35], v[108:111], v[164:167], v[32:35]
	v_mfma_f32_16x16x32_bf16 v[28:31], v[112:115], v[88:91], v[28:31]
	s_waitcnt vmcnt(3)
	ds_write_b128 v131, v[60:63] offset:49536
	v_mfma_f32_16x16x32_bf16 v[24:27], v[112:115], v[156:159], v[24:27]
	v_mfma_f32_16x16x32_bf16 v[20:23], v[112:115], v[160:163], v[20:23]
	s_waitcnt vmcnt(2)
	ds_write_b128 v131, v[56:59] offset:51584
	v_mfma_f32_16x16x32_bf16 v[16:19], v[112:115], v[164:167], v[16:19]
	v_mfma_f32_16x16x32_bf16 v[12:15], v[148:151], v[88:91], v[12:15]
	s_waitcnt vmcnt(1)
	ds_write_b128 v131, v[52:55] offset:53632
	v_mfma_f32_16x16x32_bf16 v[8:11], v[148:151], v[156:159], v[8:11]
	s_add_u32 s64, s24, s16
	s_addc_u32 s65, s25, 0
	s_add_u32 s66, s26, s16
	v_mfma_f32_16x16x32_bf16 v[4:7], v[148:151], v[160:163], v[4:7]
	s_waitcnt vmcnt(0)
	ds_write_b128 v131, v[48:51] offset:55680
	s_addc_u32 s67, s27, 0
	v_mfma_f32_16x16x32_bf16 v[0:3], v[148:151], v[164:167], v[0:3]
	v_mfma_f32_16x16x32_bf16 v[88:91], v[152:155], v[88:91], v[84:87]
	v_mfma_f32_16x16x32_bf16 v[96:99], v[152:155], v[156:159], v[96:99]
	v_mfma_f32_16x16x32_bf16 v[92:95], v[152:155], v[160:163], v[92:95]
	v_mfma_f32_16x16x32_bf16 v[132:135], v[152:155], v[164:167], v[80:83]
	s_waitcnt lgkmcnt(0)
	s_barrier
	s_nop 0
	ds_read_b128 v[80:83], v119 offset:33024
	ds_read_b128 v[100:103], v130 offset:49536
	ds_read_b128 v[112:115], v130 offset:50560
	ds_read_b128 v[136:139], v130 offset:51584
	ds_read_b128 v[140:143], v130 offset:52608
	s_waitcnt lgkmcnt(3)
	v_mfma_f32_16x16x32_bf16 v[44:47], v[80:83], v[100:103], v[44:47]
	s_waitcnt lgkmcnt(2)
	v_mfma_f32_16x16x32_bf16 v[40:43], v[80:83], v[112:115], v[40:43]
	s_waitcnt lgkmcnt(1)
	v_mfma_f32_16x16x32_bf16 v[36:39], v[80:83], v[136:139], v[36:39]
	s_waitcnt lgkmcnt(0)
	v_mfma_f32_16x16x32_bf16 v[32:35], v[80:83], v[140:143], v[32:35]
	ds_read_b128 v[80:83], v119 offset:34048
	s_waitcnt lgkmcnt(0)
	v_mfma_f32_16x16x32_bf16 v[28:31], v[80:83], v[100:103], v[28:31]
	ds_read_b128 v[104:107], v119 offset:35072
	v_mfma_f32_16x16x32_bf16 v[24:27], v[80:83], v[112:115], v[24:27]
	ds_read_b128 v[144:147], v119 offset:36096
	v_mfma_f32_16x16x32_bf16 v[20:23], v[80:83], v[136:139], v[20:23]
	ds_read_b128 v[148:151], v119 offset:41280
	v_mfma_f32_16x16x32_bf16 v[16:19], v[80:83], v[140:143], v[16:19]
	ds_read_b128 v[152:155], v119 offset:42304
	s_waitcnt lgkmcnt(3)
	v_mfma_f32_16x16x32_bf16 v[12:15], v[104:107], v[100:103], v[12:15]
	ds_read_b128 v[156:159], v119 offset:43328
	v_mfma_f32_16x16x32_bf16 v[8:11], v[104:107], v[112:115], v[8:11]
	ds_read_b128 v[80:83], v119 offset:44352
	v_mfma_f32_16x16x32_bf16 v[4:7], v[104:107], v[136:139], v[4:7]
	ds_read_b128 v[84:87], v130 offset:57792
	v_mfma_f32_16x16x32_bf16 v[0:3], v[104:107], v[140:143], v[0:3]
	ds_read_b128 v[104:107], v130 offset:58816
	s_waitcnt lgkmcnt(6)
	v_mfma_f32_16x16x32_bf16 v[100:103], v[144:147], v[100:103], v[88:91]
	ds_read_b128 v[108:111], v130 offset:59840
	v_mfma_f32_16x16x32_bf16 v[96:99], v[144:147], v[112:115], v[96:99]
	ds_read_b128 v[112:115], v130 offset:60864
	v_mfma_f32_16x16x32_bf16 v[92:95], v[144:147], v[136:139], v[92:95]
	v_mfma_f32_16x16x32_bf16 v[88:91], v[144:147], v[140:143], v[132:135]
	s_waitcnt lgkmcnt(3)
	v_mfma_f32_16x16x32_bf16 v[44:47], v[148:151], v[84:87], v[44:47]
	s_waitcnt lgkmcnt(2)
	v_mfma_f32_16x16x32_bf16 v[40:43], v[148:151], v[104:107], v[40:43]
	s_waitcnt lgkmcnt(1)
	v_mfma_f32_16x16x32_bf16 v[36:39], v[148:151], v[108:111], v[36:39]
	s_waitcnt lgkmcnt(0)
	v_mfma_f32_16x16x32_bf16 v[32:35], v[148:151], v[112:115], v[32:35]
	v_mfma_f32_16x16x32_bf16 v[28:31], v[152:155], v[84:87], v[28:31]
	v_mfma_f32_16x16x32_bf16 v[24:27], v[152:155], v[104:107], v[24:27]
	v_mfma_f32_16x16x32_bf16 v[20:23], v[152:155], v[108:111], v[20:23]
	v_mfma_f32_16x16x32_bf16 v[16:19], v[152:155], v[112:115], v[16:19]
	v_mfma_f32_16x16x32_bf16 v[12:15], v[156:159], v[84:87], v[12:15]
	v_mfma_f32_16x16x32_bf16 v[8:11], v[156:159], v[104:107], v[8:11]
	v_mfma_f32_16x16x32_bf16 v[4:7], v[156:159], v[108:111], v[4:7]
	v_mfma_f32_16x16x32_bf16 v[0:3], v[156:159], v[112:115], v[0:3]
	s_cmp_lt_u32 s21, 14
	s_mov_b32 s16, s21
	s_waitcnt lgkmcnt(0)
	s_barrier
; #define MFMA16(a, b, c) __builtin_amdgcn_mfma_f32_16x16x32_bf16(a, b, c, 0, 0, 0)
; template <int WM, int WN, typename SrcF, typename PostF>
; __device__ __forceinline__ void gemm_stream(const int nsteps, SrcF src, PostF post, f32x4 (&acc)[WM][WN], char* smem) {
;     ...
;   acc[3][0] = MFMA16(pa, pb0, acc[3][0]);
;   acc[3][1] = MFMA16(pa, pb1, acc[3][1]);
;   acc[3][2] = MFMA16(pa, pb2, acc[3][2]);
;   acc[3][3] = MFMA16(pa, pb3, acc[3][3]);
; __device__ void phase_inproj(const Params& p, int layer, char* smem) {
;     ...
;     const int row0 = rb * 128 + wr * 64, col0 = cb * 128 + wc * 64;
;     if (cb >= 12 && cb <= 16) {
; #pragma unroll
;       for (int m = 0; m < 4; ++m)
; #pragma unroll
;         for (int j = 0; j < 4; ++j) {
;           int row = row0 + m * 16 + fq * 4 + j;
;           int pos = row & (SEQ - 1);
; #pragma unroll
;           for (int n = 0; n < 2; ++n) {
;             float2 cs2 = RT[pos * 32 + n * 16 + fr];
;             float c = cs2.x, s = cs2.y;
;             float x1 = acc[m][n][j], x2 = acc[m][n + 2][j];
;             acc[m][n][j] = x1 * c - x2 * s;
;             acc[m][n + 2][j] = x2 * c + x1 * s;
;           }
;         }
	s_waitcnt vmcnt(3)
	v_mfma_f32_16x16x32_bf16 v[60:63], v[80:83], v[84:87], v[100:103]
	s_add_i32 s16, s22, -12
	s_cmp_gt_u32 s16, 4
	s_waitcnt vmcnt(2)
	v_mfma_f32_16x16x32_bf16 v[56:59], v[80:83], v[104:107], v[96:99]
	s_waitcnt vmcnt(1)
	v_mfma_f32_16x16x32_bf16 v[52:55], v[80:83], v[108:111], v[92:95]
	s_waitcnt vmcnt(0)
	v_mfma_f32_16x16x32_bf16 v[48:51], v[80:83], v[112:115], v[88:91]
	s_cbranch_scc1 .LBB0_749
	v_lshl_add_u32 v64, s20, 7, v126
	v_and_or_b32 v64, v64, s43, v127
	v_lshl_or_b32 v116, v64, 8, v128
	v_lshl_add_u64 v[92:93], s[14:15], 0, v[116:117]
	v_add_co_u32_e32 v94, vcc, s48, v92
	global_load_dwordx2 v[68:69], v116, s[14:15]
	global_load_dwordx2 v[64:65], v116, s[14:15] offset:256
	global_load_dwordx2 v[66:67], v116, s[14:15] offset:384
	global_load_dwordx2 v[72:73], v116, s[14:15] offset:512
	global_load_dwordx2 v[76:77], v116, s[14:15] offset:128
	global_load_dwordx2 v[74:75], v116, s[14:15] offset:640
	global_load_dwordx2 v[70:71], v116, s[14:15] offset:768
	global_load_dwordx2 v[78:79], v116, s[14:15] offset:896
	v_addc_co_u32_e32 v95, vcc, 0, v93, vcc
	v_add_co_u32_e32 v96, vcc, s49, v92
	s_waitcnt vmcnt(7)
	v_mov_b32_e32 v124, v68
	v_addc_co_u32_e32 v97, vcc, 0, v93, vcc
	global_load_dwordx2 v[82:83], v[96:97], off offset:-4096
	global_load_dwordx2 v[80:81], v[94:95], off offset:256
	global_load_dwordx2 v[84:85], v[94:95], off offset:384
	global_load_dwordx2 v[88:89], v[94:95], off offset:512
	global_load_dwordx2 v[98:99], v[94:95], off offset:128
	global_load_dwordx2 v[90:91], v[94:95], off offset:640
	global_load_dwordx2 v[86:87], v[94:95], off offset:768
	s_waitcnt vmcnt(13)
	v_mov_b32_e32 v125, v64
	v_mov_b32_e32 v64, v69
	s_waitcnt vmcnt(10)
	v_mov_b32_e32 v68, v76
	v_mul_f32_e32 v76, v46, v72
	v_mul_f32_e32 v130, v38, v73
	v_mul_f32_e32 v72, v38, v72
	v_mul_f32_e32 v132, v46, v73
	s_waitcnt vmcnt(9)
	v_mul_f32_e32 v134, v42, v74
	v_mul_f32_e32 v138, v42, v75
	v_mov_b32_e32 v38, v47
	v_mov_b32_e32 v46, v39
	v_mov_b32_e32 v42, v35
	v_add_co_u32_e32 v92, vcc, s50, v92
	v_mov_b32_e32 v69, v66
	v_mov_b32_e32 v66, v77
	v_mul_f32_e32 v136, v34, v75
	v_mul_f32_e32 v74, v34, v74
	v_mov_b32_e32 v34, v43
	v_pk_mul_f32 v[140:141], v[44:45], v[64:65]
	v_pk_mul_f32 v[64:65], v[36:37], v[64:65]
	s_waitcnt vmcnt(8)
	v_pk_mul_f32 v[38:39], v[38:39], v[70:71]
	v_pk_mul_f32 v[46:47], v[46:47], v[70:71]
	s_waitcnt vmcnt(7)
	v_pk_mul_f32 v[42:43], v[42:43], v[78:79]
	v_addc_co_u32_e32 v93, vcc, 0, v93, vcc
	v_pk_mul_f32 v[142:143], v[40:41], v[66:67]
	v_pk_mul_f32 v[66:67], v[32:33], v[66:67]
	v_pk_mul_f32 v[34:35], v[34:35], v[78:79]
	v_mov_b32_e32 v77, v38
	v_mov_b32_e32 v131, v39
	v_pk_fma_f32 v[44:45], v[44:45], v[124:125], v[64:65] neg_lo:[0,0,1] neg_hi:[0,0,1]
	v_mov_b32_e32 v73, v46
	v_mov_b32_e32 v133, v47
	v_mov_b32_e32 v75, v42
	v_mov_b32_e32 v139, v43
	global_load_dwordx2 v[94:95], v[94:95], off offset:896
	s_nop 0
	global_load_dwordx2 v[100:101], v[96:97], off
	global_load_dwordx2 v[102:103], v[96:97], off offset:256
	global_load_dwordx2 v[104:105], v[96:97], off offset:384
	global_load_dwordx2 v[106:107], v[96:97], off offset:128
	global_load_dwordx2 v[108:109], v[96:97], off offset:512
	global_load_dwordx2 v[110:111], v[96:97], off offset:640
	global_load_dwordx2 v[112:113], v[96:97], off offset:768
	s_nop 0
	global_load_dwordx2 v[96:97], v[96:97], off offset:896
	s_nop 0
	global_load_dwordx2 v[114:115], v[92:93], off offset:640
	global_load_dwordx2 v[120:121], v[92:93], off offset:768
	global_load_dwordx2 v[122:123], v[92:93], off offset:896
	v_mov_b32_e32 v135, v34
	v_mov_b32_e32 v137, v35
	v_pk_fma_f32 v[40:41], v[40:41], v[68:69], v[66:67] neg_lo:[0,0,1] neg_hi:[0,0,1]
	v_pk_fma_f32 v[32:33], v[32:33], v[68:69], v[142:143]
	v_pk_add_f32 v[46:47], v[76:77], v[130:131] neg_lo:[0,1] neg_hi:[0,1]
	v_pk_add_f32 v[38:39], v[72:73], v[132:133]
	v_pk_add_f32 v[34:35], v[74:75], v[138:139]
	global_load_dwordx2 v[74:75], v[92:93], off
	global_load_dwordx2 v[76:77], v[92:93], off offset:256
	v_pk_fma_f32 v[36:37], v[36:37], v[124:125], v[140:141]
	v_pk_add_f32 v[42:43], v[134:135], v[136:137] neg_lo:[0,1] neg_hi:[0,1]
	s_waitcnt vmcnt(20)
	v_mov_b32_e32 v64, v82
	s_waitcnt vmcnt(19)
	v_mov_b32_e32 v65, v80
	v_mov_b32_e32 v80, v83
	s_waitcnt vmcnt(18)
	v_mov_b32_e32 v71, v84
	s_waitcnt vmcnt(16)
	v_mov_b32_e32 v84, v99
	v_pk_mul_f32 v[66:67], v[28:29], v[80:81]
	v_pk_mul_f32 v[68:69], v[20:21], v[80:81]
	v_pk_mul_f32 v[72:73], v[24:25], v[84:85]
	v_pk_mul_f32 v[78:79], v[16:17], v[84:85]
	global_load_dwordx2 v[80:81], v[92:93], off offset:384
	global_load_dwordx2 v[82:83], v[92:93], off offset:512
	global_load_dwordx2 v[84:85], v[92:93], off offset:128
	v_mov_b32_e32 v70, v98
	v_mul_f32_e32 v92, v30, v88
	v_mul_f32_e32 v98, v22, v89
	v_mul_f32_e32 v88, v22, v88
	v_mul_f32_e32 v124, v30, v89
	s_waitcnt vmcnt(18)
; __device__ void phase_inproj(const Params& p, int layer, char* smem) {
;     ...
;     if (cb >= 12 && cb <= 16) {
; #pragma unroll
;       for (int m = 0; m < 4; ++m)
; #pragma unroll
;         for (int j = 0; j < 4; ++j) {
;           int row = row0 + m * 16 + fq * 4 + j;
;           int pos = row & (SEQ - 1);
; #pragma unroll
;           for (int n = 0; n < 2; ++n) {
;             float2 cs2 = RT[pos * 32 + n * 16 + fr];
;             float c = cs2.x, s = cs2.y;
;             float x1 = acc[m][n][j], x2 = acc[m][n + 2][j];
;             acc[m][n][j] = x1 * c - x2 * s;
;             acc[m][n + 2][j] = x2 * c + x1 * s;
;           }
;         }
	v_mul_f32_e32 v130, v26, v90
	v_mul_f32_e32 v132, v18, v91
	v_mul_f32_e32 v90, v18, v90
	v_mul_f32_e32 v134, v26, v91
	v_mov_b32_e32 v22, v31
	v_mov_b32_e32 v30, v23
	v_mov_b32_e32 v18, v27
	v_mov_b32_e32 v26, v19
	s_waitcnt vmcnt(17)
	v_pk_mul_f32 v[136:137], v[22:23], v[86:87]
	v_pk_mul_f32 v[22:23], v[30:31], v[86:87]
	v_mov_b32_e32 v93, v136
	v_mov_b32_e32 v89, v22
	v_mov_b32_e32 v125, v23
	v_mov_b32_e32 v99, v137
	v_pk_add_f32 v[22:23], v[88:89], v[124:125]
	v_pk_fma_f32 v[24:25], v[24:25], v[70:71], v[78:79] neg_lo:[0,0,1] neg_hi:[0,0,1]
	v_pk_fma_f32 v[16:17], v[16:17], v[70:71], v[72:73]
	s_waitcnt vmcnt(16)
	v_pk_mul_f32 v[30:31], v[18:19], v[94:95]
	v_pk_mul_f32 v[18:19], v[26:27], v[94:95]
	s_waitcnt vmcnt(14)
	v_mov_b32_e32 v27, v102
	v_mov_b32_e32 v91, v18
	v_mov_b32_e32 v135, v19
	v_pk_add_f32 v[18:19], v[90:91], v[134:135]
	v_mov_b32_e32 v102, v101
	s_waitcnt vmcnt(13)
	v_mov_b32_e32 v71, v104
	s_waitcnt vmcnt(12)
	v_mov_b32_e32 v104, v107
	s_waitcnt vmcnt(11)
	v_mul_f32_e32 v88, v6, v109
	v_mul_f32_e32 v90, v6, v108
	v_mov_b32_e32 v6, v15
	v_pk_fma_f32 v[28:29], v[28:29], v[64:65], v[68:69] neg_lo:[0,0,1] neg_hi:[0,0,1]
	v_pk_add_f32 v[68:69], v[92:93], v[98:99] neg_lo:[0,1] neg_hi:[0,1]
	v_pk_fma_f32 v[20:21], v[20:21], v[64:65], v[66:67]
	v_mov_b32_e32 v26, v100
	v_pk_mul_f32 v[64:65], v[12:13], v[102:103]
	v_pk_mul_f32 v[66:67], v[4:5], v[102:103]
	v_mov_b32_e32 v70, v106
	v_pk_mul_f32 v[72:73], v[8:9], v[104:105]
	v_pk_mul_f32 v[78:79], v[0:1], v[104:105]
	v_mul_f32_e32 v86, v14, v108
	v_mul_f32_e32 v92, v14, v109
	s_waitcnt vmcnt(10)
	v_mul_f32_e32 v94, v10, v110
	v_mul_f32_e32 v98, v2, v111
	v_mul_f32_e32 v100, v2, v110
	v_mul_f32_e32 v102, v10, v111
	s_waitcnt vmcnt(9)
	v_pk_mul_f32 v[104:105], v[6:7], v[112:113]
	v_mov_b32_e32 v14, v7
	v_mov_b32_e32 v2, v11
	v_mov_b32_e32 v10, v3
	v_mov_b32_e32 v87, v104
	v_mov_b32_e32 v89, v105
	v_pk_mul_f32 v[6:7], v[14:15], v[112:113]
	s_waitcnt vmcnt(8)
	v_pk_mul_f32 v[14:15], v[2:3], v[96:97]
	v_pk_fma_f32 v[8:9], v[8:9], v[70:71], v[78:79] neg_lo:[0,0,1] neg_hi:[0,0,1]
	v_pk_mul_f32 v[2:3], v[10:11], v[96:97]
	v_pk_fma_f32 v[0:1], v[0:1], v[70:71], v[72:73]
	s_waitcnt vmcnt(3)
	v_mov_b32_e32 v11, v76
	v_mov_b32_e32 v76, v75
	v_pk_fma_f32 v[12:13], v[12:13], v[26:27], v[66:67] neg_lo:[0,0,1] neg_hi:[0,0,1]
	v_pk_add_f32 v[66:67], v[86:87], v[88:89] neg_lo:[0,1] neg_hi:[0,1]
	v_mov_b32_e32 v91, v6
	v_mov_b32_e32 v93, v7
	v_pk_fma_f32 v[4:5], v[4:5], v[26:27], v[64:65]
	v_mov_b32_e32 v10, v74
	v_pk_mul_f32 v[26:27], v[60:61], v[76:77]
	v_pk_mul_f32 v[64:65], v[52:53], v[76:77]
	v_mul_f32_e32 v86, v50, v115
	v_mul_f32_e32 v88, v50, v114
	v_mov_b32_e32 v50, v59
	v_pk_add_f32 v[6:7], v[90:91], v[92:93]
	v_mul_f32_e32 v90, v58, v115
	v_pk_fma_f32 v[60:61], v[60:61], v[10:11], v[64:65] neg_lo:[0,0,1] neg_hi:[0,0,1]
	v_pk_fma_f32 v[52:53], v[52:53], v[10:11], v[26:27]
	s_waitcnt vmcnt(2)
	v_mov_b32_e32 v71, v80
	s_waitcnt vmcnt(1)
	v_mul_f32_e32 v78, v54, v83
	s_waitcnt vmcnt(0)
	v_mov_b32_e32 v80, v85
	v_pk_mul_f32 v[72:73], v[56:57], v[80:81]
	v_pk_mul_f32 v[74:75], v[48:49], v[80:81]
	v_mul_f32_e32 v80, v54, v82
	v_mov_b32_e32 v54, v63
	v_mov_b32_e32 v70, v84
	v_mul_f32_e32 v76, v62, v82
	v_mul_f32_e32 v82, v62, v83
	v_mul_f32_e32 v84, v58, v114
	v_pk_mul_f32 v[92:93], v[54:55], v[120:121]
	v_mov_b32_e32 v62, v55
	v_pk_mul_f32 v[10:11], v[50:51], v[122:123]
	v_mov_b32_e32 v58, v51
	v_mov_b32_e32 v131, v30
	v_mov_b32_e32 v133, v31
	v_mov_b32_e32 v95, v14
	v_mov_b32_e32 v99, v15
	v_mov_b32_e32 v77, v92
	v_mov_b32_e32 v79, v93
	v_pk_mul_f32 v[54:55], v[62:63], v[120:121]
	v_mov_b32_e32 v85, v10
	v_mov_b32_e32 v87, v11
	v_pk_mul_f32 v[26:27], v[58:59], v[122:123]
	v_pk_add_f32 v[30:31], v[130:131], v[132:133] neg_lo:[0,1] neg_hi:[0,1]
	v_pk_add_f32 v[14:15], v[94:95], v[98:99] neg_lo:[0,1] neg_hi:[0,1]
	v_mov_b32_e32 v101, v2
	v_mov_b32_e32 v103, v3
	v_pk_add_f32 v[64:65], v[76:77], v[78:79] neg_lo:[0,1] neg_hi:[0,1]
	v_mov_b32_e32 v81, v54
	v_mov_b32_e32 v83, v55
	v_pk_add_f32 v[10:11], v[84:85], v[86:87] neg_lo:[0,1] neg_hi:[0,1]
	v_mov_b32_e32 v89, v26
	v_mov_b32_e32 v91, v27
	v_pk_add_f32 v[2:3], v[100:101], v[102:103]
	v_pk_add_f32 v[54:55], v[80:81], v[82:83]
	v_pk_fma_f32 v[56:57], v[56:57], v[70:71], v[74:75] neg_lo:[0,0,1] neg_hi:[0,0,1]
	v_pk_fma_f32 v[48:49], v[48:49], v[70:71], v[72:73]
	v_pk_add_f32 v[50:51], v[88:89], v[90:91]
	v_mov_b32_e32 v58, v10
	v_mov_b32_e32 v59, v11
	v_mov_b32_e32 v62, v64
	v_mov_b32_e32 v63, v65
	v_mov_b32_e32 v10, v14
	v_mov_b32_e32 v11, v15
	v_mov_b32_e32 v14, v66
	v_mov_b32_e32 v15, v67
	v_mov_b32_e32 v26, v30
	v_mov_b32_e32 v27, v31
	v_mov_b32_e32 v30, v68
	v_mov_b32_e32 v31, v69

; #define MFMA16(a, b, c) __builtin_amdgcn_mfma_f32_16x16x32_bf16(a, b, c, 0, 0, 0)
; #define SGB_(mask_, n_) __builtin_amdgcn_sched_group_barrier(mask_, n_, 0)
; template <int WM, int WN> ...
;   static_assert(WM == 4 && WN == 4, "128x128 block tile");
;   constexpr int APAN = 128 * 64 + PPAD, BPAN = 128 * 64 + PPAD;
;   bf16x8 fa0[4], fb0[4], fa1[4], fb1[4];
; #pragma unroll
;   for (int n = 0; n < 4; ++n) fb0[n] = LDSF(cur + boff + n * 1024);
; #pragma unroll
;   for (int m = 0; m < 4; ++m) fa0[m] = LDSF(cur + aoff + m * 1024);
;   acc[3][0] = MFMA16(pa, pb0, acc[3][0]);
;   acc[3][1] = MFMA16(pa, pb1, acc[3][1]);
;   acc[3][2] = MFMA16(pa, pb2, acc[3][2]);
;   acc[3][3] = MFMA16(pa, pb3, acc[3][3]);
; #pragma unroll
;   for (int n = 0; n < 4; ++n) acc[0][n] = MFMA16(fa0[0], fb0[n], acc[0][n]);
; #pragma unroll
;   for (int m = 0; m < 4; ++m) fa1[m] = LDSF(cur + aoff + APAN + m * 1024);
; #pragma unroll
;   for (int n = 0; n < 4; ++n) acc[1][n] = MFMA16(fa0[1], fb0[n], acc[1][n]);
; #pragma unroll
;   for (int n = 0; n < 4; ++n) fb1[n] = LDSF(cur + boff + BPAN + n * 1024);
; #pragma unroll
;   for (int n = 0; n < 4; ++n) acc[2][n] = MFMA16(fa0[2], fb0[n], acc[2][n]);
;   *reinterpret_cast<uint4*>(nxt + wao) = a0;
;   *reinterpret_cast<uint4*>(nxt + wao + 32 * 64) = a1;
; #pragma unroll
;   for (int n = 0; n < 4; ++n) acc[3][n] = MFMA16(fa0[3], fb0[n], acc[3][n]);
;   *reinterpret_cast<uint4*>(nxt + wao + 64 * 64) = a2;
;   *reinterpret_cast<uint4*>(nxt + wao + 96 * 64) = a3;
; #pragma unroll
;   for (int n = 0; n < 4; ++n) acc[0][n] = MFMA16(fa1[0], fb1[n], acc[0][n]);
;   *reinterpret_cast<uint4*>(nxt + wbo) = b0;
;   *reinterpret_cast<uint4*>(nxt + wbo + 32 * 64) = b1;
; #pragma unroll
;   for (int n = 0; n < 4; ++n) acc[1][n] = MFMA16(fa1[1], fb1[n], acc[1][n]);
;   *reinterpret_cast<uint4*>(nxt + wbo + 64 * 64) = b2;
;   *reinterpret_cast<uint4*>(nxt + wbo + 96 * 64) = b3;
; #pragma unroll
;   for (int n = 0; n < 4; ++n) acc[2][n] = MFMA16(fa1[2], fb1[n], acc[2][n]);
;   pa = fa1[3];
;   pb0 = fb1[0]; pb1 = fb1[1]; pb2 = fb1[2]; pb3 = fb1[3];
;   SGB_(0x100, 5);
;   SGB_(0x008, 4);
; #pragma unroll
;   for (int i_ = 0; i_ < 11; ++i_) { SGB_(0x008, 1); SGB_(0x100, 1); }
; #pragma unroll
;   for (int i_ = 0; i_ < 8; ++i_) { SGB_(0x008, 2); SGB_(0x200, 1); SGB_(0x020, 1); }
;   SGB_(0x008, 1);
; }
.LBB0_1067:
	s_add_i32 s15, s12, 2
	s_add_i32 s12, s12, 4
	s_min_u32 s12, s12, 15
	s_lshl_b32 s12, s12, 7
	s_add_u32 s92, s20, s12
	s_addc_u32 s93, s21, 0
	s_add_u32 s94, s22, s12
	s_addc_u32 s95, s23, 0
	ds_read_b128 v[148:151], v119
	ds_read_b128 v[132:135], v130 offset:16512
	ds_read_b128 v[136:139], v130 offset:17536
	ds_read_b128 v[140:143], v130 offset:18560
	ds_read_b128 v[144:147], v130 offset:19584
	v_mfma_f32_16x16x32_bf16 v[84:87], v[80:83], v[84:87], v[100:103]
	v_mfma_f32_16x16x32_bf16 v[96:99], v[80:83], v[104:107], v[96:99]
	s_waitcnt vmcnt(7)
	ds_write_b128 v131, v[76:79] offset:33024
	global_load_dwordx4 v[76:79], v116, s[92:93]
	s_add_u32 s52, s20, s12
	s_addc_u32 s53, s21, 0
	v_mfma_f32_16x16x32_bf16 v[92:95], v[80:83], v[108:111], v[92:95]
	v_mfma_f32_16x16x32_bf16 v[80:83], v[80:83], v[112:115], v[88:91]
	s_waitcnt lgkmcnt(4)
	v_mfma_f32_16x16x32_bf16 v[44:47], v[148:151], v[132:135], v[44:47]
	s_nop 0
	ds_read_b128 v[88:91], v119 offset:1024
	s_waitcnt lgkmcnt(4)
	v_mfma_f32_16x16x32_bf16 v[40:43], v[148:151], v[136:139], v[40:43]
	s_waitcnt vmcnt(7)
	ds_write_b128 v131, v[68:71] offset:35072
	global_load_dwordx4 v[68:71], v120, s[92:93]
	ds_read_b128 v[100:103], v119 offset:2048
	s_waitcnt lgkmcnt(5)
	v_mfma_f32_16x16x32_bf16 v[36:39], v[148:151], v[140:143], v[36:39]
	ds_read_b128 v[104:107], v119 offset:3072
	s_waitcnt lgkmcnt(5)
	v_mfma_f32_16x16x32_bf16 v[32:35], v[148:151], v[144:147], v[32:35]
	ds_read_b128 v[108:111], v119 offset:8256
	s_waitcnt lgkmcnt(4)
	v_mfma_f32_16x16x32_bf16 v[28:31], v[88:91], v[132:135], v[28:31]
	ds_read_b128 v[112:115], v119 offset:9280
	v_mfma_f32_16x16x32_bf16 v[24:27], v[88:91], v[136:139], v[24:27]
	ds_read_b128 v[148:151], v119 offset:10304
	v_mfma_f32_16x16x32_bf16 v[20:23], v[88:91], v[140:143], v[20:23]
	s_waitcnt vmcnt(7)
	ds_write_b128 v131, v[64:67] offset:37120
	global_load_dwordx4 v[64:67], v122, s[92:93]
	ds_read_b128 v[152:155], v119 offset:11328
	v_mfma_f32_16x16x32_bf16 v[16:19], v[88:91], v[144:147], v[16:19]
	ds_read_b128 v[88:91], v130 offset:24768
	s_waitcnt lgkmcnt(7)
	v_mfma_f32_16x16x32_bf16 v[12:15], v[100:103], v[132:135], v[12:15]
	ds_read_b128 v[156:159], v130 offset:25792
	v_mfma_f32_16x16x32_bf16 v[8:11], v[100:103], v[136:139], v[8:11]
	ds_read_b128 v[160:163], v130 offset:26816
	v_mfma_f32_16x16x32_bf16 v[4:7], v[100:103], v[140:143], v[4:7]
	s_waitcnt vmcnt(7)
	ds_write_b128 v131, v[72:75] offset:39168
	global_load_dwordx4 v[72:75], v124, s[92:93]
	ds_read_b128 v[164:167], v130 offset:27840
	v_mfma_f32_16x16x32_bf16 v[0:3], v[100:103], v[144:147], v[0:3]
	s_waitcnt lgkmcnt(10)
	v_mfma_f32_16x16x32_bf16 v[84:87], v[104:107], v[132:135], v[84:87]
	v_mfma_f32_16x16x32_bf16 v[96:99], v[104:107], v[136:139], v[96:99]
	v_mfma_f32_16x16x32_bf16 v[92:95], v[104:107], v[140:143], v[92:95]
	v_mfma_f32_16x16x32_bf16 v[80:83], v[104:107], v[144:147], v[80:83]
	s_waitcnt vmcnt(7)
	ds_write_b128 v131, v[60:63] offset:49536
	global_load_dwordx4 v[60:63], v116, s[94:95]
	s_waitcnt lgkmcnt(5)
	v_mfma_f32_16x16x32_bf16 v[44:47], v[108:111], v[88:91], v[44:47]
	s_add_u32 s52, s22, s12
	s_addc_u32 s53, s23, 0
	s_waitcnt lgkmcnt(4)
	v_mfma_f32_16x16x32_bf16 v[40:43], v[108:111], v[156:159], v[40:43]
	s_min_u32 s12, s15, 12
	s_lshl_b32 s12, s12, 7
	s_waitcnt lgkmcnt(3)
	v_mfma_f32_16x16x32_bf16 v[36:39], v[108:111], v[160:163], v[36:39]
	s_waitcnt lgkmcnt(1)
	v_mfma_f32_16x16x32_bf16 v[32:35], v[108:111], v[164:167], v[32:35]
	s_waitcnt vmcnt(7)
	ds_write_b128 v131, v[56:59] offset:51584
	global_load_dwordx4 v[56:59], v120, s[94:95]
	v_mfma_f32_16x16x32_bf16 v[28:31], v[112:115], v[88:91], v[28:31]
	v_mfma_f32_16x16x32_bf16 v[24:27], v[112:115], v[156:159], v[24:27]
	v_mfma_f32_16x16x32_bf16 v[20:23], v[112:115], v[160:163], v[20:23]
	v_mfma_f32_16x16x32_bf16 v[16:19], v[112:115], v[164:167], v[16:19]
	v_mfma_f32_16x16x32_bf16 v[12:15], v[148:151], v[88:91], v[12:15]
	s_waitcnt vmcnt(7)
	ds_write_b128 v131, v[52:55] offset:53632
	global_load_dwordx4 v[52:55], v122, s[94:95]
	v_mfma_f32_16x16x32_bf16 v[8:11], v[148:151], v[156:159], v[8:11]
	s_add_u32 s52, s20, s12
	s_addc_u32 s53, s21, 0
	s_add_u32 s54, s22, s12
	v_mfma_f32_16x16x32_bf16 v[4:7], v[148:151], v[160:163], v[4:7]
	s_addc_u32 s55, s23, 0
	v_mfma_f32_16x16x32_bf16 v[0:3], v[148:151], v[164:167], v[0:3]
	v_mfma_f32_16x16x32_bf16 v[88:91], v[152:155], v[88:91], v[84:87]
	s_waitcnt vmcnt(7)
	ds_write_b128 v131, v[48:51] offset:55680
	global_load_dwordx4 v[48:51], v124, s[94:95]
	v_mfma_f32_16x16x32_bf16 v[96:99], v[152:155], v[156:159], v[96:99]
	v_mfma_f32_16x16x32_bf16 v[92:95], v[152:155], v[160:163], v[92:95]
	v_mfma_f32_16x16x32_bf16 v[132:135], v[152:155], v[164:167], v[80:83]
	s_waitcnt lgkmcnt(0)
	s_barrier
; #define MFMA16(a, b, c) __builtin_amdgcn_mfma_f32_16x16x32_bf16(a, b, c, 0, 0, 0)
; template <int WM, int WN> ...
;     ...
;   for (int n = 0; n < 4; ++n) fb0[n] = LDSF(cur + boff + n * 1024);
; #pragma unroll
;   for (int m = 0; m < 4; ++m) fa0[m] = LDSF(cur + aoff + m * 1024);
;   acc[3][0] = MFMA16(pa, pb0, acc[3][0]);
;   acc[3][1] = MFMA16(pa, pb1, acc[3][1]);
;   acc[3][2] = MFMA16(pa, pb2, acc[3][2]);
;   acc[3][3] = MFMA16(pa, pb3, acc[3][3]);
; #pragma unroll
;   for (int n = 0; n < 4; ++n) acc[0][n] = MFMA16(fa0[0], fb0[n], acc[0][n]);
; #pragma unroll
;   for (int m = 0; m < 4; ++m) fa1[m] = LDSF(cur + aoff + APAN + m * 1024);
; #pragma unroll
;   for (int n = 0; n < 4; ++n) acc[1][n] = MFMA16(fa0[1], fb0[n], acc[1][n]);
; #pragma unroll
;   for (int n = 0; n < 4; ++n) fb1[n] = LDSF(cur + boff + BPAN + n * 1024);
; #pragma unroll
;   for (int n = 0; n < 4; ++n) acc[2][n] = MFMA16(fa0[2], fb0[n], acc[2][n]);
;   *reinterpret_cast<uint4*>(nxt + wao) = a0;
;   *reinterpret_cast<uint4*>(nxt + wao + 32 * 64) = a1;
; #pragma unroll
;   for (int n = 0; n < 4; ++n) acc[3][n] = MFMA16(fa0[3], fb0[n], acc[3][n]);
;   *reinterpret_cast<uint4*>(nxt + wao + 64 * 64) = a2;
;   *reinterpret_cast<uint4*>(nxt + wao + 96 * 64) = a3;
; #pragma unroll
;   for (int n = 0; n < 4; ++n) acc[0][n] = MFMA16(fa1[0], fb1[n], acc[0][n]);
;   *reinterpret_cast<uint4*>(nxt + wbo) = b0;
;   *reinterpret_cast<uint4*>(nxt + wbo + 32 * 64) = b1;
; #pragma unroll
;   for (int n = 0; n < 4; ++n) acc[1][n] = MFMA16(fa1[1], fb1[n], acc[1][n]);
;   *reinterpret_cast<uint4*>(nxt + wbo + 64 * 64) = b2;
;   *reinterpret_cast<uint4*>(nxt + wbo + 96 * 64) = b3;
; #pragma unroll
;   for (int n = 0; n < 4; ++n) acc[2][n] = MFMA16(fa1[2], fb1[n], acc[2][n]);
;   pa = fa1[3];
;   pb0 = fb1[0]; pb1 = fb1[1]; pb2 = fb1[2]; pb3 = fb1[3];
;   SGB_(0x100, 5);
;   SGB_(0x008, 4);
; #pragma unroll
;   for (int i_ = 0; i_ < 11; ++i_) { SGB_(0x008, 1); SGB_(0x100, 1); }
; #pragma unroll
;   for (int i_ = 0; i_ < 8; ++i_) { SGB_(0x008, 2); SGB_(0x200, 1); SGB_(0x020, 1); }
;   SGB_(0x008, 1);
; template <int WM, int WN, typename SrcF, typename PostF>
; __device__ __forceinline__ void gemm_stream(const int nsteps, SrcF src, PostF post, f32x4 (&acc)[WM][WN], char* smem) {
;     ...
;       TileSrc s = src(min(kt + 3, nsteps - 1));
;       GLOAD_TILE(ya, s.a, s.lda, ACH);
;       GLOAD_TILE(yb, s.b, s.ldb, BCH);
;     }
	s_nop 0
	ds_read_b128 v[80:83], v119 offset:33024
	ds_read_b128 v[100:103], v130 offset:49536
	ds_read_b128 v[112:115], v130 offset:50560
	ds_read_b128 v[136:139], v130 offset:51584
	ds_read_b128 v[140:143], v130 offset:52608
	s_waitcnt lgkmcnt(3)
	v_mfma_f32_16x16x32_bf16 v[44:47], v[80:83], v[100:103], v[44:47]
	s_waitcnt lgkmcnt(2)
	v_mfma_f32_16x16x32_bf16 v[40:43], v[80:83], v[112:115], v[40:43]
	s_waitcnt vmcnt(7)
	ds_write_b128 v131, v[76:79]
	global_load_dwordx4 v[76:79], v116, s[52:53] offset:384
	s_waitcnt lgkmcnt(2)
	v_mfma_f32_16x16x32_bf16 v[36:39], v[80:83], v[136:139], v[36:39]
	s_waitcnt lgkmcnt(0)
	v_mfma_f32_16x16x32_bf16 v[32:35], v[80:83], v[140:143], v[32:35]
	ds_read_b128 v[80:83], v119 offset:34048
	s_waitcnt lgkmcnt(0)
	v_mfma_f32_16x16x32_bf16 v[28:31], v[80:83], v[100:103], v[28:31]
	s_waitcnt vmcnt(7)
	ds_write_b128 v131, v[68:71] offset:2048
	global_load_dwordx4 v[68:71], v120, s[52:53] offset:384
	ds_read_b128 v[104:107], v119 offset:35072
	v_mfma_f32_16x16x32_bf16 v[24:27], v[80:83], v[112:115], v[24:27]
	ds_read_b128 v[144:147], v119 offset:36096
	v_mfma_f32_16x16x32_bf16 v[20:23], v[80:83], v[136:139], v[20:23]
	ds_read_b128 v[148:151], v119 offset:41280
	v_mfma_f32_16x16x32_bf16 v[16:19], v[80:83], v[140:143], v[16:19]
	ds_read_b128 v[152:155], v119 offset:42304
	s_waitcnt lgkmcnt(3)
	v_mfma_f32_16x16x32_bf16 v[12:15], v[104:107], v[100:103], v[12:15]
	s_waitcnt vmcnt(7)
	ds_write_b128 v131, v[64:67] offset:4096
	global_load_dwordx4 v[64:67], v122, s[52:53] offset:384
	ds_read_b128 v[156:159], v119 offset:43328
	v_mfma_f32_16x16x32_bf16 v[8:11], v[104:107], v[112:115], v[8:11]
	ds_read_b128 v[80:83], v119 offset:44352
	v_mfma_f32_16x16x32_bf16 v[4:7], v[104:107], v[136:139], v[4:7]
	ds_read_b128 v[84:87], v130 offset:57792
	v_mfma_f32_16x16x32_bf16 v[0:3], v[104:107], v[140:143], v[0:3]
	s_waitcnt vmcnt(7)
	ds_write_b128 v131, v[72:75] offset:6144
	global_load_dwordx4 v[72:75], v124, s[52:53] offset:384
	ds_read_b128 v[104:107], v130 offset:58816
	s_waitcnt lgkmcnt(8)
	v_mfma_f32_16x16x32_bf16 v[100:103], v[144:147], v[100:103], v[88:91]
	ds_read_b128 v[108:111], v130 offset:59840
	v_mfma_f32_16x16x32_bf16 v[96:99], v[144:147], v[112:115], v[96:99]
	ds_read_b128 v[112:115], v130 offset:60864
	v_mfma_f32_16x16x32_bf16 v[92:95], v[144:147], v[136:139], v[92:95]
	v_mfma_f32_16x16x32_bf16 v[88:91], v[144:147], v[140:143], v[132:135]
	s_waitcnt vmcnt(7)
	ds_write_b128 v131, v[60:63] offset:16512
	global_load_dwordx4 v[60:63], v116, s[54:55] offset:384
	s_waitcnt lgkmcnt(5)
	v_mfma_f32_16x16x32_bf16 v[44:47], v[148:151], v[84:87], v[44:47]
	s_waitcnt lgkmcnt(3)
	v_mfma_f32_16x16x32_bf16 v[40:43], v[148:151], v[104:107], v[40:43]
	s_waitcnt lgkmcnt(2)
	v_mfma_f32_16x16x32_bf16 v[36:39], v[148:151], v[108:111], v[36:39]
	s_waitcnt vmcnt(7)
	ds_write_b128 v131, v[56:59] offset:18560
	global_load_dwordx4 v[56:59], v120, s[54:55] offset:384
	s_waitcnt lgkmcnt(2)
	v_mfma_f32_16x16x32_bf16 v[32:35], v[148:151], v[112:115], v[32:35]
	v_mfma_f32_16x16x32_bf16 v[28:31], v[152:155], v[84:87], v[28:31]
	v_mfma_f32_16x16x32_bf16 v[24:27], v[152:155], v[104:107], v[24:27]
	v_mfma_f32_16x16x32_bf16 v[20:23], v[152:155], v[108:111], v[20:23]
	s_waitcnt vmcnt(7)
	ds_write_b128 v131, v[52:55] offset:20608
	global_load_dwordx4 v[52:55], v122, s[54:55] offset:384
	v_mfma_f32_16x16x32_bf16 v[16:19], v[152:155], v[112:115], v[16:19]
	v_mfma_f32_16x16x32_bf16 v[12:15], v[156:159], v[84:87], v[12:15]
	v_mfma_f32_16x16x32_bf16 v[8:11], v[156:159], v[104:107], v[8:11]
	s_waitcnt vmcnt(7)
	ds_write_b128 v131, v[48:51] offset:22656
	global_load_dwordx4 v[48:51], v124, s[54:55] offset:384
	v_mfma_f32_16x16x32_bf16 v[4:7], v[156:159], v[108:111], v[4:7]
	v_mfma_f32_16x16x32_bf16 v[0:3], v[156:159], v[112:115], v[0:3]
	s_cmp_lt_u32 s15, 12
	s_mov_b32 s12, s15
	s_waitcnt lgkmcnt(0)
	s_barrier
	s_cbranch_scc1 .LBB0_1067
	ds_read_b128 v[148:151], v119
	ds_read_b128 v[132:135], v130 offset:16512
	ds_read_b128 v[136:139], v130 offset:17536
	ds_read_b128 v[140:143], v130 offset:18560
	ds_read_b128 v[144:147], v130 offset:19584
	v_mfma_f32_16x16x32_bf16 v[84:87], v[80:83], v[84:87], v[100:103]
	s_add_i32 s15, s12, 2
	s_add_i32 s12, s12, 4
	s_min_u32 s12, s12, 15
	v_mfma_f32_16x16x32_bf16 v[96:99], v[80:83], v[104:107], v[96:99]
	s_lshl_b32 s12, s12, 7
	s_add_u32 s52, s20, s12
	s_addc_u32 s53, s21, 0
	v_mfma_f32_16x16x32_bf16 v[92:95], v[80:83], v[108:111], v[92:95]
	v_mfma_f32_16x16x32_bf16 v[80:83], v[80:83], v[112:115], v[88:91]
	s_waitcnt lgkmcnt(3)
	v_mfma_f32_16x16x32_bf16 v[44:47], v[148:151], v[132:135], v[44:47]
	s_nop 0
	ds_read_b128 v[88:91], v119 offset:1024
	s_waitcnt lgkmcnt(3)
	v_mfma_f32_16x16x32_bf16 v[40:43], v[148:151], v[136:139], v[40:43]
	ds_read_b128 v[100:103], v119 offset:2048
	s_waitcnt lgkmcnt(3)
	v_mfma_f32_16x16x32_bf16 v[36:39], v[148:151], v[140:143], v[36:39]
	ds_read_b128 v[104:107], v119 offset:3072
	s_waitcnt lgkmcnt(3)
	v_mfma_f32_16x16x32_bf16 v[32:35], v[148:151], v[144:147], v[32:35]
	ds_read_b128 v[108:111], v119 offset:8256
	s_waitcnt lgkmcnt(3)
	v_mfma_f32_16x16x32_bf16 v[28:31], v[88:91], v[132:135], v[28:31]
	ds_read_b128 v[112:115], v119 offset:9280
	v_mfma_f32_16x16x32_bf16 v[24:27], v[88:91], v[136:139], v[24:27]
	ds_read_b128 v[148:151], v119 offset:10304
	v_mfma_f32_16x16x32_bf16 v[20:23], v[88:91], v[140:143], v[20:23]
	ds_read_b128 v[152:155], v119 offset:11328
	v_mfma_f32_16x16x32_bf16 v[16:19], v[88:91], v[144:147], v[16:19]
	ds_read_b128 v[88:91], v130 offset:24768
	s_waitcnt lgkmcnt(6)
; template <int WM, int WN> ...
;     ...
;   for (int n = 0; n < 4; ++n) fb0[n] = LDSF(cur + boff + n * 1024);
; #pragma unroll
;   for (int m = 0; m < 4; ++m) fa0[m] = LDSF(cur + aoff + m * 1024);
;   acc[3][0] = MFMA16(pa, pb0, acc[3][0]);
;   acc[3][1] = MFMA16(pa, pb1, acc[3][1]);
;   acc[3][2] = MFMA16(pa, pb2, acc[3][2]);
;   acc[3][3] = MFMA16(pa, pb3, acc[3][3]);
; #pragma unroll
;   for (int n = 0; n < 4; ++n) acc[0][n] = MFMA16(fa0[0], fb0[n], acc[0][n]);
; #pragma unroll
;   for (int m = 0; m < 4; ++m) fa1[m] = LDSF(cur + aoff + APAN + m * 1024);
; #pragma unroll
;   for (int n = 0; n < 4; ++n) acc[1][n] = MFMA16(fa0[1], fb0[n], acc[1][n]);
; #pragma unroll
;   for (int n = 0; n < 4; ++n) fb1[n] = LDSF(cur + boff + BPAN + n * 1024);
; #pragma unroll
;   for (int n = 0; n < 4; ++n) acc[2][n] = MFMA16(fa0[2], fb0[n], acc[2][n]);
;   *reinterpret_cast<uint4*>(nxt + wao) = a0;
;   *reinterpret_cast<uint4*>(nxt + wao + 32 * 64) = a1;
; #pragma unroll
;   for (int n = 0; n < 4; ++n) acc[3][n] = MFMA16(fa0[3], fb0[n], acc[3][n]);
;   *reinterpret_cast<uint4*>(nxt + wao + 64 * 64) = a2;
;   *reinterpret_cast<uint4*>(nxt + wao + 96 * 64) = a3;
; #pragma unroll
;   for (int n = 0; n < 4; ++n) acc[0][n] = MFMA16(fa1[0], fb1[n], acc[0][n]);
;   *reinterpret_cast<uint4*>(nxt + wbo) = b0;
;   *reinterpret_cast<uint4*>(nxt + wbo + 32 * 64) = b1;
; #pragma unroll
;   for (int n = 0; n < 4; ++n) acc[1][n] = MFMA16(fa1[1], fb1[n], acc[1][n]);
;   *reinterpret_cast<uint4*>(nxt + wbo + 64 * 64) = b2;
;   *reinterpret_cast<uint4*>(nxt + wbo + 96 * 64) = b3;
; #pragma unroll
;   for (int n = 0; n < 4; ++n) acc[2][n] = MFMA16(fa1[2], fb1[n], acc[2][n]);
;   pa = fa1[3];
;   pb0 = fb1[0]; pb1 = fb1[1]; pb2 = fb1[2]; pb3 = fb1[3];
;   SGB_(0x100, 5);
;   SGB_(0x008, 4);
; #pragma unroll
;   for (int i_ = 0; i_ < 11; ++i_) { SGB_(0x008, 1); SGB_(0x100, 1); }
; #pragma unroll
;   for (int i_ = 0; i_ < 8; ++i_) { SGB_(0x008, 2); SGB_(0x200, 1); SGB_(0x020, 1); }
;   SGB_(0x008, 1);
; template <int WM, int WN, typename SrcF, typename PostF>
; __device__ __forceinline__ void gemm_stream(const int nsteps, SrcF src, PostF post, f32x4 (&acc)[WM][WN], char* smem) {
;     ...
;     step_compute<WM, WN>(smem + STAGE, smem, acc, aoff, boff, wao, wbo, xa0, xa1, xa2, xa3, xb0, xb1, xb2, xb3, pa, pb0, pb1, pb2, pb3);
;     SB_;
;     post(kt + 1);
;     __syncthreads();
;   }
	v_mfma_f32_16x16x32_bf16 v[12:15], v[100:103], v[132:135], v[12:15]
	ds_read_b128 v[156:159], v130 offset:25792
	v_mfma_f32_16x16x32_bf16 v[8:11], v[100:103], v[136:139], v[8:11]
	ds_read_b128 v[160:163], v130 offset:26816
	v_mfma_f32_16x16x32_bf16 v[4:7], v[100:103], v[140:143], v[4:7]
	ds_read_b128 v[164:167], v130 offset:27840
	v_mfma_f32_16x16x32_bf16 v[0:3], v[100:103], v[144:147], v[0:3]
	s_waitcnt lgkmcnt(8)
	v_mfma_f32_16x16x32_bf16 v[84:87], v[104:107], v[132:135], v[84:87]
	s_waitcnt vmcnt(7)
	ds_write_b128 v131, v[76:79] offset:33024
	v_mfma_f32_16x16x32_bf16 v[96:99], v[104:107], v[136:139], v[96:99]
	v_mfma_f32_16x16x32_bf16 v[92:95], v[104:107], v[140:143], v[92:95]
	s_waitcnt vmcnt(6)
	ds_write_b128 v131, v[68:71] offset:35072
	v_mfma_f32_16x16x32_bf16 v[80:83], v[104:107], v[144:147], v[80:83]
	s_waitcnt lgkmcnt(5)
	v_mfma_f32_16x16x32_bf16 v[44:47], v[108:111], v[88:91], v[44:47]
	s_waitcnt vmcnt(5)
	ds_write_b128 v131, v[64:67] offset:37120
	s_add_u32 s52, s22, s12
	s_addc_u32 s53, s23, 0
	s_waitcnt lgkmcnt(5)
	v_mfma_f32_16x16x32_bf16 v[40:43], v[108:111], v[156:159], v[40:43]
	s_min_u32 s12, s15, 12
	s_lshl_b32 s12, s12, 7
	s_waitcnt lgkmcnt(4)
	v_mfma_f32_16x16x32_bf16 v[36:39], v[108:111], v[160:163], v[36:39]
	s_waitcnt vmcnt(4)
	ds_write_b128 v131, v[72:75] offset:39168
	s_waitcnt lgkmcnt(4)
	v_mfma_f32_16x16x32_bf16 v[32:35], v[108:111], v[164:167], v[32:35]
	v_mfma_f32_16x16x32_bf16 v[28:31], v[112:115], v[88:91], v[28:31]
	s_waitcnt vmcnt(3)
	ds_write_b128 v131, v[60:63] offset:49536
	v_mfma_f32_16x16x32_bf16 v[24:27], v[112:115], v[156:159], v[24:27]
	v_mfma_f32_16x16x32_bf16 v[20:23], v[112:115], v[160:163], v[20:23]
	s_waitcnt vmcnt(2)
	ds_write_b128 v131, v[56:59] offset:51584
	v_mfma_f32_16x16x32_bf16 v[16:19], v[112:115], v[164:167], v[16:19]
	v_mfma_f32_16x16x32_bf16 v[12:15], v[148:151], v[88:91], v[12:15]
	s_waitcnt vmcnt(1)
	ds_write_b128 v131, v[52:55] offset:53632
	v_mfma_f32_16x16x32_bf16 v[8:11], v[148:151], v[156:159], v[8:11]
	s_add_u32 s52, s20, s12
	s_addc_u32 s53, s21, 0
	s_add_u32 s54, s22, s12
	v_mfma_f32_16x16x32_bf16 v[4:7], v[148:151], v[160:163], v[4:7]
	s_waitcnt vmcnt(0)
	ds_write_b128 v131, v[48:51] offset:55680
	s_addc_u32 s55, s23, 0
	v_mfma_f32_16x16x32_bf16 v[0:3], v[148:151], v[164:167], v[0:3]
	v_mfma_f32_16x16x32_bf16 v[88:91], v[152:155], v[88:91], v[84:87]
	v_mfma_f32_16x16x32_bf16 v[96:99], v[152:155], v[156:159], v[96:99]
	v_mfma_f32_16x16x32_bf16 v[92:95], v[152:155], v[160:163], v[92:95]
	v_mfma_f32_16x16x32_bf16 v[132:135], v[152:155], v[164:167], v[80:83]
	s_waitcnt lgkmcnt(0)
	s_barrier
	s_nop 0
	ds_read_b128 v[80:83], v119 offset:33024
	ds_read_b128 v[100:103], v130 offset:49536
	ds_read_b128 v[112:115], v130 offset:50560
	ds_read_b128 v[136:139], v130 offset:51584
	ds_read_b128 v[140:143], v130 offset:52608
	s_waitcnt lgkmcnt(3)
	v_mfma_f32_16x16x32_bf16 v[44:47], v[80:83], v[100:103], v[44:47]
	s_waitcnt lgkmcnt(2)
	v_mfma_f32_16x16x32_bf16 v[40:43], v[80:83], v[112:115], v[40:43]
	s_waitcnt lgkmcnt(1)
	v_mfma_f32_16x16x32_bf16 v[36:39], v[80:83], v[136:139], v[36:39]
	s_waitcnt lgkmcnt(0)
	v_mfma_f32_16x16x32_bf16 v[32:35], v[80:83], v[140:143], v[32:35]
	ds_read_b128 v[80:83], v119 offset:34048
	s_waitcnt lgkmcnt(0)
	v_mfma_f32_16x16x32_bf16 v[28:31], v[80:83], v[100:103], v[28:31]
	ds_read_b128 v[104:107], v119 offset:35072
	v_mfma_f32_16x16x32_bf16 v[24:27], v[80:83], v[112:115], v[24:27]
	ds_read_b128 v[144:147], v119 offset:36096
	v_mfma_f32_16x16x32_bf16 v[20:23], v[80:83], v[136:139], v[20:23]
	ds_read_b128 v[148:151], v119 offset:41280
	v_mfma_f32_16x16x32_bf16 v[16:19], v[80:83], v[140:143], v[16:19]
	ds_read_b128 v[152:155], v119 offset:42304
	s_waitcnt lgkmcnt(3)
	v_mfma_f32_16x16x32_bf16 v[12:15], v[104:107], v[100:103], v[12:15]
	ds_read_b128 v[156:159], v119 offset:43328
	v_mfma_f32_16x16x32_bf16 v[8:11], v[104:107], v[112:115], v[8:11]
	ds_read_b128 v[80:83], v119 offset:44352
	v_mfma_f32_16x16x32_bf16 v[4:7], v[104:107], v[136:139], v[4:7]
	ds_read_b128 v[84:87], v130 offset:57792
	v_mfma_f32_16x16x32_bf16 v[0:3], v[104:107], v[140:143], v[0:3]
	ds_read_b128 v[104:107], v130 offset:58816
	s_waitcnt lgkmcnt(6)
	v_mfma_f32_16x16x32_bf16 v[100:103], v[144:147], v[100:103], v[88:91]
	ds_read_b128 v[108:111], v130 offset:59840
	v_mfma_f32_16x16x32_bf16 v[96:99], v[144:147], v[112:115], v[96:99]
	ds_read_b128 v[112:115], v130 offset:60864
	v_mfma_f32_16x16x32_bf16 v[92:95], v[144:147], v[136:139], v[92:95]
	v_mfma_f32_16x16x32_bf16 v[88:91], v[144:147], v[140:143], v[132:135]
	s_waitcnt lgkmcnt(3)
	v_mfma_f32_16x16x32_bf16 v[44:47], v[148:151], v[84:87], v[44:47]
	s_waitcnt lgkmcnt(2)
	v_mfma_f32_16x16x32_bf16 v[40:43], v[148:151], v[104:107], v[40:43]
	s_waitcnt lgkmcnt(1)
	v_mfma_f32_16x16x32_bf16 v[36:39], v[148:151], v[108:111], v[36:39]
	s_waitcnt lgkmcnt(0)
	v_mfma_f32_16x16x32_bf16 v[32:35], v[148:151], v[112:115], v[32:35]
	v_mfma_f32_16x16x32_bf16 v[28:31], v[152:155], v[84:87], v[28:31]
	v_mfma_f32_16x16x32_bf16 v[24:27], v[152:155], v[104:107], v[24:27]
	v_mfma_f32_16x16x32_bf16 v[20:23], v[152:155], v[108:111], v[20:23]
	v_mfma_f32_16x16x32_bf16 v[16:19], v[152:155], v[112:115], v[16:19]
	v_mfma_f32_16x16x32_bf16 v[12:15], v[156:159], v[84:87], v[12:15]
	v_mfma_f32_16x16x32_bf16 v[8:11], v[156:159], v[104:107], v[8:11]
	v_mfma_f32_16x16x32_bf16 v[4:7], v[156:159], v[108:111], v[4:7]
	v_mfma_f32_16x16x32_bf16 v[0:3], v[156:159], v[112:115], v[0:3]
	s_cmp_lt_u32 s15, 14
	s_mov_b32 s12, s15
	s_waitcnt lgkmcnt(0)
	s_barrier
; #define MFMA16(a, b, c) __builtin_amdgcn_mfma_f32_16x16x32_bf16(a, b, c, 0, 0, 0)
; template <int WM, int WN, typename SrcF, typename PostF>
; __device__ __forceinline__ void gemm_stream(const int nsteps, SrcF src, PostF post, f32x4 (&acc)[WM][WN], char* smem) {
;     ...
;   acc[3][0] = MFMA16(pa, pb0, acc[3][0]);
;   acc[3][1] = MFMA16(pa, pb1, acc[3][1]);
;   acc[3][2] = MFMA16(pa, pb2, acc[3][2]);
;   acc[3][3] = MFMA16(pa, pb3, acc[3][3]);
; __device__ void phase_inproj(const Params& p, int layer, char* smem) {
;     ...
;     const int row0 = rb * 128 + wr * 64, col0 = cb * 128 + wc * 64;
;     if (cb >= 12 && cb <= 16) {
; #pragma unroll
;       for (int m = 0; m < 4; ++m)
; #pragma unroll
;         for (int j = 0; j < 4; ++j) {
;           int row = row0 + m * 16 + fq * 4 + j;
;           int pos = row & (SEQ - 1);
; #pragma unroll
;           for (int n = 0; n < 2; ++n) {
;             float2 cs2 = RT[pos * 32 + n * 16 + fr];
;             float c = cs2.x, s = cs2.y;
;             float x1 = acc[m][n][j], x2 = acc[m][n + 2][j];
;             acc[m][n][j] = x1 * c - x2 * s;
;             acc[m][n + 2][j] = x2 * c + x1 * s;
;           }
;         }
	s_waitcnt vmcnt(3)
	v_mfma_f32_16x16x32_bf16 v[60:63], v[80:83], v[84:87], v[100:103]
	s_add_i32 s12, s16, -12
	s_cmp_gt_u32 s12, 4
	s_waitcnt vmcnt(2)
	v_mfma_f32_16x16x32_bf16 v[56:59], v[80:83], v[104:107], v[96:99]
	s_waitcnt vmcnt(1)
	v_mfma_f32_16x16x32_bf16 v[52:55], v[80:83], v[108:111], v[92:95]
	s_waitcnt vmcnt(0)
	v_mfma_f32_16x16x32_bf16 v[48:51], v[80:83], v[112:115], v[88:91]
	s_cbranch_scc1 .LBB0_1070
	v_lshl_add_u32 v64, s14, 7, v126
	v_and_or_b32 v64, v64, s39, v127
	v_lshl_or_b32 v116, v64, 8, v128
	v_lshl_add_u64 v[92:93], s[8:9], 0, v[116:117]
	v_add_co_u32_e32 v94, vcc, s43, v92
	global_load_dwordx2 v[68:69], v116, s[8:9]
	global_load_dwordx2 v[64:65], v116, s[8:9] offset:256
	global_load_dwordx2 v[66:67], v116, s[8:9] offset:384
	global_load_dwordx2 v[72:73], v116, s[8:9] offset:512
	global_load_dwordx2 v[76:77], v116, s[8:9] offset:128
	global_load_dwordx2 v[74:75], v116, s[8:9] offset:640
	global_load_dwordx2 v[70:71], v116, s[8:9] offset:768
	global_load_dwordx2 v[78:79], v116, s[8:9] offset:896
	v_addc_co_u32_e32 v95, vcc, 0, v93, vcc
	v_add_co_u32_e32 v96, vcc, s44, v92
	s_waitcnt vmcnt(7)
	v_mov_b32_e32 v124, v68
	v_addc_co_u32_e32 v97, vcc, 0, v93, vcc
	global_load_dwordx2 v[82:83], v[96:97], off offset:-4096
	global_load_dwordx2 v[80:81], v[94:95], off offset:256
	global_load_dwordx2 v[84:85], v[94:95], off offset:384
	global_load_dwordx2 v[88:89], v[94:95], off offset:512
	global_load_dwordx2 v[98:99], v[94:95], off offset:128
	global_load_dwordx2 v[90:91], v[94:95], off offset:640
	global_load_dwordx2 v[86:87], v[94:95], off offset:768
	s_waitcnt vmcnt(13)
	v_mov_b32_e32 v125, v64
	v_mov_b32_e32 v64, v69
	s_waitcnt vmcnt(10)
	v_mov_b32_e32 v68, v76
	v_mul_f32_e32 v76, v46, v72
	v_mul_f32_e32 v130, v38, v73
	v_mul_f32_e32 v72, v38, v72
	v_mul_f32_e32 v132, v46, v73
	s_waitcnt vmcnt(9)
	v_mul_f32_e32 v134, v42, v74
	v_mul_f32_e32 v138, v42, v75
	v_mov_b32_e32 v38, v47
	v_mov_b32_e32 v46, v39
	v_mov_b32_e32 v42, v35
	v_add_co_u32_e32 v92, vcc, s45, v92
	v_mov_b32_e32 v69, v66
	v_mov_b32_e32 v66, v77
	v_mul_f32_e32 v136, v34, v75
	v_mul_f32_e32 v74, v34, v74
	v_mov_b32_e32 v34, v43
	v_pk_mul_f32 v[140:141], v[44:45], v[64:65]
	v_pk_mul_f32 v[64:65], v[36:37], v[64:65]
	s_waitcnt vmcnt(8)
	v_pk_mul_f32 v[38:39], v[38:39], v[70:71]
	v_pk_mul_f32 v[46:47], v[46:47], v[70:71]
	s_waitcnt vmcnt(7)
	v_pk_mul_f32 v[42:43], v[42:43], v[78:79]
	v_addc_co_u32_e32 v93, vcc, 0, v93, vcc
	v_pk_mul_f32 v[142:143], v[40:41], v[66:67]
	v_pk_mul_f32 v[66:67], v[32:33], v[66:67]
	v_pk_mul_f32 v[34:35], v[34:35], v[78:79]
	v_mov_b32_e32 v77, v38
	v_mov_b32_e32 v131, v39
	v_pk_fma_f32 v[44:45], v[44:45], v[124:125], v[64:65] neg_lo:[0,0,1] neg_hi:[0,0,1]
	v_mov_b32_e32 v73, v46
	v_mov_b32_e32 v133, v47
	v_mov_b32_e32 v75, v42
	v_mov_b32_e32 v139, v43
	global_load_dwordx2 v[94:95], v[94:95], off offset:896
	s_nop 0
	global_load_dwordx2 v[100:101], v[96:97], off
	global_load_dwordx2 v[102:103], v[96:97], off offset:256
	global_load_dwordx2 v[104:105], v[96:97], off offset:384
	global_load_dwordx2 v[106:107], v[96:97], off offset:128
	global_load_dwordx2 v[108:109], v[96:97], off offset:512
	global_load_dwordx2 v[110:111], v[96:97], off offset:640
	global_load_dwordx2 v[112:113], v[96:97], off offset:768
	s_nop 0
	global_load_dwordx2 v[96:97], v[96:97], off offset:896
	s_nop 0
	global_load_dwordx2 v[114:115], v[92:93], off offset:640
	global_load_dwordx2 v[120:121], v[92:93], off offset:768
	global_load_dwordx2 v[122:123], v[92:93], off offset:896
	v_mov_b32_e32 v135, v34
	v_mov_b32_e32 v137, v35
	v_pk_fma_f32 v[40:41], v[40:41], v[68:69], v[66:67] neg_lo:[0,0,1] neg_hi:[0,0,1]
	v_pk_fma_f32 v[32:33], v[32:33], v[68:69], v[142:143]
	v_pk_add_f32 v[46:47], v[76:77], v[130:131] neg_lo:[0,1] neg_hi:[0,1]
	v_pk_add_f32 v[38:39], v[72:73], v[132:133]
	v_pk_add_f32 v[34:35], v[74:75], v[138:139]
	global_load_dwordx2 v[74:75], v[92:93], off
	global_load_dwordx2 v[76:77], v[92:93], off offset:256
	v_pk_fma_f32 v[36:37], v[36:37], v[124:125], v[140:141]
	v_pk_add_f32 v[42:43], v[134:135], v[136:137] neg_lo:[0,1] neg_hi:[0,1]
	s_waitcnt vmcnt(20)
	v_mov_b32_e32 v64, v82
	s_waitcnt vmcnt(19)
	v_mov_b32_e32 v65, v80
	v_mov_b32_e32 v80, v83
	s_waitcnt vmcnt(18)
	v_mov_b32_e32 v71, v84
	s_waitcnt vmcnt(16)
	v_mov_b32_e32 v84, v99
	v_pk_mul_f32 v[66:67], v[28:29], v[80:81]
	v_pk_mul_f32 v[68:69], v[20:21], v[80:81]
	v_pk_mul_f32 v[72:73], v[24:25], v[84:85]
	v_pk_mul_f32 v[78:79], v[16:17], v[84:85]
	global_load_dwordx2 v[80:81], v[92:93], off offset:384
	global_load_dwordx2 v[82:83], v[92:93], off offset:512
	global_load_dwordx2 v[84:85], v[92:93], off offset:128
	v_mov_b32_e32 v70, v98
	v_mul_f32_e32 v92, v30, v88
	v_mul_f32_e32 v98, v22, v89
	v_mul_f32_e32 v88, v22, v88
	v_mul_f32_e32 v124, v30, v89
	s_waitcnt vmcnt(18)
; __device__ void phase_inproj(const Params& p, int layer, char* smem) {
;     ...
;     if (cb >= 12 && cb <= 16) {
; #pragma unroll
;       for (int m = 0; m < 4; ++m)
; #pragma unroll
;         for (int j = 0; j < 4; ++j) {
;           int row = row0 + m * 16 + fq * 4 + j;
;           int pos = row & (SEQ - 1);
; #pragma unroll
;           for (int n = 0; n < 2; ++n) {
;             float2 cs2 = RT[pos * 32 + n * 16 + fr];
;             float c = cs2.x, s = cs2.y;
;             float x1 = acc[m][n][j], x2 = acc[m][n + 2][j];
;             acc[m][n][j] = x1 * c - x2 * s;
;             acc[m][n + 2][j] = x2 * c + x1 * s;
;           }
;         }
	v_mul_f32_e32 v130, v26, v90
	v_mul_f32_e32 v132, v18, v91
	v_mul_f32_e32 v90, v18, v90
	v_mul_f32_e32 v134, v26, v91
	v_mov_b32_e32 v22, v31
	v_mov_b32_e32 v30, v23
	v_mov_b32_e32 v18, v27
	v_mov_b32_e32 v26, v19
	s_waitcnt vmcnt(17)
	v_pk_mul_f32 v[136:137], v[22:23], v[86:87]
	v_pk_mul_f32 v[22:23], v[30:31], v[86:87]
	v_mov_b32_e32 v93, v136
	v_mov_b32_e32 v89, v22
	v_mov_b32_e32 v125, v23
	v_mov_b32_e32 v99, v137
	v_pk_add_f32 v[22:23], v[88:89], v[124:125]
	v_pk_fma_f32 v[24:25], v[24:25], v[70:71], v[78:79] neg_lo:[0,0,1] neg_hi:[0,0,1]
	v_pk_fma_f32 v[16:17], v[16:17], v[70:71], v[72:73]
	s_waitcnt vmcnt(16)
	v_pk_mul_f32 v[30:31], v[18:19], v[94:95]
	v_pk_mul_f32 v[18:19], v[26:27], v[94:95]
	s_waitcnt vmcnt(14)
	v_mov_b32_e32 v27, v102
	v_mov_b32_e32 v91, v18
	v_mov_b32_e32 v135, v19
	v_pk_add_f32 v[18:19], v[90:91], v[134:135]
	v_mov_b32_e32 v102, v101
	s_waitcnt vmcnt(13)
	v_mov_b32_e32 v71, v104
	s_waitcnt vmcnt(12)
	v_mov_b32_e32 v104, v107
	s_waitcnt vmcnt(11)
	v_mul_f32_e32 v88, v6, v109
	v_mul_f32_e32 v90, v6, v108
	v_mov_b32_e32 v6, v15
	v_pk_fma_f32 v[28:29], v[28:29], v[64:65], v[68:69] neg_lo:[0,0,1] neg_hi:[0,0,1]
	v_pk_add_f32 v[68:69], v[92:93], v[98:99] neg_lo:[0,1] neg_hi:[0,1]
	v_pk_fma_f32 v[20:21], v[20:21], v[64:65], v[66:67]
	v_mov_b32_e32 v26, v100
	v_pk_mul_f32 v[64:65], v[12:13], v[102:103]
	v_pk_mul_f32 v[66:67], v[4:5], v[102:103]
	v_mov_b32_e32 v70, v106
	v_pk_mul_f32 v[72:73], v[8:9], v[104:105]
	v_pk_mul_f32 v[78:79], v[0:1], v[104:105]
	v_mul_f32_e32 v86, v14, v108
	v_mul_f32_e32 v92, v14, v109
	s_waitcnt vmcnt(10)
	v_mul_f32_e32 v94, v10, v110
	v_mul_f32_e32 v98, v2, v111
	v_mul_f32_e32 v100, v2, v110
	v_mul_f32_e32 v102, v10, v111
	s_waitcnt vmcnt(9)
	v_pk_mul_f32 v[104:105], v[6:7], v[112:113]
	v_mov_b32_e32 v14, v7
	v_mov_b32_e32 v2, v11
	v_mov_b32_e32 v10, v3
	v_mov_b32_e32 v87, v104
	v_mov_b32_e32 v89, v105
	v_pk_mul_f32 v[6:7], v[14:15], v[112:113]
	s_waitcnt vmcnt(8)
	v_pk_mul_f32 v[14:15], v[2:3], v[96:97]
	v_pk_fma_f32 v[8:9], v[8:9], v[70:71], v[78:79] neg_lo:[0,0,1] neg_hi:[0,0,1]
	v_pk_mul_f32 v[2:3], v[10:11], v[96:97]
	v_pk_fma_f32 v[0:1], v[0:1], v[70:71], v[72:73]
	s_waitcnt vmcnt(3)
	v_mov_b32_e32 v11, v76
	v_mov_b32_e32 v76, v75
	v_pk_fma_f32 v[12:13], v[12:13], v[26:27], v[66:67] neg_lo:[0,0,1] neg_hi:[0,0,1]
	v_pk_add_f32 v[66:67], v[86:87], v[88:89] neg_lo:[0,1] neg_hi:[0,1]
	v_mov_b32_e32 v91, v6
	v_mov_b32_e32 v93, v7
	v_pk_fma_f32 v[4:5], v[4:5], v[26:27], v[64:65]
	v_mov_b32_e32 v10, v74
	v_pk_mul_f32 v[26:27], v[60:61], v[76:77]
	v_pk_mul_f32 v[64:65], v[52:53], v[76:77]
	v_mul_f32_e32 v86, v50, v115
	v_mul_f32_e32 v88, v50, v114
	v_mov_b32_e32 v50, v59
	v_pk_add_f32 v[6:7], v[90:91], v[92:93]
	v_mul_f32_e32 v90, v58, v115
	v_pk_fma_f32 v[60:61], v[60:61], v[10:11], v[64:65] neg_lo:[0,0,1] neg_hi:[0,0,1]
	v_pk_fma_f32 v[52:53], v[52:53], v[10:11], v[26:27]
	s_waitcnt vmcnt(2)
	v_mov_b32_e32 v71, v80
	s_waitcnt vmcnt(1)
	v_mul_f32_e32 v78, v54, v83
	s_waitcnt vmcnt(0)
	v_mov_b32_e32 v80, v85
	v_pk_mul_f32 v[72:73], v[56:57], v[80:81]
	v_pk_mul_f32 v[74:75], v[48:49], v[80:81]
	v_mul_f32_e32 v80, v54, v82
	v_mov_b32_e32 v54, v63
	v_mov_b32_e32 v70, v84
	v_mul_f32_e32 v76, v62, v82
	v_mul_f32_e32 v82, v62, v83
	v_mul_f32_e32 v84, v58, v114
	v_pk_mul_f32 v[92:93], v[54:55], v[120:121]
	v_mov_b32_e32 v62, v55
	v_pk_mul_f32 v[10:11], v[50:51], v[122:123]
	v_mov_b32_e32 v58, v51
	v_mov_b32_e32 v131, v30
	v_mov_b32_e32 v133, v31
	v_mov_b32_e32 v95, v14
	v_mov_b32_e32 v99, v15
	v_mov_b32_e32 v77, v92
	v_mov_b32_e32 v79, v93
	v_pk_mul_f32 v[54:55], v[62:63], v[120:121]
	v_mov_b32_e32 v85, v10
	v_mov_b32_e32 v87, v11
	v_pk_mul_f32 v[26:27], v[58:59], v[122:123]
	v_pk_add_f32 v[30:31], v[130:131], v[132:133] neg_lo:[0,1] neg_hi:[0,1]
	v_pk_add_f32 v[14:15], v[94:95], v[98:99] neg_lo:[0,1] neg_hi:[0,1]
	v_mov_b32_e32 v101, v2
	v_mov_b32_e32 v103, v3
	v_pk_add_f32 v[64:65], v[76:77], v[78:79] neg_lo:[0,1] neg_hi:[0,1]
	v_mov_b32_e32 v81, v54
	v_mov_b32_e32 v83, v55
	v_pk_add_f32 v[10:11], v[84:85], v[86:87] neg_lo:[0,1] neg_hi:[0,1]
	v_mov_b32_e32 v89, v26
	v_mov_b32_e32 v91, v27
	v_pk_add_f32 v[2:3], v[100:101], v[102:103]
	v_pk_add_f32 v[54:55], v[80:81], v[82:83]
	v_pk_fma_f32 v[56:57], v[56:57], v[70:71], v[74:75] neg_lo:[0,0,1] neg_hi:[0,0,1]
	v_pk_fma_f32 v[48:49], v[48:49], v[70:71], v[72:73]
	v_pk_add_f32 v[50:51], v[88:89], v[90:91]
	v_mov_b32_e32 v58, v10
	v_mov_b32_e32 v59, v11
	v_mov_b32_e32 v62, v64
	v_mov_b32_e32 v63, v65
	v_mov_b32_e32 v10, v14
	v_mov_b32_e32 v11, v15
	v_mov_b32_e32 v14, v66
	v_mov_b32_e32 v15, v67
	v_mov_b32_e32 v26, v30
	v_mov_b32_e32 v27, v31
	v_mov_b32_e32 v30, v68
	v_mov_b32_e32 v31, v69

; template <int WM, int WN> ...
;     ...
;   for (int n = 0; n < 4; ++n) fb0[n] = LDSF(cur + boff + n * 1024);
; #pragma unroll
;   for (int m = 0; m < 4; ++m) fa0[m] = LDSF(cur + aoff + m * 1024);
;   acc[3][0] = MFMA16(pa, pb0, acc[3][0]);
;   acc[3][1] = MFMA16(pa, pb1, acc[3][1]);
;   acc[3][2] = MFMA16(pa, pb2, acc[3][2]);
;   acc[3][3] = MFMA16(pa, pb3, acc[3][3]);
; #pragma unroll
;   for (int n = 0; n < 4; ++n) acc[0][n] = MFMA16(fa0[0], fb0[n], acc[0][n]);
; #pragma unroll
;   for (int m = 0; m < 4; ++m) fa1[m] = LDSF(cur + aoff + APAN + m * 1024);
; #pragma unroll
;   for (int n = 0; n < 4; ++n) acc[1][n] = MFMA16(fa0[1], fb0[n], acc[1][n]);
; #pragma unroll
;   for (int n = 0; n < 4; ++n) fb1[n] = LDSF(cur + boff + BPAN + n * 1024);
; #pragma unroll
;   for (int n = 0; n < 4; ++n) acc[2][n] = MFMA16(fa0[2], fb0[n], acc[2][n]);
;   *reinterpret_cast<uint4*>(nxt + wao) = a0;
;   *reinterpret_cast<uint4*>(nxt + wao + 32 * 64) = a1;
; #pragma unroll
;   for (int n = 0; n < 4; ++n) acc[3][n] = MFMA16(fa0[3], fb0[n], acc[3][n]);
;   *reinterpret_cast<uint4*>(nxt + wao + 64 * 64) = a2;
;   *reinterpret_cast<uint4*>(nxt + wao + 96 * 64) = a3;
; #pragma unroll
;   for (int n = 0; n < 4; ++n) acc[0][n] = MFMA16(fa1[0], fb1[n], acc[0][n]);
;   *reinterpret_cast<uint4*>(nxt + wbo) = b0;
;   *reinterpret_cast<uint4*>(nxt + wbo + 32 * 64) = b1;
; #pragma unroll
;   for (int n = 0; n < 4; ++n) acc[1][n] = MFMA16(fa1[1], fb1[n], acc[1][n]);
;   *reinterpret_cast<uint4*>(nxt + wbo + 64 * 64) = b2;
;   *reinterpret_cast<uint4*>(nxt + wbo + 96 * 64) = b3;
; #pragma unroll
;   for (int n = 0; n < 4; ++n) acc[2][n] = MFMA16(fa1[2], fb1[n], acc[2][n]);
;   pa = fa1[3];
;   pb0 = fb1[0]; pb1 = fb1[1]; pb2 = fb1[2]; pb3 = fb1[3];
;   SGB_(0x100, 5);
;   SGB_(0x008, 4);
; #pragma unroll
;   for (int i_ = 0; i_ < 11; ++i_) { SGB_(0x008, 1); SGB_(0x100, 1); }
; #pragma unroll
; template <int WM, int WN, typename SrcF, typename PostF>
; __device__ __forceinline__ void gemm_stream(const int nsteps, SrcF src, PostF post, f32x4 (&acc)[WM][WN], char* smem) {
;     ...
;   for (int kt = 0; kt < nsteps; kt += 2) {
;     {
;       TileSrc s = src(min(kt + 2, nsteps - 1));
;       GLOAD_TILE(xa, s.a, s.lda, ACH);
;       GLOAD_TILE(xb, s.b, s.ldb, BCH);
;     }
;     step_compute<WM, WN>(smem, smem + STAGE, acc, aoff, boff, wao, wbo, ya0, ya1, ya2, ya3, yb0, yb1, yb2, yb3, pa, pb0, pb1, pb2, pb3);
.LBB0_1281:
	s_add_i32 s27, s5, 2
	s_add_i32 s5, s5, 4
	s_min_u32 s5, s5, 15
	s_lshl_b32 s5, s5, 7
	s_add_u32 s92, s8, s5
	s_addc_u32 s93, s9, 0
	s_add_u32 s94, s10, s5
	s_addc_u32 s95, s11, 0
	ds_read_b128 v[144:147], v124
	ds_read_b128 v[128:131], v125 offset:16512
	ds_read_b128 v[132:135], v125 offset:17536
	ds_read_b128 v[136:139], v125 offset:18560
	ds_read_b128 v[140:143], v125 offset:19584
	v_mfma_f32_16x16x32_bf16 v[64:67], v[48:51], v[64:67], v[92:95]
	v_mfma_f32_16x16x32_bf16 v[88:91], v[48:51], v[104:107], v[88:91]
	s_waitcnt vmcnt(7)
	ds_write_b128 v126, v[32:35] offset:33024
	global_load_dwordx4 v[32:35], v116, s[92:93]
	s_add_u32 s34, s8, s5
	s_addc_u32 s35, s9, 0
	v_mfma_f32_16x16x32_bf16 v[80:83], v[48:51], v[112:115], v[80:83]
	v_mfma_f32_16x16x32_bf16 v[48:51], v[48:51], v[108:111], v[56:59]
	s_waitcnt lgkmcnt(4)
	v_mfma_f32_16x16x32_bf16 v[56:59], v[144:147], v[128:131], v[100:103]
	ds_read_b128 v[92:95], v124 offset:1024
	s_waitcnt lgkmcnt(4)
	v_mfma_f32_16x16x32_bf16 v[96:99], v[144:147], v[132:135], v[96:99]
	s_waitcnt vmcnt(7)
	ds_write_b128 v126, v[20:23] offset:35072
	global_load_dwordx4 v[20:23], v118, s[92:93]
	ds_read_b128 v[100:103], v124 offset:2048
	s_waitcnt lgkmcnt(5)
	v_mfma_f32_16x16x32_bf16 v[84:87], v[144:147], v[136:139], v[84:87]
	ds_read_b128 v[104:107], v124 offset:3072
	s_waitcnt lgkmcnt(5)
	v_mfma_f32_16x16x32_bf16 v[76:79], v[144:147], v[140:143], v[76:79]
	ds_read_b128 v[108:111], v124 offset:8256
	s_waitcnt lgkmcnt(4)
	v_mfma_f32_16x16x32_bf16 v[72:75], v[92:95], v[128:131], v[72:75]
	ds_read_b128 v[112:115], v124 offset:9280
	v_mfma_f32_16x16x32_bf16 v[68:71], v[92:95], v[132:135], v[68:71]
	ds_read_b128 v[144:147], v124 offset:10304
	v_mfma_f32_16x16x32_bf16 v[60:63], v[92:95], v[136:139], v[60:63]
	s_waitcnt vmcnt(7)
	ds_write_b128 v126, v[16:19] offset:37120
	global_load_dwordx4 v[16:19], v120, s[92:93]
	ds_read_b128 v[148:151], v124 offset:11328
	v_mfma_f32_16x16x32_bf16 v[52:55], v[92:95], v[140:143], v[52:55]
	ds_read_b128 v[92:95], v125 offset:24768
	s_waitcnt lgkmcnt(7)
	v_mfma_f32_16x16x32_bf16 v[44:47], v[100:103], v[128:131], v[44:47]
	ds_read_b128 v[152:155], v125 offset:25792
	v_mfma_f32_16x16x32_bf16 v[40:43], v[100:103], v[132:135], v[40:43]
	ds_read_b128 v[156:159], v125 offset:26816
	v_mfma_f32_16x16x32_bf16 v[36:39], v[100:103], v[136:139], v[36:39]
	s_waitcnt vmcnt(7)
	ds_write_b128 v126, v[24:27] offset:39168
	global_load_dwordx4 v[24:27], v122, s[92:93]
	ds_read_b128 v[160:163], v125 offset:27840
	v_mfma_f32_16x16x32_bf16 v[28:31], v[100:103], v[140:143], v[28:31]
	s_waitcnt lgkmcnt(10)
	v_mfma_f32_16x16x32_bf16 v[64:67], v[104:107], v[128:131], v[64:67]
	v_mfma_f32_16x16x32_bf16 v[88:91], v[104:107], v[132:135], v[88:91]
	v_mfma_f32_16x16x32_bf16 v[80:83], v[104:107], v[136:139], v[80:83]
	v_mfma_f32_16x16x32_bf16 v[48:51], v[104:107], v[140:143], v[48:51]
	s_waitcnt vmcnt(7)
	ds_write_b128 v126, v[12:15] offset:49536
	global_load_dwordx4 v[12:15], v116, s[94:95]
	s_waitcnt lgkmcnt(5)
	v_mfma_f32_16x16x32_bf16 v[56:59], v[108:111], v[92:95], v[56:59]
	s_add_u32 s34, s10, s5
	s_addc_u32 s35, s11, 0
	s_waitcnt lgkmcnt(4)
	v_mfma_f32_16x16x32_bf16 v[96:99], v[108:111], v[152:155], v[96:99]
	s_min_u32 s5, s27, 12
	s_lshl_b32 s5, s5, 7
	s_waitcnt lgkmcnt(3)
	v_mfma_f32_16x16x32_bf16 v[84:87], v[108:111], v[156:159], v[84:87]
	s_waitcnt lgkmcnt(1)
	v_mfma_f32_16x16x32_bf16 v[76:79], v[108:111], v[160:163], v[76:79]
	s_waitcnt vmcnt(7)
	ds_write_b128 v126, v[8:11] offset:51584
	global_load_dwordx4 v[8:11], v118, s[94:95]
	v_mfma_f32_16x16x32_bf16 v[72:75], v[112:115], v[92:95], v[72:75]
	v_mfma_f32_16x16x32_bf16 v[68:71], v[112:115], v[152:155], v[68:71]
	v_mfma_f32_16x16x32_bf16 v[60:63], v[112:115], v[156:159], v[60:63]
	v_mfma_f32_16x16x32_bf16 v[52:55], v[112:115], v[160:163], v[52:55]
	v_mfma_f32_16x16x32_bf16 v[44:47], v[144:147], v[92:95], v[44:47]
	s_waitcnt vmcnt(7)
	ds_write_b128 v126, v[4:7] offset:53632
	global_load_dwordx4 v[4:7], v120, s[94:95]
	v_mfma_f32_16x16x32_bf16 v[40:43], v[144:147], v[152:155], v[40:43]
	s_add_u32 s34, s8, s5
	s_addc_u32 s35, s9, 0
	s_add_u32 s36, s10, s5
	v_mfma_f32_16x16x32_bf16 v[36:39], v[144:147], v[156:159], v[36:39]
	s_addc_u32 s37, s11, 0
	v_mfma_f32_16x16x32_bf16 v[28:31], v[144:147], v[160:163], v[28:31]
	v_mfma_f32_16x16x32_bf16 v[92:95], v[148:151], v[92:95], v[64:67]
	s_waitcnt vmcnt(7)
	ds_write_b128 v126, v[0:3] offset:55680
	global_load_dwordx4 v[0:3], v122, s[94:95]
	v_mfma_f32_16x16x32_bf16 v[88:91], v[148:151], v[152:155], v[88:91]
	v_mfma_f32_16x16x32_bf16 v[80:83], v[148:151], v[156:159], v[80:83]
	v_mfma_f32_16x16x32_bf16 v[100:103], v[148:151], v[160:163], v[48:51]
	s_waitcnt lgkmcnt(0)
	s_barrier
; #define MFMA16(a, b, c) __builtin_amdgcn_mfma_f32_16x16x32_bf16(a, b, c, 0, 0, 0)
; template <int WM, int WN> ...
;     ...
;   for (int n = 0; n < 4; ++n) fb0[n] = LDSF(cur + boff + n * 1024);
; #pragma unroll
;   for (int m = 0; m < 4; ++m) fa0[m] = LDSF(cur + aoff + m * 1024);
;   acc[3][0] = MFMA16(pa, pb0, acc[3][0]);
;   acc[3][1] = MFMA16(pa, pb1, acc[3][1]);
;   acc[3][2] = MFMA16(pa, pb2, acc[3][2]);
;   acc[3][3] = MFMA16(pa, pb3, acc[3][3]);
; #pragma unroll
;   for (int n = 0; n < 4; ++n) acc[0][n] = MFMA16(fa0[0], fb0[n], acc[0][n]);
; #pragma unroll
;   for (int m = 0; m < 4; ++m) fa1[m] = LDSF(cur + aoff + APAN + m * 1024);
; #pragma unroll
;   for (int n = 0; n < 4; ++n) acc[1][n] = MFMA16(fa0[1], fb0[n], acc[1][n]);
; #pragma unroll
;   for (int n = 0; n < 4; ++n) fb1[n] = LDSF(cur + boff + BPAN + n * 1024);
; #pragma unroll
;   for (int n = 0; n < 4; ++n) acc[2][n] = MFMA16(fa0[2], fb0[n], acc[2][n]);
;   *reinterpret_cast<uint4*>(nxt + wao) = a0;
;   *reinterpret_cast<uint4*>(nxt + wao + 32 * 64) = a1;
; #pragma unroll
;   for (int n = 0; n < 4; ++n) acc[3][n] = MFMA16(fa0[3], fb0[n], acc[3][n]);
;   *reinterpret_cast<uint4*>(nxt + wao + 64 * 64) = a2;
;   *reinterpret_cast<uint4*>(nxt + wao + 96 * 64) = a3;
; #pragma unroll
;   for (int n = 0; n < 4; ++n) acc[0][n] = MFMA16(fa1[0], fb1[n], acc[0][n]);
;   *reinterpret_cast<uint4*>(nxt + wbo) = b0;
;   *reinterpret_cast<uint4*>(nxt + wbo + 32 * 64) = b1;
; #pragma unroll
;   for (int n = 0; n < 4; ++n) acc[1][n] = MFMA16(fa1[1], fb1[n], acc[1][n]);
;   *reinterpret_cast<uint4*>(nxt + wbo + 64 * 64) = b2;
;   *reinterpret_cast<uint4*>(nxt + wbo + 96 * 64) = b3;
; #pragma unroll
;   for (int n = 0; n < 4; ++n) acc[2][n] = MFMA16(fa1[2], fb1[n], acc[2][n]);
;   pa = fa1[3];
;   pb0 = fb1[0]; pb1 = fb1[1]; pb2 = fb1[2]; pb3 = fb1[3];
;   SGB_(0x100, 5);
;   SGB_(0x008, 4);
; #pragma unroll
;   for (int i_ = 0; i_ < 11; ++i_) { SGB_(0x008, 1); SGB_(0x100, 1); }
; #pragma unroll
;   for (int i_ = 0; i_ < 8; ++i_) { SGB_(0x008, 2); SGB_(0x200, 1); SGB_(0x020, 1); }
;   SGB_(0x008, 1);
; template <int WM, int WN, typename SrcF, typename PostF>
; __device__ __forceinline__ void gemm_stream(const int nsteps, SrcF src, PostF post, f32x4 (&acc)[WM][WN], char* smem) {
;     ...
;       TileSrc s = src(min(kt + 3, nsteps - 1));
;       GLOAD_TILE(ya, s.a, s.lda, ACH);
;       GLOAD_TILE(yb, s.b, s.ldb, BCH);
;     }
	s_nop 0
	ds_read_b128 v[48:51], v124 offset:33024
	ds_read_b128 v[108:111], v125 offset:49536
	ds_read_b128 v[128:131], v125 offset:50560
	ds_read_b128 v[132:135], v125 offset:51584
	ds_read_b128 v[136:139], v125 offset:52608
	s_waitcnt lgkmcnt(3)
	v_mfma_f32_16x16x32_bf16 v[140:143], v[48:51], v[108:111], v[56:59]
	s_waitcnt lgkmcnt(2)
	v_mfma_f32_16x16x32_bf16 v[96:99], v[48:51], v[128:131], v[96:99]
	s_waitcnt vmcnt(7)
	ds_write_b128 v126, v[32:35]
	global_load_dwordx4 v[32:35], v116, s[34:35] offset:384
	s_waitcnt lgkmcnt(2)
	v_mfma_f32_16x16x32_bf16 v[84:87], v[48:51], v[132:135], v[84:87]
	s_waitcnt lgkmcnt(0)
	v_mfma_f32_16x16x32_bf16 v[76:79], v[48:51], v[136:139], v[76:79]
	ds_read_b128 v[48:51], v124 offset:34048
	s_waitcnt lgkmcnt(0)
	v_mfma_f32_16x16x32_bf16 v[72:75], v[48:51], v[108:111], v[72:75]
	s_waitcnt vmcnt(7)
	ds_write_b128 v126, v[20:23] offset:2048
	global_load_dwordx4 v[20:23], v118, s[34:35] offset:384
	ds_read_b128 v[56:59], v124 offset:35072
	v_mfma_f32_16x16x32_bf16 v[68:71], v[48:51], v[128:131], v[68:71]
	ds_read_b128 v[144:147], v124 offset:36096
	v_mfma_f32_16x16x32_bf16 v[60:63], v[48:51], v[132:135], v[60:63]
	ds_read_b128 v[148:151], v124 offset:41280
	v_mfma_f32_16x16x32_bf16 v[52:55], v[48:51], v[136:139], v[52:55]
	ds_read_b128 v[152:155], v124 offset:42304
	s_waitcnt lgkmcnt(3)
	v_mfma_f32_16x16x32_bf16 v[44:47], v[56:59], v[108:111], v[44:47]
	s_waitcnt vmcnt(7)
	ds_write_b128 v126, v[16:19] offset:4096
	global_load_dwordx4 v[16:19], v120, s[34:35] offset:384
	ds_read_b128 v[156:159], v124 offset:43328
	v_mfma_f32_16x16x32_bf16 v[40:43], v[56:59], v[128:131], v[40:43]
	ds_read_b128 v[48:51], v124 offset:44352
	v_mfma_f32_16x16x32_bf16 v[36:39], v[56:59], v[132:135], v[36:39]
	ds_read_b128 v[64:67], v125 offset:57792
	v_mfma_f32_16x16x32_bf16 v[28:31], v[56:59], v[136:139], v[28:31]
	s_waitcnt vmcnt(7)
	ds_write_b128 v126, v[24:27] offset:6144
	global_load_dwordx4 v[24:27], v122, s[34:35] offset:384
	ds_read_b128 v[104:107], v125 offset:58816
	s_waitcnt lgkmcnt(8)
	v_mfma_f32_16x16x32_bf16 v[92:95], v[144:147], v[108:111], v[92:95]
	ds_read_b128 v[112:115], v125 offset:59840
	v_mfma_f32_16x16x32_bf16 v[88:91], v[144:147], v[128:131], v[88:91]
	ds_read_b128 v[108:111], v125 offset:60864
	v_mfma_f32_16x16x32_bf16 v[80:83], v[144:147], v[132:135], v[80:83]
	v_mfma_f32_16x16x32_bf16 v[56:59], v[144:147], v[136:139], v[100:103]
	s_waitcnt vmcnt(7)
	ds_write_b128 v126, v[12:15] offset:16512
	global_load_dwordx4 v[12:15], v116, s[36:37] offset:384
	s_waitcnt lgkmcnt(5)
	v_mfma_f32_16x16x32_bf16 v[100:103], v[148:151], v[64:67], v[140:143]
	s_waitcnt lgkmcnt(3)
	v_mfma_f32_16x16x32_bf16 v[96:99], v[148:151], v[104:107], v[96:99]
	s_waitcnt lgkmcnt(2)
	v_mfma_f32_16x16x32_bf16 v[84:87], v[148:151], v[112:115], v[84:87]
	s_waitcnt vmcnt(7)
	ds_write_b128 v126, v[8:11] offset:18560
	global_load_dwordx4 v[8:11], v118, s[36:37] offset:384
	s_waitcnt lgkmcnt(2)
	v_mfma_f32_16x16x32_bf16 v[76:79], v[148:151], v[108:111], v[76:79]
	v_mfma_f32_16x16x32_bf16 v[72:75], v[152:155], v[64:67], v[72:75]
	v_mfma_f32_16x16x32_bf16 v[68:71], v[152:155], v[104:107], v[68:71]
	v_mfma_f32_16x16x32_bf16 v[60:63], v[152:155], v[112:115], v[60:63]
	s_waitcnt vmcnt(7)
	ds_write_b128 v126, v[4:7] offset:20608
	global_load_dwordx4 v[4:7], v120, s[36:37] offset:384
	v_mfma_f32_16x16x32_bf16 v[52:55], v[152:155], v[108:111], v[52:55]
	v_mfma_f32_16x16x32_bf16 v[44:47], v[156:159], v[64:67], v[44:47]
	v_mfma_f32_16x16x32_bf16 v[40:43], v[156:159], v[104:107], v[40:43]
	s_waitcnt vmcnt(7)
	ds_write_b128 v126, v[0:3] offset:22656
	global_load_dwordx4 v[0:3], v122, s[36:37] offset:384
	v_mfma_f32_16x16x32_bf16 v[36:39], v[156:159], v[112:115], v[36:39]
	v_mfma_f32_16x16x32_bf16 v[28:31], v[156:159], v[108:111], v[28:31]
	s_cmp_lt_u32 s27, 12
	s_mov_b32 s5, s27
	s_waitcnt lgkmcnt(0)
	s_barrier
	s_cbranch_scc1 .LBB0_1281
	ds_read_b128 v[144:147], v124
	ds_read_b128 v[128:131], v125 offset:16512
	ds_read_b128 v[132:135], v125 offset:17536
	ds_read_b128 v[136:139], v125 offset:18560
	ds_read_b128 v[140:143], v125 offset:19584
	v_mfma_f32_16x16x32_bf16 v[64:67], v[48:51], v[64:67], v[92:95]
	s_add_i32 s27, s5, 2
	s_add_i32 s5, s5, 4
	s_min_u32 s5, s5, 15
	v_mfma_f32_16x16x32_bf16 v[88:91], v[48:51], v[104:107], v[88:91]
	s_lshl_b32 s5, s5, 7
	s_add_u32 s34, s8, s5
	s_addc_u32 s35, s9, 0
	v_mfma_f32_16x16x32_bf16 v[80:83], v[48:51], v[112:115], v[80:83]
	v_mfma_f32_16x16x32_bf16 v[48:51], v[48:51], v[108:111], v[56:59]
	s_waitcnt lgkmcnt(3)
	v_mfma_f32_16x16x32_bf16 v[56:59], v[144:147], v[128:131], v[100:103]
	ds_read_b128 v[92:95], v124 offset:1024
	s_waitcnt lgkmcnt(3)
	v_mfma_f32_16x16x32_bf16 v[96:99], v[144:147], v[132:135], v[96:99]
	ds_read_b128 v[100:103], v124 offset:2048
	s_waitcnt lgkmcnt(3)
	v_mfma_f32_16x16x32_bf16 v[84:87], v[144:147], v[136:139], v[84:87]
	ds_read_b128 v[104:107], v124 offset:3072
	s_waitcnt lgkmcnt(3)
	v_mfma_f32_16x16x32_bf16 v[76:79], v[144:147], v[140:143], v[76:79]
	ds_read_b128 v[108:111], v124 offset:8256
	s_waitcnt lgkmcnt(3)
	v_mfma_f32_16x16x32_bf16 v[72:75], v[92:95], v[128:131], v[72:75]
	ds_read_b128 v[112:115], v124 offset:9280
	v_mfma_f32_16x16x32_bf16 v[68:71], v[92:95], v[132:135], v[68:71]
	ds_read_b128 v[144:147], v124 offset:10304
	v_mfma_f32_16x16x32_bf16 v[60:63], v[92:95], v[136:139], v[60:63]
	ds_read_b128 v[148:151], v124 offset:11328
	v_mfma_f32_16x16x32_bf16 v[52:55], v[92:95], v[140:143], v[52:55]
	ds_read_b128 v[92:95], v125 offset:24768
	s_waitcnt lgkmcnt(6)
; template <int WM, int WN> ...
;     ...
;   for (int n = 0; n < 4; ++n) fb0[n] = LDSF(cur + boff + n * 1024);
; #pragma unroll
;   for (int m = 0; m < 4; ++m) fa0[m] = LDSF(cur + aoff + m * 1024);
;   acc[3][0] = MFMA16(pa, pb0, acc[3][0]);
;   acc[3][1] = MFMA16(pa, pb1, acc[3][1]);
;   acc[3][2] = MFMA16(pa, pb2, acc[3][2]);
;   acc[3][3] = MFMA16(pa, pb3, acc[3][3]);
; #pragma unroll
;   for (int n = 0; n < 4; ++n) acc[0][n] = MFMA16(fa0[0], fb0[n], acc[0][n]);
; #pragma unroll
;   for (int m = 0; m < 4; ++m) fa1[m] = LDSF(cur + aoff + APAN + m * 1024);
; #pragma unroll
;   for (int n = 0; n < 4; ++n) acc[1][n] = MFMA16(fa0[1], fb0[n], acc[1][n]);
; #pragma unroll
;   for (int n = 0; n < 4; ++n) fb1[n] = LDSF(cur + boff + BPAN + n * 1024);
; #pragma unroll
;   for (int n = 0; n < 4; ++n) acc[2][n] = MFMA16(fa0[2], fb0[n], acc[2][n]);
;   *reinterpret_cast<uint4*>(nxt + wao) = a0;
;   *reinterpret_cast<uint4*>(nxt + wao + 32 * 64) = a1;
; #pragma unroll
;   for (int n = 0; n < 4; ++n) acc[3][n] = MFMA16(fa0[3], fb0[n], acc[3][n]);
;   *reinterpret_cast<uint4*>(nxt + wao + 64 * 64) = a2;
;   *reinterpret_cast<uint4*>(nxt + wao + 96 * 64) = a3;
; #pragma unroll
;   for (int n = 0; n < 4; ++n) acc[0][n] = MFMA16(fa1[0], fb1[n], acc[0][n]);
;   *reinterpret_cast<uint4*>(nxt + wbo) = b0;
;   *reinterpret_cast<uint4*>(nxt + wbo + 32 * 64) = b1;
; #pragma unroll
;   for (int n = 0; n < 4; ++n) acc[1][n] = MFMA16(fa1[1], fb1[n], acc[1][n]);
;   *reinterpret_cast<uint4*>(nxt + wbo + 64 * 64) = b2;
;   *reinterpret_cast<uint4*>(nxt + wbo + 96 * 64) = b3;
; #pragma unroll
;   for (int n = 0; n < 4; ++n) acc[2][n] = MFMA16(fa1[2], fb1[n], acc[2][n]);
;   pa = fa1[3];
;   pb0 = fb1[0]; pb1 = fb1[1]; pb2 = fb1[2]; pb3 = fb1[3];
;   SGB_(0x100, 5);
;   SGB_(0x008, 4);
; #pragma unroll
;   for (int i_ = 0; i_ < 11; ++i_) { SGB_(0x008, 1); SGB_(0x100, 1); }
; #pragma unroll
;   for (int i_ = 0; i_ < 8; ++i_) { SGB_(0x008, 2); SGB_(0x200, 1); SGB_(0x020, 1); }
;   SGB_(0x008, 1);
; template <int WM, int WN, typename SrcF, typename PostF>
; __device__ __forceinline__ void gemm_stream(const int nsteps, SrcF src, PostF post, f32x4 (&acc)[WM][WN], char* smem) {
;     ...
;     step_compute<WM, WN>(smem + STAGE, smem, acc, aoff, boff, wao, wbo, xa0, xa1, xa2, xa3, xb0, xb1, xb2, xb3, pa, pb0, pb1, pb2, pb3);
;     SB_;
;     post(kt + 1);
;     __syncthreads();
;   }
	v_mfma_f32_16x16x32_bf16 v[44:47], v[100:103], v[128:131], v[44:47]
	ds_read_b128 v[152:155], v125 offset:25792
	v_mfma_f32_16x16x32_bf16 v[40:43], v[100:103], v[132:135], v[40:43]
	ds_read_b128 v[156:159], v125 offset:26816
	v_mfma_f32_16x16x32_bf16 v[36:39], v[100:103], v[136:139], v[36:39]
	ds_read_b128 v[160:163], v125 offset:27840
	v_mfma_f32_16x16x32_bf16 v[28:31], v[100:103], v[140:143], v[28:31]
	s_waitcnt lgkmcnt(8)
	v_mfma_f32_16x16x32_bf16 v[64:67], v[104:107], v[128:131], v[64:67]
	s_waitcnt vmcnt(7)
	ds_write_b128 v126, v[32:35] offset:33024
	v_mfma_f32_16x16x32_bf16 v[88:91], v[104:107], v[132:135], v[88:91]
	v_mfma_f32_16x16x32_bf16 v[80:83], v[104:107], v[136:139], v[80:83]
	s_waitcnt vmcnt(6)
	ds_write_b128 v126, v[20:23] offset:35072
	v_mfma_f32_16x16x32_bf16 v[48:51], v[104:107], v[140:143], v[48:51]
	s_waitcnt lgkmcnt(5)
	v_mfma_f32_16x16x32_bf16 v[56:59], v[108:111], v[92:95], v[56:59]
	s_waitcnt vmcnt(5)
	ds_write_b128 v126, v[16:19] offset:37120
	s_add_u32 s34, s10, s5
	s_addc_u32 s35, s11, 0
	s_waitcnt lgkmcnt(5)
	v_mfma_f32_16x16x32_bf16 v[96:99], v[108:111], v[152:155], v[96:99]
	s_min_u32 s5, s27, 12
	s_lshl_b32 s5, s5, 7
	s_waitcnt lgkmcnt(4)
	v_mfma_f32_16x16x32_bf16 v[84:87], v[108:111], v[156:159], v[84:87]
	s_waitcnt vmcnt(4)
	ds_write_b128 v126, v[24:27] offset:39168
	s_waitcnt lgkmcnt(4)
	v_mfma_f32_16x16x32_bf16 v[76:79], v[108:111], v[160:163], v[76:79]
	v_mfma_f32_16x16x32_bf16 v[72:75], v[112:115], v[92:95], v[72:75]
	s_waitcnt vmcnt(3)
	ds_write_b128 v126, v[12:15] offset:49536
	v_mfma_f32_16x16x32_bf16 v[68:71], v[112:115], v[152:155], v[68:71]
	v_mfma_f32_16x16x32_bf16 v[60:63], v[112:115], v[156:159], v[60:63]
	s_waitcnt vmcnt(2)
	ds_write_b128 v126, v[8:11] offset:51584
	v_mfma_f32_16x16x32_bf16 v[52:55], v[112:115], v[160:163], v[52:55]
	v_mfma_f32_16x16x32_bf16 v[44:47], v[144:147], v[92:95], v[44:47]
	s_waitcnt vmcnt(1)
	ds_write_b128 v126, v[4:7] offset:53632
	v_mfma_f32_16x16x32_bf16 v[40:43], v[144:147], v[152:155], v[40:43]
	s_add_u32 s34, s8, s5
	s_addc_u32 s35, s9, 0
	s_add_u32 s36, s10, s5
	v_mfma_f32_16x16x32_bf16 v[36:39], v[144:147], v[156:159], v[36:39]
	s_waitcnt vmcnt(0)
	ds_write_b128 v126, v[0:3] offset:55680
	s_addc_u32 s37, s11, 0
	v_mfma_f32_16x16x32_bf16 v[28:31], v[144:147], v[160:163], v[28:31]
	v_mfma_f32_16x16x32_bf16 v[92:95], v[148:151], v[92:95], v[64:67]
	v_mfma_f32_16x16x32_bf16 v[88:91], v[148:151], v[152:155], v[88:91]
	v_mfma_f32_16x16x32_bf16 v[80:83], v[148:151], v[156:159], v[80:83]
	v_mfma_f32_16x16x32_bf16 v[100:103], v[148:151], v[160:163], v[48:51]
	s_waitcnt lgkmcnt(0)
	s_barrier
	s_nop 0
	ds_read_b128 v[48:51], v124 offset:33024
	ds_read_b128 v[108:111], v125 offset:49536
	ds_read_b128 v[128:131], v125 offset:50560
	ds_read_b128 v[132:135], v125 offset:51584
	ds_read_b128 v[136:139], v125 offset:52608
	s_waitcnt lgkmcnt(3)
	v_mfma_f32_16x16x32_bf16 v[140:143], v[48:51], v[108:111], v[56:59]
	s_waitcnt lgkmcnt(2)
	v_mfma_f32_16x16x32_bf16 v[96:99], v[48:51], v[128:131], v[96:99]
	s_waitcnt lgkmcnt(1)
	v_mfma_f32_16x16x32_bf16 v[84:87], v[48:51], v[132:135], v[84:87]
	s_waitcnt lgkmcnt(0)
	v_mfma_f32_16x16x32_bf16 v[76:79], v[48:51], v[136:139], v[76:79]
	ds_read_b128 v[48:51], v124 offset:34048
	s_waitcnt lgkmcnt(0)
	v_mfma_f32_16x16x32_bf16 v[72:75], v[48:51], v[108:111], v[72:75]
	ds_read_b128 v[56:59], v124 offset:35072
	v_mfma_f32_16x16x32_bf16 v[68:71], v[48:51], v[128:131], v[68:71]
	ds_read_b128 v[144:147], v124 offset:36096
	v_mfma_f32_16x16x32_bf16 v[60:63], v[48:51], v[132:135], v[60:63]
	ds_read_b128 v[148:151], v124 offset:41280
	v_mfma_f32_16x16x32_bf16 v[52:55], v[48:51], v[136:139], v[52:55]
	ds_read_b128 v[152:155], v124 offset:42304
	s_waitcnt lgkmcnt(3)
	v_mfma_f32_16x16x32_bf16 v[44:47], v[56:59], v[108:111], v[44:47]
	ds_read_b128 v[156:159], v124 offset:43328
	v_mfma_f32_16x16x32_bf16 v[40:43], v[56:59], v[128:131], v[40:43]
	ds_read_b128 v[48:51], v124 offset:44352
	v_mfma_f32_16x16x32_bf16 v[36:39], v[56:59], v[132:135], v[36:39]
	ds_read_b128 v[64:67], v125 offset:57792
	v_mfma_f32_16x16x32_bf16 v[28:31], v[56:59], v[136:139], v[28:31]
	ds_read_b128 v[104:107], v125 offset:58816
	s_waitcnt lgkmcnt(6)
	v_mfma_f32_16x16x32_bf16 v[92:95], v[144:147], v[108:111], v[92:95]
	ds_read_b128 v[112:115], v125 offset:59840
	v_mfma_f32_16x16x32_bf16 v[88:91], v[144:147], v[128:131], v[88:91]
	ds_read_b128 v[108:111], v125 offset:60864
	v_mfma_f32_16x16x32_bf16 v[80:83], v[144:147], v[132:135], v[80:83]
	v_mfma_f32_16x16x32_bf16 v[56:59], v[144:147], v[136:139], v[100:103]
	s_waitcnt lgkmcnt(3)
	v_mfma_f32_16x16x32_bf16 v[100:103], v[148:151], v[64:67], v[140:143]
	s_waitcnt lgkmcnt(2)
	v_mfma_f32_16x16x32_bf16 v[96:99], v[148:151], v[104:107], v[96:99]
	s_waitcnt lgkmcnt(1)
	v_mfma_f32_16x16x32_bf16 v[84:87], v[148:151], v[112:115], v[84:87]
	s_waitcnt lgkmcnt(0)
	v_mfma_f32_16x16x32_bf16 v[76:79], v[148:151], v[108:111], v[76:79]
	v_mfma_f32_16x16x32_bf16 v[72:75], v[152:155], v[64:67], v[72:75]
	v_mfma_f32_16x16x32_bf16 v[68:71], v[152:155], v[104:107], v[68:71]
	v_mfma_f32_16x16x32_bf16 v[60:63], v[152:155], v[112:115], v[60:63]
	v_mfma_f32_16x16x32_bf16 v[52:55], v[152:155], v[108:111], v[52:55]
	v_mfma_f32_16x16x32_bf16 v[44:47], v[156:159], v[64:67], v[44:47]
	v_mfma_f32_16x16x32_bf16 v[40:43], v[156:159], v[104:107], v[40:43]
	v_mfma_f32_16x16x32_bf16 v[36:39], v[156:159], v[112:115], v[36:39]
	v_mfma_f32_16x16x32_bf16 v[28:31], v[156:159], v[108:111], v[28:31]
	s_cmp_lt_u32 s27, 14
	s_mov_b32 s5, s27
	s_waitcnt lgkmcnt(0)
	s_barrier
; #define MFMA16(a, b, c) __builtin_amdgcn_mfma_f32_16x16x32_bf16(a, b, c, 0, 0, 0)
; template <int WM, int WN, typename SrcF, typename PostF>
; __device__ __forceinline__ void gemm_stream(const int nsteps, SrcF src, PostF post, f32x4 (&acc)[WM][WN], char* smem) {
;     ...
;   acc[3][0] = MFMA16(pa, pb0, acc[3][0]);
;   acc[3][1] = MFMA16(pa, pb1, acc[3][1]);
;   acc[3][2] = MFMA16(pa, pb2, acc[3][2]);
;   acc[3][3] = MFMA16(pa, pb3, acc[3][3]);
; template <int WM, int WN>
; __device__ __forceinline__ void store_tile_bf16(const f32x4 (&acc)[WM][WN], u16* dst, int ld, char* smem) {
;   constexpr int BM = 32 * WM, BN = 32 * WN, STR = BN + 8;
;   const int tid = opaque_tid(), lane = tid & 63, wid = tid >> 6;
;   const int wr = wid >> 1, wc = wid & 1, fr = lane & 15, fq = lane >> 4;
;   u16* T = reinterpret_cast<u16*>(smem);
; #pragma unroll
;   for (int m = 0; m < WM; ++m)
; #pragma unroll
;     for (int n = 0; n < WN; ++n)
; #pragma unroll
;       for (int j = 0; j < 4; ++j)
;         T[(wr * 16 * WM + m * 16 + fq * 4 + j) * STR + wc * 16 * WN + n * 16 + fr] = f2bf(acc[m][n][j]);
;   __syncthreads();
	s_waitcnt vmcnt(5)
	v_mov_b32_e32 v16, v232
	s_waitcnt vmcnt(0)
	v_mfma_f32_16x16x32_bf16 v[0:3], v[48:51], v[64:67], v[92:95]
	v_lshrrev_b32_e32 v18, 2, v16
	v_lshrrev_b32_e32 v17, 1, v16
	v_and_b32_e32 v18, 12, v18
	v_and_or_b32 v17, v17, s24, v18
	v_and_b32_e32 v18, 0x4f, v16
	v_mul_lo_u32 v17, v17, s26
	v_lshl_add_u32 v17, v18, 1, v17
	v_cvt_pk_bf16_f32 v18, v101, v102
	ds_write_b16 v17, v18 offset:272
	ds_write_b16_d16_hi v17, v18 offset:544
	v_cvt_pk_bf16_f32 v18, v103, v96
	ds_write_b16 v17, v18 offset:816
	ds_write_b16_d16_hi v17, v18 offset:32
	v_cvt_pk_bf16_f32 v18, v97, v98
	ds_write_b16 v17, v18 offset:304
	ds_write_b16_d16_hi v17, v18 offset:576
	v_cvt_pk_bf16_f32 v18, v99, v84
	ds_write_b16 v17, v18 offset:848
	ds_write_b16_d16_hi v17, v18 offset:64
	v_cvt_pk_bf16_f32 v18, v85, v86
	ds_write_b16 v17, v18 offset:336
	ds_write_b16_d16_hi v17, v18 offset:608
	v_cvt_pk_bf16_f32 v18, v87, v76
	ds_write_b16 v17, v18 offset:880
	ds_write_b16_d16_hi v17, v18 offset:96
	v_cvt_pk_bf16_f32 v18, v77, v78
	ds_write_b16 v17, v18 offset:368
	ds_write_b16_d16_hi v17, v18 offset:640
	v_cvt_pk_bf16_f32 v18, v79, v72
	ds_write_b16 v17, v18 offset:912
	ds_write_b16_d16_hi v17, v18 offset:4352
	v_cvt_pk_bf16_f32 v18, v73, v74
	ds_write_b16 v17, v18 offset:4624
	ds_write_b16_d16_hi v17, v18 offset:4896
	v_cvt_pk_bf16_f32 v18, v75, v68
	ds_write_b16 v17, v18 offset:5168
	ds_write_b16_d16_hi v17, v18 offset:4384
	v_cvt_pk_bf16_f32 v18, v69, v70
	ds_write_b16 v17, v18 offset:4656
	ds_write_b16_d16_hi v17, v18 offset:4928
	v_cvt_pk_bf16_f32 v18, v71, v60
	ds_write_b16 v17, v18 offset:5200
	ds_write_b16_d16_hi v17, v18 offset:4416
	v_cvt_pk_bf16_f32 v18, v61, v62
	ds_write_b16 v17, v18 offset:4688
	ds_write_b16_d16_hi v17, v18 offset:4960
	v_cvt_pk_bf16_f32 v18, v63, v52
	ds_write_b16 v17, v18 offset:5232
	ds_write_b16_d16_hi v17, v18 offset:4448
	v_cvt_pk_bf16_f32 v18, v53, v54
	ds_write_b16 v17, v18 offset:4720
	ds_write_b16_d16_hi v17, v18 offset:4992
	v_cvt_pk_bf16_f32 v18, v55, v44
	ds_write_b16 v17, v18 offset:5264
	ds_write_b16_d16_hi v17, v18 offset:8704
	v_cvt_pk_bf16_f32 v18, v45, v46
	ds_write_b16 v17, v18 offset:8976
	ds_write_b16_d16_hi v17, v18 offset:9248
	v_cvt_pk_bf16_f32 v18, v47, v40
	ds_write_b16 v17, v18 offset:9520
	ds_write_b16_d16_hi v17, v18 offset:8736
	v_cvt_pk_bf16_f32 v18, v41, v42
	ds_write_b16 v17, v18 offset:9008
	ds_write_b16_d16_hi v17, v18 offset:9280
	v_cvt_pk_bf16_f32 v18, v43, v36
	ds_write_b16 v17, v18 offset:9552
	ds_write_b16_d16_hi v17, v18 offset:8768
	v_cvt_pk_bf16_f32 v18, v37, v38
	ds_write_b16 v17, v18 offset:9040
	ds_write_b16_d16_hi v17, v18 offset:9312
	v_cvt_pk_bf16_f32 v18, v39, v28
	ds_write_b16 v17, v18 offset:9584
	ds_write_b16_d16_hi v17, v18 offset:8800
	v_cvt_pk_bf16_f32 v18, v29, v30
	ds_write_b16 v17, v18 offset:9072
	ds_write_b16_d16_hi v17, v18 offset:9344
	v_cvt_pk_bf16_f32 v18, 0, v31
	ds_write_b16_d16_hi v17, v18 offset:9616
	v_cvt_pk_bf16_f32 v0, 0, v0
	ds_write_b16_d16_hi v17, v0 offset:13056
	v_cvt_pk_bf16_f32 v0, 0, v1
	v_mfma_f32_16x16x32_bf16 v[4:7], v[48:51], v[104:107], v[88:91]
	ds_write_b16_d16_hi v17, v0 offset:13328
	v_cvt_pk_bf16_f32 v0, v2, v3
	ds_write_b16 v17, v0 offset:13600
	ds_write_b16_d16_hi v17, v0 offset:13872
	s_nop 0
	s_nop 1
	s_nop 0
	v_cvt_pk_bf16_f32 v0, 0, v4
	ds_write_b16_d16_hi v17, v0 offset:13088
	v_cvt_pk_bf16_f32 v0, 0, v5
	v_mfma_f32_16x16x32_bf16 v[8:11], v[48:51], v[112:115], v[80:83]
	ds_write_b16_d16_hi v17, v0 offset:13360
	v_cvt_pk_bf16_f32 v0, v6, v7
	ds_write_b16 v17, v0 offset:13632
	ds_write_b16_d16_hi v17, v0 offset:13904
	s_nop 0
	s_nop 1
	s_nop 0
	v_cvt_pk_bf16_f32 v0, 0, v8
	ds_write_b16_d16_hi v17, v0 offset:13120
	v_cvt_pk_bf16_f32 v0, 0, v9
	v_mfma_f32_16x16x32_bf16 v[12:15], v[48:51], v[108:111], v[56:59]
	ds_write_b16_d16_hi v17, v0 offset:13392
	v_cvt_pk_bf16_f32 v0, v10, v11
	ds_write_b16 v17, v0 offset:13664
	ds_write_b16_d16_hi v17, v0 offset:13936
	s_nop 0
	s_nop 1
	s_nop 0
	v_cvt_pk_bf16_f32 v0, v12, v13
	ds_write_b16 v17, v0 offset:13152
	ds_write_b16_d16_hi v17, v0 offset:13424
	v_cvt_pk_bf16_f32 v0, 0, v14
	ds_write_b16_d16_hi v17, v0 offset:13696
	s_lshl_b64 s[6:7], s[6:7], 1
	v_cvt_pk_bf16_f32 v0, 0, v15
	s_add_u32 s6, s16, s6
	ds_write_b16_d16_hi v17, v0 offset:13968
	v_ashrrev_i32_e32 v0, 31, v16
	s_addc_u32 s7, s17, s7
	s_lshl_b32 s4, s4, 7
	v_lshrrev_b32_e32 v0, 28, v0
	s_ashr_i32 s5, s4, 31
	v_add_u32_e32 v0, v16, v0
	s_lshl_b64 s[4:5], s[4:5], 1
	v_ashrrev_i32_e32 v4, 4, v0
	v_and_b32_e32 v0, -16, v0
	s_add_u32 s4, s6, s4
	v_sub_u32_e32 v0, v16, v0
	v_ashrrev_i32_e32 v5, 31, v4
	s_addc_u32 s5, s7, s5
	v_mul_lo_u32 v1, v4, s26
	v_lshlrev_b32_e32 v6, 3, v0
	v_lshlrev_b64 v[4:5], 11, v[4:5]
	v_ashrrev_i32_e32 v7, 31, v6
	v_lshl_add_u64 v[4:5], s[4:5], 0, v[4:5]
	v_lshl_add_u64 v[8:9], v[6:7], 1, v[4:5]
	v_add_u32_e32 v4, 0x100, v16
	v_ashrrev_i32_e32 v5, 31, v4
	v_cvt_pk_bf16_f32 v19, 0, v100
	v_lshl_add_u32 v0, v0, 4, v1
	v_lshrrev_b32_e32 v5, 28, v5
	ds_write_b16_d16_hi v17, v19
	s_waitcnt lgkmcnt(0)
	s_barrier
; template <int WM, int WN>
; __device__ __forceinline__ void store_tile_bf16(const f32x4 (&acc)[WM][WN], u16* dst, int ld, char* smem) {
;     ...
;   constexpr int CPR = BN / 8;
; #pragma unroll
;   for (int i = 0; i < BM * CPR / 256; ++i) {
;     int q = tid + 256 * i, row = q / CPR, c = q % CPR;
;     uint4 v = *reinterpret_cast<const uint4*>(T + row * STR + c * 8);
;     *reinterpret_cast<uint4*>(dst + (size_t)row * ld + c * 8) = v;
;   }
; __device__ void phase_out(const Params& p, int layer, char* smem) {
;     ...
;   for (int t = li_; t < rbp_ * 8; t += nl_) {
;     const int rg_ = t / (8 * 8), v_ = t % (8 * 8);
;     const int rb = xg_ * rbp_ + rg_ * 8 + (v_ & 7), cb = v_ >> 3;
;     f32x4 acc[4][4];
; #pragma unroll
;     for (int m = 0; m < 4; ++m)
; #pragma unroll
;       for (int n = 0; n < 4; ++n) acc[m][n] = f32x4{0.f, 0.f, 0.f, 0.f};
;     {
;       const u16* Ab = MG + (size_t)rb * 128 * 1024;
;       const u16* Bb = Wo + (size_t)cb * 128 * 1024;
;       gemm_stream<4, 4>(16, [&](int s) { return TileSrc{Ab + s * 64, Bb + s * 64, 1024, 1024}; }, [&](int) {}, acc, smem);
;     }
;     store_tile_bf16<4, 4>(acc, OUTB + (size_t)rb * 128 * DM + cb * 128, DM, smem);
;   }
	ds_read_b128 v[0:3], v0
	v_add_u32_e32 v5, v4, v5
	v_ashrrev_i32_e32 v10, 4, v5
	v_and_b32_e32 v5, -16, v5
	v_sub_u32_e32 v11, v4, v5
	v_mul_lo_u32 v4, v10, s26
	v_lshl_add_u32 v4, v11, 4, v4
	ds_read_b128 v[4:7], v4
	s_waitcnt lgkmcnt(1)
	global_store_dwordx4 v[8:9], v[0:3], off
	s_add_i32 s60, s60, s61
	s_cmp_lt_i32 s60, s62
	v_lshlrev_b32_e32 v0, 3, v11
	v_ashrrev_i32_e32 v11, 31, v10
	v_lshlrev_b64 v[2:3], 11, v[10:11]
	v_ashrrev_i32_e32 v1, 31, v0
	v_lshl_add_u64 v[2:3], s[4:5], 0, v[2:3]
	v_lshl_add_u64 v[0:1], v[0:1], 1, v[2:3]
	s_waitcnt lgkmcnt(0)
	global_store_dwordx4 v[0:1], v[4:7], off
	v_add_u32_e32 v0, 0x200, v16
	v_ashrrev_i32_e32 v1, 31, v0
	v_lshrrev_b32_e32 v1, 28, v1
	v_add_u32_e32 v1, v0, v1
	v_ashrrev_i32_e32 v4, 4, v1
	v_and_b32_e32 v1, -16, v1
	v_sub_u32_e32 v0, v0, v1
	v_ashrrev_i32_e32 v5, 31, v4
	v_mul_lo_u32 v1, v4, s26
	v_lshlrev_b32_e32 v6, 3, v0
	v_lshlrev_b64 v[4:5], 11, v[4:5]
	v_ashrrev_i32_e32 v7, 31, v6
	v_lshl_add_u64 v[4:5], s[4:5], 0, v[4:5]
	v_lshl_add_u64 v[8:9], v[6:7], 1, v[4:5]
	v_add_u32_e32 v4, 0x300, v16
	v_ashrrev_i32_e32 v5, 31, v4
	v_lshl_add_u32 v0, v0, 4, v1
	v_lshrrev_b32_e32 v5, 28, v5
	ds_read_b128 v[0:3], v0
	v_add_u32_e32 v5, v4, v5
	v_ashrrev_i32_e32 v10, 4, v5
	v_and_b32_e32 v5, -16, v5
	v_sub_u32_e32 v11, v4, v5
	v_mul_lo_u32 v4, v10, s26
	v_lshl_add_u32 v4, v11, 4, v4
	ds_read_b128 v[4:7], v4
	s_waitcnt lgkmcnt(1)
	global_store_dwordx4 v[8:9], v[0:3], off
	s_nop 1
	v_lshlrev_b32_e32 v0, 3, v11
	v_ashrrev_i32_e32 v11, 31, v10
	v_lshlrev_b64 v[2:3], 11, v[10:11]
	v_ashrrev_i32_e32 v1, 31, v0
	v_lshl_add_u64 v[2:3], s[4:5], 0, v[2:3]
	v_lshl_add_u64 v[0:1], v[0:1], 1, v[2:3]
	s_waitcnt lgkmcnt(0)
	global_store_dwordx4 v[0:1], v[4:7], off
	v_add_u32_e32 v0, 0x400, v16
	v_ashrrev_i32_e32 v1, 31, v0
	v_lshrrev_b32_e32 v1, 28, v1
	v_add_u32_e32 v1, v0, v1
	v_ashrrev_i32_e32 v4, 4, v1
	v_and_b32_e32 v1, -16, v1
	v_sub_u32_e32 v0, v0, v1
	v_ashrrev_i32_e32 v5, 31, v4
	v_mul_lo_u32 v1, v4, s26
	v_lshlrev_b32_e32 v6, 3, v0
	v_lshlrev_b64 v[4:5], 11, v[4:5]
	v_ashrrev_i32_e32 v7, 31, v6
	v_lshl_add_u64 v[4:5], s[4:5], 0, v[4:5]
	v_lshl_add_u64 v[8:9], v[6:7], 1, v[4:5]
	v_add_u32_e32 v4, 0x500, v16
	v_ashrrev_i32_e32 v5, 31, v4
	v_lshl_add_u32 v0, v0, 4, v1
	v_lshrrev_b32_e32 v5, 28, v5
	ds_read_b128 v[0:3], v0
	v_add_u32_e32 v5, v4, v5
	v_ashrrev_i32_e32 v10, 4, v5
	v_and_b32_e32 v5, -16, v5
	v_sub_u32_e32 v11, v4, v5
	v_mul_lo_u32 v4, v10, s26
	v_lshl_add_u32 v4, v11, 4, v4
	ds_read_b128 v[4:7], v4
	s_waitcnt lgkmcnt(1)
	global_store_dwordx4 v[8:9], v[0:3], off
	s_nop 1
	v_lshlrev_b32_e32 v0, 3, v11
	v_ashrrev_i32_e32 v11, 31, v10
	v_lshlrev_b64 v[2:3], 11, v[10:11]
	v_ashrrev_i32_e32 v1, 31, v0
	v_lshl_add_u64 v[2:3], s[4:5], 0, v[2:3]
	v_lshl_add_u64 v[0:1], v[0:1], 1, v[2:3]
	s_waitcnt lgkmcnt(0)
	global_store_dwordx4 v[0:1], v[4:7], off
	v_add_u32_e32 v0, 0x600, v16
	v_ashrrev_i32_e32 v1, 31, v0
	v_lshrrev_b32_e32 v1, 28, v1
	v_add_u32_e32 v1, v0, v1
	v_ashrrev_i32_e32 v4, 4, v1
	v_and_b32_e32 v1, -16, v1
	v_sub_u32_e32 v0, v0, v1
	v_ashrrev_i32_e32 v5, 31, v4
	v_mul_lo_u32 v1, v4, s26
	v_lshlrev_b32_e32 v6, 3, v0
	v_lshlrev_b64 v[4:5], 11, v[4:5]
	v_ashrrev_i32_e32 v7, 31, v6
	v_lshl_add_u64 v[4:5], s[4:5], 0, v[4:5]
	v_lshl_add_u64 v[8:9], v[6:7], 1, v[4:5]
	v_add_u32_e32 v4, 0x700, v16
	v_ashrrev_i32_e32 v5, 31, v4
	v_lshl_add_u32 v0, v0, 4, v1
	v_lshrrev_b32_e32 v5, 28, v5
	ds_read_b128 v[0:3], v0
	v_add_u32_e32 v5, v4, v5
	v_ashrrev_i32_e32 v10, 4, v5
	v_and_b32_e32 v5, -16, v5
	v_sub_u32_e32 v11, v4, v5
	v_mul_lo_u32 v4, v10, s26
	v_lshl_add_u32 v4, v11, 4, v4
	ds_read_b128 v[4:7], v4
	s_waitcnt lgkmcnt(1)
	global_store_dwordx4 v[8:9], v[0:3], off
	s_nop 1
	v_lshlrev_b32_e32 v0, 3, v11
	v_ashrrev_i32_e32 v11, 31, v10
	v_lshlrev_b64 v[2:3], 11, v[10:11]
	v_ashrrev_i32_e32 v1, 31, v0
	v_lshl_add_u64 v[2:3], s[4:5], 0, v[2:3]
	v_lshl_add_u64 v[0:1], v[0:1], 1, v[2:3]
	s_waitcnt lgkmcnt(0)
	global_store_dwordx4 v[0:1], v[4:7], off
	s_cbranch_scc1 .LBB0_1280
